# GEMM K-loops: 48 LDS-DMA stages use the SGPR-base + 32-bit VGPR-offset form instead of a v_lshl_add_u64 per load
# speedup vs baseline: 1.0054x; 1.0054x over previous
.LBB0_305:
	s_add_u32 s30, s4, 0xfffc0080
	s_addc_u32 s31, s5, -1
	s_add_i32 s52, 0, 0x10000
	v_add_u32_e32 v48, s52, v141
	ds_read_b128 v[150:153], v48
	ds_read_b128 v[156:159], v48 offset:1024
	ds_read_b128 v[160:163], v48 offset:2048
	ds_read_b128 v[164:167], v48 offset:3072
	s_cmp_eq_u32 s51, 12
	s_cselect_b32 s35, s27, s31
	s_cselect_b32 s34, s26, s30
	s_cselect_b32 s31, s29, s25
	s_cselect_b32 s30, s28, s23
	s_add_i32 m0, s42, 0xc000
	ds_read_b128 v[168:171], v155
	ds_read_b128 v[172:175], v155 offset:1024
	ds_read_b128 v[176:179], v155 offset:2048
	ds_read_b128 v[180:183], v155 offset:3072
	ds_read_b128 v[184:187], v155 offset:4096
	ds_read_b128 v[188:191], v155 offset:5120
	ds_read_b128 v[198:201], v155 offset:6144
	ds_read_b128 v[202:205], v155 offset:7168
	global_load_lds_dwordx4 v146, s[4:5]
	s_add_i32 m0, s42, 0xe000
	s_nop 0
	global_load_lds_dwordx4 v148, s[4:5]
	s_waitcnt lgkmcnt(8)
	s_barrier
	s_waitcnt lgkmcnt(0)
	s_setprio 1
	s_waitcnt lgkmcnt(0)
	v_mfma_f32_16x16x32_bf16 v[126:129], v[150:153], v[168:171], v[126:129]
	v_mfma_f32_16x16x32_bf16 v[122:125], v[160:163], v[168:171], v[122:125]
	v_mfma_f32_16x16x32_bf16 v[110:113], v[150:153], v[176:179], v[110:113]
	v_mfma_f32_16x16x32_bf16 v[106:109], v[160:163], v[176:179], v[106:109]
	v_mfma_f32_16x16x32_bf16 v[94:97], v[150:153], v[184:187], v[94:97]
	v_mfma_f32_16x16x32_bf16 v[90:93], v[160:163], v[184:187], v[90:93]
	v_mfma_f32_16x16x32_bf16 v[78:81], v[150:153], v[198:201], v[78:81]
	v_mfma_f32_16x16x32_bf16 v[74:77], v[160:163], v[198:201], v[74:77]
	v_mfma_f32_16x16x32_bf16 v[126:129], v[156:159], v[172:175], v[126:129]
	v_mfma_f32_16x16x32_bf16 v[122:125], v[164:167], v[172:175], v[122:125]
	v_mfma_f32_16x16x32_bf16 v[110:113], v[156:159], v[180:183], v[110:113]
	v_mfma_f32_16x16x32_bf16 v[106:109], v[164:167], v[180:183], v[106:109]
	v_mfma_f32_16x16x32_bf16 v[94:97], v[156:159], v[188:191], v[94:97]
	v_mfma_f32_16x16x32_bf16 v[90:93], v[164:167], v[188:191], v[90:93]
	v_mfma_f32_16x16x32_bf16 v[78:81], v[156:159], v[202:205], v[78:81]
	v_mfma_f32_16x16x32_bf16 v[74:77], v[164:167], v[202:205], v[74:77]
	s_setprio 0
	s_barrier
	s_add_i32 s54, 0, 0x14000
	s_add_i32 s52, s52, s41
	v_add_u32_e32 v48, s54, v141
	v_lshl_add_u64 v[192:193], s[30:31], 0, v[132:133]
	s_mov_b32 m0, s52
	ds_read_b128 v[206:209], v48
	ds_read_b128 v[210:213], v48 offset:1024
	ds_read_b128 v[214:217], v48 offset:2048
	ds_read_b128 v[218:221], v48 offset:3072
	global_load_lds_dwordx4 v[192:193], off
	v_lshl_add_u64 v[222:223], s[30:31], 0, v[136:137]
	s_add_i32 m0, s52, 0x2000
	s_nop 0
	global_load_lds_dwordx4 v[222:223], off
	s_barrier
	s_waitcnt lgkmcnt(0)
	s_setprio 1
	s_waitcnt lgkmcnt(0)
	v_mfma_f32_16x16x32_bf16 v[118:121], v[206:209], v[168:171], v[118:121]
	v_mfma_f32_16x16x32_bf16 v[114:117], v[214:217], v[168:171], v[114:117]
	v_mfma_f32_16x16x32_bf16 v[102:105], v[206:209], v[176:179], v[102:105]
	v_mfma_f32_16x16x32_bf16 v[98:101], v[214:217], v[176:179], v[98:101]
	v_mfma_f32_16x16x32_bf16 v[86:89], v[206:209], v[184:187], v[86:89]
	v_mfma_f32_16x16x32_bf16 v[82:85], v[214:217], v[184:187], v[82:85]
	v_mfma_f32_16x16x32_bf16 v[70:73], v[206:209], v[198:201], v[70:73]
	v_mfma_f32_16x16x32_bf16 v[66:69], v[214:217], v[198:201], v[66:69]
	v_mfma_f32_16x16x32_bf16 v[118:121], v[210:213], v[172:175], v[118:121]
	v_mfma_f32_16x16x32_bf16 v[114:117], v[218:221], v[172:175], v[114:117]
	v_mfma_f32_16x16x32_bf16 v[102:105], v[210:213], v[180:183], v[102:105]
	v_mfma_f32_16x16x32_bf16 v[98:101], v[218:221], v[180:183], v[98:101]
	v_mfma_f32_16x16x32_bf16 v[86:89], v[210:213], v[188:191], v[86:89]
	v_mfma_f32_16x16x32_bf16 v[82:85], v[218:221], v[188:191], v[82:85]
	v_mfma_f32_16x16x32_bf16 v[70:73], v[210:213], v[202:205], v[70:73]
	v_mfma_f32_16x16x32_bf16 v[66:69], v[218:221], v[202:205], v[66:69]
	s_setprio 0
	s_mov_b32 m0, s42
	v_lshl_add_u64 v[242:243], s[34:35], 0, v[130:131]
	s_barrier
	ds_read_b128 v[168:171], v155 offset:16384
	ds_read_b128 v[172:175], v155 offset:17408
	ds_read_b128 v[176:179], v155 offset:18432
	ds_read_b128 v[180:183], v155 offset:19456
	ds_read_b128 v[184:187], v155 offset:20480
	ds_read_b128 v[188:191], v155 offset:21504
	ds_read_b128 v[198:201], v155 offset:22528
	ds_read_b128 v[202:205], v155 offset:23552
	global_load_lds_dwordx4 v[242:243], off
	v_lshl_add_u64 v[244:245], s[34:35], 0, v[134:135]
	s_mov_b32 m0, s43
	s_nop 0
	global_load_lds_dwordx4 v[244:245], off
	s_barrier
	s_waitcnt lgkmcnt(0)
	s_setprio 1
	s_waitcnt lgkmcnt(0)
	v_mfma_f32_16x16x32_bf16 v[62:65], v[150:153], v[168:171], v[62:65]
	v_mfma_f32_16x16x32_bf16 v[58:61], v[160:163], v[168:171], v[58:61]
	v_mfma_f32_16x16x32_bf16 v[44:47], v[150:153], v[176:179], v[44:47]
	v_mfma_f32_16x16x32_bf16 v[40:43], v[160:163], v[176:179], v[40:43]
	v_mfma_f32_16x16x32_bf16 v[28:31], v[150:153], v[184:187], v[28:31]
	v_mfma_f32_16x16x32_bf16 v[24:27], v[160:163], v[184:187], v[24:27]
	v_mfma_f32_16x16x32_bf16 v[12:15], v[150:153], v[198:201], v[12:15]
	v_mfma_f32_16x16x32_bf16 v[8:11], v[160:163], v[198:201], v[8:11]
	v_mfma_f32_16x16x32_bf16 v[62:65], v[156:159], v[172:175], v[62:65]
	v_mfma_f32_16x16x32_bf16 v[58:61], v[164:167], v[172:175], v[58:61]
	v_mfma_f32_16x16x32_bf16 v[44:47], v[156:159], v[180:183], v[44:47]
	v_mfma_f32_16x16x32_bf16 v[40:43], v[164:167], v[180:183], v[40:43]
	v_mfma_f32_16x16x32_bf16 v[28:31], v[156:159], v[188:191], v[28:31]
	v_mfma_f32_16x16x32_bf16 v[24:27], v[164:167], v[188:191], v[24:27]
	v_mfma_f32_16x16x32_bf16 v[12:15], v[156:159], v[202:205], v[12:15]
	v_mfma_f32_16x16x32_bf16 v[8:11], v[164:167], v[202:205], v[8:11]
	s_setprio 0
	s_barrier
	s_add_u32 s52, s30, 0x40000
	s_addc_u32 s53, s31, 0
	s_add_i32 s54, s54, s41
	s_mov_b32 m0, s54
	s_nop 0
	global_load_lds_dwordx4 v132, s[52:53]
	s_add_i32 m0, s54, 0x2000
	s_nop 0
	global_load_lds_dwordx4 v136, s[52:53]
	s_waitcnt vmcnt(6)
	s_barrier
	s_setprio 1
	v_mfma_f32_16x16x32_bf16 v[54:57], v[206:209], v[168:171], v[54:57]
	v_mfma_f32_16x16x32_bf16 v[50:53], v[214:217], v[168:171], v[50:53]
	v_mfma_f32_16x16x32_bf16 v[36:39], v[206:209], v[176:179], v[36:39]
	v_mfma_f32_16x16x32_bf16 v[32:35], v[214:217], v[176:179], v[32:35]
	v_mfma_f32_16x16x32_bf16 v[20:23], v[206:209], v[184:187], v[20:23]
	v_mfma_f32_16x16x32_bf16 v[16:19], v[214:217], v[184:187], v[16:19]
	v_mfma_f32_16x16x32_bf16 v[4:7], v[206:209], v[198:201], v[4:7]
	v_mfma_f32_16x16x32_bf16 v[0:3], v[214:217], v[198:201], v[0:3]
	v_mfma_f32_16x16x32_bf16 v[54:57], v[210:213], v[172:175], v[54:57]
	v_mfma_f32_16x16x32_bf16 v[50:53], v[218:221], v[172:175], v[50:53]
	v_mfma_f32_16x16x32_bf16 v[36:39], v[210:213], v[180:183], v[36:39]
	v_mfma_f32_16x16x32_bf16 v[32:35], v[218:221], v[180:183], v[32:35]
	v_mfma_f32_16x16x32_bf16 v[20:23], v[210:213], v[188:191], v[20:23]
	v_mfma_f32_16x16x32_bf16 v[16:19], v[218:221], v[188:191], v[16:19]
	v_mfma_f32_16x16x32_bf16 v[4:7], v[210:213], v[202:205], v[4:7]
	v_mfma_f32_16x16x32_bf16 v[0:3], v[218:221], v[202:205], v[0:3]
	s_setprio 0
	s_add_i32 s52, 0, 0x18000
	v_add_u32_e32 v48, s52, v141
	s_barrier
	ds_read_b128 v[150:153], v48
	ds_read_b128 v[156:159], v48 offset:1024
	ds_read_b128 v[160:163], v48 offset:2048
	ds_read_b128 v[164:167], v48 offset:3072
	s_add_u32 s34, s34, 0x40000
	s_addc_u32 s35, s35, 0
	s_mov_b32 m0, s44
	ds_read_b128 v[168:171], v155 offset:32768
	ds_read_b128 v[172:175], v155 offset:33792
	ds_read_b128 v[176:179], v155 offset:34816
	ds_read_b128 v[180:183], v155 offset:35840
	ds_read_b128 v[184:187], v155 offset:36864
	ds_read_b128 v[188:191], v155 offset:37888
	ds_read_b128 v[198:201], v155 offset:38912
	ds_read_b128 v[202:205], v155 offset:39936
	global_load_lds_dwordx4 v130, s[34:35]
	s_mov_b32 m0, s45
	s_nop 0
	global_load_lds_dwordx4 v134, s[34:35]
	s_waitcnt lgkmcnt(8)
	s_barrier
	s_waitcnt lgkmcnt(0)
	s_setprio 1
	s_waitcnt lgkmcnt(0)
	v_mfma_f32_16x16x32_bf16 v[126:129], v[150:153], v[168:171], v[126:129]
	v_mfma_f32_16x16x32_bf16 v[122:125], v[160:163], v[168:171], v[122:125]
	v_mfma_f32_16x16x32_bf16 v[110:113], v[150:153], v[176:179], v[110:113]
	v_mfma_f32_16x16x32_bf16 v[106:109], v[160:163], v[176:179], v[106:109]
	v_mfma_f32_16x16x32_bf16 v[94:97], v[150:153], v[184:187], v[94:97]
	v_mfma_f32_16x16x32_bf16 v[90:93], v[160:163], v[184:187], v[90:93]
	v_mfma_f32_16x16x32_bf16 v[78:81], v[150:153], v[198:201], v[78:81]
	v_mfma_f32_16x16x32_bf16 v[74:77], v[160:163], v[198:201], v[74:77]
	v_mfma_f32_16x16x32_bf16 v[126:129], v[156:159], v[172:175], v[126:129]
	v_mfma_f32_16x16x32_bf16 v[122:125], v[164:167], v[172:175], v[122:125]
	v_mfma_f32_16x16x32_bf16 v[110:113], v[156:159], v[180:183], v[110:113]
	v_mfma_f32_16x16x32_bf16 v[106:109], v[164:167], v[180:183], v[106:109]
	v_mfma_f32_16x16x32_bf16 v[94:97], v[156:159], v[188:191], v[94:97]
	v_mfma_f32_16x16x32_bf16 v[90:93], v[164:167], v[188:191], v[90:93]
	v_mfma_f32_16x16x32_bf16 v[78:81], v[156:159], v[202:205], v[78:81]
	v_mfma_f32_16x16x32_bf16 v[74:77], v[164:167], v[202:205], v[74:77]
	s_setprio 0
	s_barrier
	s_add_i32 s34, 0, 0x1c000
	s_add_i32 s35, s52, s41
	v_add_u32_e32 v48, s34, v141
	v_lshl_add_u64 v[192:193], v[192:193], 0, s[66:67]
	s_mov_b32 m0, s35
	ds_read_b128 v[206:209], v48
	ds_read_b128 v[210:213], v48 offset:1024
	ds_read_b128 v[214:217], v48 offset:2048
	ds_read_b128 v[218:221], v48 offset:3072
	global_load_lds_dwordx4 v[192:193], off
	v_lshl_add_u64 v[192:193], v[222:223], 0, s[66:67]
	s_add_i32 m0, s35, 0x2000
	s_nop 0
	global_load_lds_dwordx4 v[192:193], off
	s_barrier
	s_waitcnt lgkmcnt(0)
	s_setprio 1
	s_waitcnt lgkmcnt(0)
	v_mfma_f32_16x16x32_bf16 v[118:121], v[206:209], v[168:171], v[118:121]
	v_mfma_f32_16x16x32_bf16 v[114:117], v[214:217], v[168:171], v[114:117]
	v_mfma_f32_16x16x32_bf16 v[102:105], v[206:209], v[176:179], v[102:105]
	v_mfma_f32_16x16x32_bf16 v[98:101], v[214:217], v[176:179], v[98:101]
	v_mfma_f32_16x16x32_bf16 v[86:89], v[206:209], v[184:187], v[86:89]
	v_mfma_f32_16x16x32_bf16 v[82:85], v[214:217], v[184:187], v[82:85]
	v_mfma_f32_16x16x32_bf16 v[70:73], v[206:209], v[198:201], v[70:73]
	v_mfma_f32_16x16x32_bf16 v[66:69], v[214:217], v[198:201], v[66:69]
	v_mfma_f32_16x16x32_bf16 v[118:121], v[210:213], v[172:175], v[118:121]
	v_mfma_f32_16x16x32_bf16 v[114:117], v[218:221], v[172:175], v[114:117]
	v_mfma_f32_16x16x32_bf16 v[102:105], v[210:213], v[180:183], v[102:105]
	v_mfma_f32_16x16x32_bf16 v[98:101], v[218:221], v[180:183], v[98:101]
	v_mfma_f32_16x16x32_bf16 v[86:89], v[210:213], v[188:191], v[86:89]
	v_mfma_f32_16x16x32_bf16 v[82:85], v[218:221], v[188:191], v[82:85]
	v_mfma_f32_16x16x32_bf16 v[70:73], v[210:213], v[202:205], v[70:73]
	v_mfma_f32_16x16x32_bf16 v[66:69], v[218:221], v[202:205], v[66:69]
	s_setprio 0
	s_mov_b32 m0, s46
	v_lshl_add_u64 v[192:193], v[242:243], 0, s[66:67]
	s_barrier
	ds_read_b128 v[168:171], v155 offset:49152
	ds_read_b128 v[172:175], v155 offset:50176
	ds_read_b128 v[176:179], v155 offset:51200
	ds_read_b128 v[180:183], v155 offset:52224
	ds_read_b128 v[184:187], v155 offset:53248
	ds_read_b128 v[188:191], v155 offset:54272
	ds_read_b128 v[198:201], v155 offset:55296
	ds_read_b128 v[202:205], v155 offset:56320
	global_load_lds_dwordx4 v[192:193], off
	v_lshl_add_u64 v[192:193], v[244:245], 0, s[66:67]
	s_mov_b32 m0, s47
	s_nop 0
	global_load_lds_dwordx4 v[192:193], off
	s_barrier
	s_waitcnt lgkmcnt(0)
	s_setprio 1
	s_waitcnt lgkmcnt(0)
	v_mfma_f32_16x16x32_bf16 v[62:65], v[150:153], v[168:171], v[62:65]
	v_mfma_f32_16x16x32_bf16 v[58:61], v[160:163], v[168:171], v[58:61]
	v_mfma_f32_16x16x32_bf16 v[44:47], v[150:153], v[176:179], v[44:47]
	v_mfma_f32_16x16x32_bf16 v[40:43], v[160:163], v[176:179], v[40:43]
	v_mfma_f32_16x16x32_bf16 v[28:31], v[150:153], v[184:187], v[28:31]
	v_mfma_f32_16x16x32_bf16 v[24:27], v[160:163], v[184:187], v[24:27]
	v_mfma_f32_16x16x32_bf16 v[12:15], v[150:153], v[198:201], v[12:15]
	v_mfma_f32_16x16x32_bf16 v[8:11], v[160:163], v[198:201], v[8:11]
	v_mfma_f32_16x16x32_bf16 v[62:65], v[156:159], v[172:175], v[62:65]
	v_mfma_f32_16x16x32_bf16 v[58:61], v[164:167], v[172:175], v[58:61]
	v_mfma_f32_16x16x32_bf16 v[44:47], v[156:159], v[180:183], v[44:47]
	v_mfma_f32_16x16x32_bf16 v[40:43], v[164:167], v[180:183], v[40:43]
	v_mfma_f32_16x16x32_bf16 v[28:31], v[156:159], v[188:191], v[28:31]
	v_mfma_f32_16x16x32_bf16 v[24:27], v[164:167], v[188:191], v[24:27]
	v_mfma_f32_16x16x32_bf16 v[12:15], v[156:159], v[202:205], v[12:15]
	v_mfma_f32_16x16x32_bf16 v[8:11], v[164:167], v[202:205], v[8:11]
	s_setprio 0
	s_barrier
	s_add_u32 s30, s30, 0x40080
	s_addc_u32 s31, s31, 0
	s_add_i32 s34, s34, s41
	s_mov_b32 m0, s34
	s_nop 0
	global_load_lds_dwordx4 v132, s[30:31]
	s_add_i32 m0, s34, 0x2000
	s_nop 0
	global_load_lds_dwordx4 v136, s[30:31]
	s_waitcnt vmcnt(6)
	s_barrier
	s_setprio 1
	v_mfma_f32_16x16x32_bf16 v[54:57], v[206:209], v[168:171], v[54:57]
	v_mfma_f32_16x16x32_bf16 v[50:53], v[214:217], v[168:171], v[50:53]
	v_mfma_f32_16x16x32_bf16 v[36:39], v[206:209], v[176:179], v[36:39]
	v_mfma_f32_16x16x32_bf16 v[32:35], v[214:217], v[176:179], v[32:35]
	v_mfma_f32_16x16x32_bf16 v[20:23], v[206:209], v[184:187], v[20:23]
	v_mfma_f32_16x16x32_bf16 v[16:19], v[214:217], v[184:187], v[16:19]
	v_mfma_f32_16x16x32_bf16 v[4:7], v[206:209], v[198:201], v[4:7]
	v_mfma_f32_16x16x32_bf16 v[0:3], v[214:217], v[198:201], v[0:3]
	v_mfma_f32_16x16x32_bf16 v[54:57], v[210:213], v[172:175], v[54:57]
	v_mfma_f32_16x16x32_bf16 v[50:53], v[218:221], v[172:175], v[50:53]
	v_mfma_f32_16x16x32_bf16 v[36:39], v[210:213], v[180:183], v[36:39]
	v_mfma_f32_16x16x32_bf16 v[32:35], v[218:221], v[180:183], v[32:35]
	v_mfma_f32_16x16x32_bf16 v[20:23], v[210:213], v[188:191], v[20:23]
	v_mfma_f32_16x16x32_bf16 v[16:19], v[218:221], v[188:191], v[16:19]
	v_mfma_f32_16x16x32_bf16 v[4:7], v[210:213], v[202:205], v[4:7]
	v_mfma_f32_16x16x32_bf16 v[0:3], v[218:221], v[202:205], v[0:3]
	s_setprio 0
	s_add_i32 s51, s51, 2
	s_add_u32 s4, s4, 0x100
	s_addc_u32 s5, s5, 0
	s_add_u32 s23, s23, 0x100
	s_addc_u32 s25, s25, 0
	s_cmp_gt_u32 s51, 13
	s_barrier
	s_cbranch_scc0 .LBB0_305
	v_lshl_add_u32 v156, s50, 8, v139
	v_ashrrev_i32_e32 v48, 31, v156
	v_alignbit_b32 v150, v48, v156, 6
	v_mad_u64_u32 v[150:151], s[4:5], v150, s71, 0
	v_mad_i32_i24 v151, v48, s71, v151
	v_lshlrev_b32_e32 v48, 3, v156
	s_cmp_lg_u32 s49, 0
	v_and_b32_e32 v48, 0x78, v48
	s_cselect_b64 s[30:31], -1, 0
	s_and_b64 vcc, exec, s[30:31]
	v_lshl_add_u32 v157, s49, 8, v145
	v_lshlrev_b32_e32 v48, 1, v48
	s_cbranch_vccz .LBB0_314
	v_ashrrev_i32_e32 v152, 3, v157
	v_ashrrev_i32_e32 v153, 31, v152
	v_lshl_add_u64 v[152:153], v[150:151], 0, v[152:153]
	v_lshlrev_b64 v[152:153], 10, v[152:153]
	v_lshl_add_u64 v[152:153], s[18:19], 0, v[152:153]
	v_lshl_add_u64 v[152:153], v[152:153], 0, v[48:49]
	v_ashrrev_i32_e32 v159, 5, v156
	v_add_u32_e32 v158, v159, v140
	s_cbranch_execnz .LBB0_309

.LBB0_641:
	s_add_u32 s24, s22, 0x100
	s_addc_u32 s25, s23, 0
	s_add_i32 s50, 0, 0x10000
	v_add_u32_e32 v145, s50, v143
	ds_read_b128 v[146:149], v145
	ds_read_b128 v[150:153], v145 offset:1024
	ds_read_b128 v[154:157], v145 offset:2048
	ds_read_b128 v[158:161], v145 offset:3072
	s_cmp_eq_u32 s49, 4
	s_cselect_b32 s29, s19, s25
	s_cselect_b32 s28, s18, s24
	s_cselect_b32 s27, s21, s48
	s_cselect_b32 s26, s20, s5
	v_lshl_add_u64 v[198:199], s[22:23], 0, v[138:139]
	s_add_i32 m0, s38, 0xc000
	ds_read_b128 v[162:165], v144
	ds_read_b128 v[166:169], v144 offset:1024
	ds_read_b128 v[170:173], v144 offset:2048
	ds_read_b128 v[174:177], v144 offset:3072
	ds_read_b128 v[178:181], v144 offset:4096
	ds_read_b128 v[182:185], v144 offset:5120
	ds_read_b128 v[186:189], v144 offset:6144
	ds_read_b128 v[190:193], v144 offset:7168
	global_load_lds_dwordx4 v[198:199], off
	v_lshl_add_u64 v[198:199], s[22:23], 0, v[140:141]
	s_add_i32 m0, s38, 0xe000
	s_nop 0
	global_load_lds_dwordx4 v[198:199], off
	s_waitcnt lgkmcnt(8)
	s_barrier
	s_waitcnt lgkmcnt(0)
	s_setprio 1
	s_waitcnt lgkmcnt(0)
	v_mfma_f32_16x16x32_bf16 v[126:129], v[146:149], v[162:165], v[126:129]
	v_mfma_f32_16x16x32_bf16 v[122:125], v[154:157], v[162:165], v[122:125]
	v_mfma_f32_16x16x32_bf16 v[118:121], v[146:149], v[170:173], v[118:121]
	v_mfma_f32_16x16x32_bf16 v[114:117], v[154:157], v[170:173], v[114:117]
	v_mfma_f32_16x16x32_bf16 v[106:109], v[146:149], v[178:181], v[106:109]
	v_mfma_f32_16x16x32_bf16 v[98:101], v[154:157], v[178:181], v[98:101]
	v_mfma_f32_16x16x32_bf16 v[90:93], v[146:149], v[186:189], v[90:93]
	v_mfma_f32_16x16x32_bf16 v[82:85], v[154:157], v[186:189], v[82:85]
	v_mfma_f32_16x16x32_bf16 v[126:129], v[150:153], v[166:169], v[126:129]
	v_mfma_f32_16x16x32_bf16 v[122:125], v[158:161], v[166:169], v[122:125]
	v_mfma_f32_16x16x32_bf16 v[118:121], v[150:153], v[174:177], v[118:121]
	v_mfma_f32_16x16x32_bf16 v[114:117], v[158:161], v[174:177], v[114:117]
	v_mfma_f32_16x16x32_bf16 v[106:109], v[150:153], v[182:185], v[106:109]
	v_mfma_f32_16x16x32_bf16 v[98:101], v[158:161], v[182:185], v[98:101]
	v_mfma_f32_16x16x32_bf16 v[90:93], v[150:153], v[190:193], v[90:93]
	v_mfma_f32_16x16x32_bf16 v[82:85], v[158:161], v[190:193], v[82:85]
	s_setprio 0
	s_barrier
	s_add_i32 s51, 0, 0x14000
	s_add_i32 s22, s50, s37
	v_add_u32_e32 v145, s51, v143
	v_lshl_add_u64 v[214:215], s[26:27], 0, v[48:49]
	s_mov_b32 m0, s22
	ds_read_b128 v[198:201], v145
	ds_read_b128 v[202:205], v145 offset:1024
	ds_read_b128 v[206:209], v145 offset:2048
	ds_read_b128 v[210:213], v145 offset:3072
	global_load_lds_dwordx4 v[214:215], off
	v_lshl_add_u64 v[216:217], s[26:27], 0, v[130:131]
	s_add_i32 m0, s22, 0x2000
	s_nop 0
	global_load_lds_dwordx4 v[216:217], off
	s_barrier
	s_waitcnt lgkmcnt(0)
	s_setprio 1
	s_waitcnt lgkmcnt(0)
	v_mfma_f32_16x16x32_bf16 v[110:113], v[198:201], v[162:165], v[110:113]
	v_mfma_f32_16x16x32_bf16 v[102:105], v[206:209], v[162:165], v[102:105]
	v_mfma_f32_16x16x32_bf16 v[94:97], v[198:201], v[170:173], v[94:97]
	v_mfma_f32_16x16x32_bf16 v[86:89], v[206:209], v[170:173], v[86:89]
	v_mfma_f32_16x16x32_bf16 v[78:81], v[198:201], v[178:181], v[78:81]
	v_mfma_f32_16x16x32_bf16 v[74:77], v[206:209], v[178:181], v[74:77]
	v_mfma_f32_16x16x32_bf16 v[70:73], v[198:201], v[186:189], v[70:73]
	v_mfma_f32_16x16x32_bf16 v[66:69], v[206:209], v[186:189], v[66:69]
	v_mfma_f32_16x16x32_bf16 v[110:113], v[202:205], v[166:169], v[110:113]
	v_mfma_f32_16x16x32_bf16 v[102:105], v[210:213], v[166:169], v[102:105]
	v_mfma_f32_16x16x32_bf16 v[94:97], v[202:205], v[174:177], v[94:97]
	v_mfma_f32_16x16x32_bf16 v[86:89], v[210:213], v[174:177], v[86:89]
	v_mfma_f32_16x16x32_bf16 v[78:81], v[202:205], v[182:185], v[78:81]
	v_mfma_f32_16x16x32_bf16 v[74:77], v[210:213], v[182:185], v[74:77]
	v_mfma_f32_16x16x32_bf16 v[70:73], v[202:205], v[190:193], v[70:73]
	v_mfma_f32_16x16x32_bf16 v[66:69], v[210:213], v[190:193], v[66:69]
	s_setprio 0
	s_mov_b32 m0, s38
	v_lshl_add_u64 v[218:219], s[28:29], 0, v[134:135]
	s_barrier
	ds_read_b128 v[162:165], v144 offset:16384
	ds_read_b128 v[166:169], v144 offset:17408
	ds_read_b128 v[170:173], v144 offset:18432
	ds_read_b128 v[174:177], v144 offset:19456
	ds_read_b128 v[178:181], v144 offset:20480
	ds_read_b128 v[182:185], v144 offset:21504
	ds_read_b128 v[186:189], v144 offset:22528
	ds_read_b128 v[190:193], v144 offset:23552
	global_load_lds_dwordx4 v[218:219], off
	v_lshl_add_u64 v[220:221], s[28:29], 0, v[132:133]
	s_mov_b32 m0, s39
	s_nop 0
	global_load_lds_dwordx4 v[220:221], off
	s_barrier
	s_waitcnt lgkmcnt(0)
	s_setprio 1
	s_waitcnt lgkmcnt(0)
	v_mfma_f32_16x16x32_bf16 v[62:65], v[146:149], v[162:165], v[62:65]
	v_mfma_f32_16x16x32_bf16 v[58:61], v[154:157], v[162:165], v[58:61]
	v_mfma_f32_16x16x32_bf16 v[54:57], v[146:149], v[170:173], v[54:57]
	v_mfma_f32_16x16x32_bf16 v[50:53], v[154:157], v[170:173], v[50:53]
	v_mfma_f32_16x16x32_bf16 v[36:39], v[146:149], v[178:181], v[36:39]
	v_mfma_f32_16x16x32_bf16 v[32:35], v[154:157], v[178:181], v[32:35]
	v_mfma_f32_16x16x32_bf16 v[20:23], v[146:149], v[186:189], v[20:23]
	v_mfma_f32_16x16x32_bf16 v[16:19], v[154:157], v[186:189], v[16:19]
	v_mfma_f32_16x16x32_bf16 v[62:65], v[150:153], v[166:169], v[62:65]
	v_mfma_f32_16x16x32_bf16 v[58:61], v[158:161], v[166:169], v[58:61]
	v_mfma_f32_16x16x32_bf16 v[54:57], v[150:153], v[174:177], v[54:57]
	v_mfma_f32_16x16x32_bf16 v[50:53], v[158:161], v[174:177], v[50:53]
	v_mfma_f32_16x16x32_bf16 v[36:39], v[150:153], v[182:185], v[36:39]
	v_mfma_f32_16x16x32_bf16 v[32:35], v[158:161], v[182:185], v[32:35]
	v_mfma_f32_16x16x32_bf16 v[20:23], v[150:153], v[190:193], v[20:23]
	v_mfma_f32_16x16x32_bf16 v[16:19], v[158:161], v[190:193], v[16:19]
	s_setprio 0
	s_barrier
	s_add_u32 s22, s26, 0x20000
	s_addc_u32 s23, s27, 0
	s_add_i32 s50, s51, s37
	v_lshl_add_u64 v[146:147], s[22:23], 0, v[48:49]
	s_mov_b32 m0, s50
	s_nop 0
	global_load_lds_dwordx4 v[146:147], off
	s_add_i32 m0, s50, 0x2000
	s_nop 0
	global_load_lds_dwordx4 v130, s[22:23]
	s_waitcnt vmcnt(6)
	s_barrier
	s_setprio 1
	v_mfma_f32_16x16x32_bf16 v[44:47], v[198:201], v[162:165], v[44:47]
	v_mfma_f32_16x16x32_bf16 v[40:43], v[206:209], v[162:165], v[40:43]
	v_mfma_f32_16x16x32_bf16 v[28:31], v[198:201], v[170:173], v[28:31]
	v_mfma_f32_16x16x32_bf16 v[24:27], v[206:209], v[170:173], v[24:27]
	v_mfma_f32_16x16x32_bf16 v[12:15], v[198:201], v[178:181], v[12:15]
	v_mfma_f32_16x16x32_bf16 v[8:11], v[206:209], v[178:181], v[8:11]
	v_mfma_f32_16x16x32_bf16 v[4:7], v[198:201], v[186:189], v[4:7]
	v_mfma_f32_16x16x32_bf16 v[0:3], v[206:209], v[186:189], v[0:3]
	v_mfma_f32_16x16x32_bf16 v[44:47], v[202:205], v[166:169], v[44:47]
	v_mfma_f32_16x16x32_bf16 v[40:43], v[210:213], v[166:169], v[40:43]
	v_mfma_f32_16x16x32_bf16 v[28:31], v[202:205], v[174:177], v[28:31]
	v_mfma_f32_16x16x32_bf16 v[24:27], v[210:213], v[174:177], v[24:27]
	v_mfma_f32_16x16x32_bf16 v[12:15], v[202:205], v[182:185], v[12:15]
	v_mfma_f32_16x16x32_bf16 v[8:11], v[210:213], v[182:185], v[8:11]
	v_mfma_f32_16x16x32_bf16 v[4:7], v[202:205], v[190:193], v[4:7]
	v_mfma_f32_16x16x32_bf16 v[0:3], v[210:213], v[190:193], v[0:3]
	s_setprio 0
	s_add_i32 s50, 0, 0x18000
	v_add_u32_e32 v145, s50, v143
	s_barrier
	ds_read_b128 v[146:149], v145
	ds_read_b128 v[150:153], v145 offset:1024
	ds_read_b128 v[154:157], v145 offset:2048
	ds_read_b128 v[158:161], v145 offset:3072
	s_add_u32 s22, s28, 0x30000
	s_addc_u32 s23, s29, 0
	s_mov_b32 m0, s40
	ds_read_b128 v[162:165], v144 offset:32768
	ds_read_b128 v[166:169], v144 offset:33792
	ds_read_b128 v[170:173], v144 offset:34816
	ds_read_b128 v[174:177], v144 offset:35840
	ds_read_b128 v[178:181], v144 offset:36864
	ds_read_b128 v[182:185], v144 offset:37888
	ds_read_b128 v[186:189], v144 offset:38912
	ds_read_b128 v[190:193], v144 offset:39936
	global_load_lds_dwordx4 v134, s[22:23]
	s_mov_b32 m0, s41
	s_nop 0
	global_load_lds_dwordx4 v132, s[22:23]
	s_waitcnt lgkmcnt(8)
	s_barrier
	s_waitcnt lgkmcnt(0)
	s_setprio 1
	s_waitcnt lgkmcnt(0)
	v_mfma_f32_16x16x32_bf16 v[126:129], v[146:149], v[162:165], v[126:129]
	v_mfma_f32_16x16x32_bf16 v[122:125], v[154:157], v[162:165], v[122:125]
	v_mfma_f32_16x16x32_bf16 v[118:121], v[146:149], v[170:173], v[118:121]
	v_mfma_f32_16x16x32_bf16 v[114:117], v[154:157], v[170:173], v[114:117]
	v_mfma_f32_16x16x32_bf16 v[106:109], v[146:149], v[178:181], v[106:109]
	v_mfma_f32_16x16x32_bf16 v[98:101], v[154:157], v[178:181], v[98:101]
	v_mfma_f32_16x16x32_bf16 v[90:93], v[146:149], v[186:189], v[90:93]
	v_mfma_f32_16x16x32_bf16 v[82:85], v[154:157], v[186:189], v[82:85]
	v_mfma_f32_16x16x32_bf16 v[126:129], v[150:153], v[166:169], v[126:129]
	v_mfma_f32_16x16x32_bf16 v[122:125], v[158:161], v[166:169], v[122:125]
	v_mfma_f32_16x16x32_bf16 v[118:121], v[150:153], v[174:177], v[118:121]
	v_mfma_f32_16x16x32_bf16 v[114:117], v[158:161], v[174:177], v[114:117]
	v_mfma_f32_16x16x32_bf16 v[106:109], v[150:153], v[182:185], v[106:109]
	v_mfma_f32_16x16x32_bf16 v[98:101], v[158:161], v[182:185], v[98:101]
	v_mfma_f32_16x16x32_bf16 v[90:93], v[150:153], v[190:193], v[90:93]
	v_mfma_f32_16x16x32_bf16 v[82:85], v[158:161], v[190:193], v[82:85]
	s_setprio 0
	s_barrier
	s_add_i32 s28, 0, 0x1c000
	s_add_i32 s22, s50, s37
	v_add_u32_e32 v145, s28, v143
	v_lshl_add_u64 v[214:215], v[214:215], 0, s[66:67]
	s_mov_b32 m0, s22
	ds_read_b128 v[198:201], v145
	ds_read_b128 v[202:205], v145 offset:1024
	ds_read_b128 v[206:209], v145 offset:2048
	ds_read_b128 v[210:213], v145 offset:3072
	global_load_lds_dwordx4 v[214:215], off
	v_lshl_add_u64 v[214:215], v[216:217], 0, s[66:67]
	s_add_i32 m0, s22, 0x2000
	s_nop 0
	global_load_lds_dwordx4 v[214:215], off
	s_barrier
	s_waitcnt lgkmcnt(0)
	s_setprio 1
	s_waitcnt lgkmcnt(0)
	v_mfma_f32_16x16x32_bf16 v[110:113], v[198:201], v[162:165], v[110:113]
	v_mfma_f32_16x16x32_bf16 v[102:105], v[206:209], v[162:165], v[102:105]
	v_mfma_f32_16x16x32_bf16 v[94:97], v[198:201], v[170:173], v[94:97]
	v_mfma_f32_16x16x32_bf16 v[86:89], v[206:209], v[170:173], v[86:89]
	v_mfma_f32_16x16x32_bf16 v[78:81], v[198:201], v[178:181], v[78:81]
	v_mfma_f32_16x16x32_bf16 v[74:77], v[206:209], v[178:181], v[74:77]
	v_mfma_f32_16x16x32_bf16 v[70:73], v[198:201], v[186:189], v[70:73]
	v_mfma_f32_16x16x32_bf16 v[66:69], v[206:209], v[186:189], v[66:69]
	v_mfma_f32_16x16x32_bf16 v[110:113], v[202:205], v[166:169], v[110:113]
	v_mfma_f32_16x16x32_bf16 v[102:105], v[210:213], v[166:169], v[102:105]
	v_mfma_f32_16x16x32_bf16 v[94:97], v[202:205], v[174:177], v[94:97]
	v_mfma_f32_16x16x32_bf16 v[86:89], v[210:213], v[174:177], v[86:89]
	v_mfma_f32_16x16x32_bf16 v[78:81], v[202:205], v[182:185], v[78:81]
	v_mfma_f32_16x16x32_bf16 v[74:77], v[210:213], v[182:185], v[74:77]
	v_mfma_f32_16x16x32_bf16 v[70:73], v[202:205], v[190:193], v[70:73]
	v_mfma_f32_16x16x32_bf16 v[66:69], v[210:213], v[190:193], v[66:69]
	s_setprio 0
	s_mov_b32 m0, s42
	v_lshl_add_u64 v[214:215], v[218:219], 0, s[66:67]
	s_barrier
	ds_read_b128 v[162:165], v144 offset:49152
	ds_read_b128 v[166:169], v144 offset:50176
	ds_read_b128 v[170:173], v144 offset:51200
	ds_read_b128 v[174:177], v144 offset:52224
	ds_read_b128 v[178:181], v144 offset:53248
	ds_read_b128 v[182:185], v144 offset:54272
	ds_read_b128 v[186:189], v144 offset:55296
	ds_read_b128 v[190:193], v144 offset:56320
	global_load_lds_dwordx4 v[214:215], off
	v_lshl_add_u64 v[214:215], v[220:221], 0, s[66:67]
	s_mov_b32 m0, s43
	s_nop 0
	global_load_lds_dwordx4 v[214:215], off
	s_barrier
	s_waitcnt lgkmcnt(0)
	s_setprio 1
	s_waitcnt lgkmcnt(0)
	v_mfma_f32_16x16x32_bf16 v[62:65], v[146:149], v[162:165], v[62:65]
	v_mfma_f32_16x16x32_bf16 v[58:61], v[154:157], v[162:165], v[58:61]
	v_mfma_f32_16x16x32_bf16 v[54:57], v[146:149], v[170:173], v[54:57]
	v_mfma_f32_16x16x32_bf16 v[50:53], v[154:157], v[170:173], v[50:53]
	v_mfma_f32_16x16x32_bf16 v[36:39], v[146:149], v[178:181], v[36:39]
	v_mfma_f32_16x16x32_bf16 v[32:35], v[154:157], v[178:181], v[32:35]
	v_mfma_f32_16x16x32_bf16 v[20:23], v[146:149], v[186:189], v[20:23]
	v_mfma_f32_16x16x32_bf16 v[16:19], v[154:157], v[186:189], v[16:19]
	v_mfma_f32_16x16x32_bf16 v[62:65], v[150:153], v[166:169], v[62:65]
	v_mfma_f32_16x16x32_bf16 v[58:61], v[158:161], v[166:169], v[58:61]
	v_mfma_f32_16x16x32_bf16 v[54:57], v[150:153], v[174:177], v[54:57]
	v_mfma_f32_16x16x32_bf16 v[50:53], v[158:161], v[174:177], v[50:53]
	v_mfma_f32_16x16x32_bf16 v[36:39], v[150:153], v[182:185], v[36:39]
	v_mfma_f32_16x16x32_bf16 v[32:35], v[158:161], v[182:185], v[32:35]
	v_mfma_f32_16x16x32_bf16 v[20:23], v[150:153], v[190:193], v[20:23]
	v_mfma_f32_16x16x32_bf16 v[16:19], v[158:161], v[190:193], v[16:19]
	s_setprio 0
	s_barrier
	s_add_u32 s22, s26, 0x20080
	s_addc_u32 s23, s27, 0
	s_add_i32 s26, s28, s37
	v_lshl_add_u64 v[146:147], s[22:23], 0, v[48:49]
	s_mov_b32 m0, s26
	s_nop 0
	global_load_lds_dwordx4 v[146:147], off
	s_add_i32 m0, s26, 0x2000
	s_nop 0
	global_load_lds_dwordx4 v130, s[22:23]
	s_waitcnt vmcnt(6)
	s_barrier
	s_setprio 1
	v_mfma_f32_16x16x32_bf16 v[44:47], v[198:201], v[162:165], v[44:47]
	v_mfma_f32_16x16x32_bf16 v[40:43], v[206:209], v[162:165], v[40:43]
	v_mfma_f32_16x16x32_bf16 v[28:31], v[198:201], v[170:173], v[28:31]
	v_mfma_f32_16x16x32_bf16 v[24:27], v[206:209], v[170:173], v[24:27]
	v_mfma_f32_16x16x32_bf16 v[12:15], v[198:201], v[178:181], v[12:15]
	v_mfma_f32_16x16x32_bf16 v[8:11], v[206:209], v[178:181], v[8:11]
	v_mfma_f32_16x16x32_bf16 v[4:7], v[198:201], v[186:189], v[4:7]
	v_mfma_f32_16x16x32_bf16 v[0:3], v[206:209], v[186:189], v[0:3]
	v_mfma_f32_16x16x32_bf16 v[44:47], v[202:205], v[166:169], v[44:47]
	v_mfma_f32_16x16x32_bf16 v[40:43], v[210:213], v[166:169], v[40:43]
	v_mfma_f32_16x16x32_bf16 v[28:31], v[202:205], v[174:177], v[28:31]
	v_mfma_f32_16x16x32_bf16 v[24:27], v[210:213], v[174:177], v[24:27]
	v_mfma_f32_16x16x32_bf16 v[12:15], v[202:205], v[182:185], v[12:15]
	v_mfma_f32_16x16x32_bf16 v[8:11], v[210:213], v[182:185], v[8:11]
	v_mfma_f32_16x16x32_bf16 v[4:7], v[202:205], v[190:193], v[4:7]
	v_mfma_f32_16x16x32_bf16 v[0:3], v[210:213], v[190:193], v[0:3]
	s_setprio 0
	s_add_i32 s49, s49, 2
	s_add_u32 s5, s5, 0x100
	s_addc_u32 s48, s48, 0
	s_cmp_gt_u32 s49, 5
	s_mov_b64 s[22:23], s[24:25]
	s_barrier
	s_cbranch_scc0 .LBB0_641
	v_lshl_add_u32 v146, s47, 8, v142
	v_mov_b32_e32 v145, 0x240000
	v_ashrrev_i32_e32 v147, 31, v146
	v_mad_i64_i32 v[148:149], s[22:23], s46, v145, v[136:137]
	v_lshlrev_b64 v[150:151], 10, v[146:147]
	v_lshl_add_u64 v[150:151], v[148:149], 0, v[150:151]
	global_store_dwordx4 v[150:151], v[126:129], off
	global_store_dwordx4 v[150:151], v[122:125], off offset:64
	global_store_dwordx4 v[150:151], v[110:113], off offset:512
	global_store_dwordx4 v[150:151], v[102:105], off offset:576
	s_mov_b32 s5, 0x20000
	s_mov_b64 s[22:23], 0x20000
	v_or_b32_e32 v102, 16, v146
	v_ashrrev_i32_e32 v103, 31, v102
	v_lshlrev_b64 v[102:103], 10, v[102:103]
	v_lshl_add_u64 v[102:103], v[148:149], 0, v[102:103]
	global_store_dwordx4 v[102:103], v[118:121], off
	global_store_dwordx4 v[102:103], v[114:117], off offset:64
	global_store_dwordx4 v[102:103], v[94:97], off offset:512
	global_store_dwordx4 v[102:103], v[86:89], off offset:576
	s_mov_b32 s46, s4
	s_mov_b32 s47, s45
	v_or_b32_e32 v86, 32, v146
	v_ashrrev_i32_e32 v87, 31, v86
	v_lshlrev_b64 v[86:87], 10, v[86:87]
	v_lshl_add_u64 v[86:87], v[148:149], 0, v[86:87]
	global_store_dwordx4 v[86:87], v[106:109], off
	global_store_dwordx4 v[86:87], v[98:101], off offset:64
	global_store_dwordx4 v[86:87], v[78:81], off offset:512
	global_store_dwordx4 v[86:87], v[74:77], off offset:576
	s_mov_b64 s[24:25], s[20:21]
	s_nop 0
	v_or_b32_e32 v74, 48, v146
	v_ashrrev_i32_e32 v75, 31, v74
	v_lshlrev_b64 v[74:75], 10, v[74:75]
	v_lshl_add_u64 v[74:75], v[148:149], 0, v[74:75]
	global_store_dwordx4 v[74:75], v[90:93], off
	global_store_dwordx4 v[74:75], v[82:85], off offset:64
	global_store_dwordx4 v[74:75], v[70:73], off offset:512
	global_store_dwordx4 v[74:75], v[66:69], off offset:576
	s_nop 1
	v_add_co_u32_e32 v68, vcc, s5, v150
	s_mov_b32 s5, 0x24000
	s_nop 0
	v_addc_co_u32_e32 v69, vcc, 0, v151, vcc
	v_lshl_add_u64 v[66:67], v[150:151], 0, s[22:23]
	global_store_dwordx4 v[68:69], v[62:65], off
	global_store_dwordx4 v[66:67], v[58:61], off offset:64
	global_store_dwordx4 v[66:67], v[44:47], off offset:512
	global_store_dwordx4 v[66:67], v[40:43], off offset:576
	s_mov_b64 s[22:23], 0x24000
	s_nop 0
	v_add_co_u32_e32 v42, vcc, s5, v150
	s_mov_b32 s5, 0x28000
	s_nop 0
	v_addc_co_u32_e32 v43, vcc, 0, v151, vcc
	v_lshl_add_u64 v[40:41], v[150:151], 0, s[22:23]
	global_store_dwordx4 v[42:43], v[54:57], off
	global_store_dwordx4 v[40:41], v[50:53], off offset:64
	global_store_dwordx4 v[40:41], v[28:31], off offset:512
	global_store_dwordx4 v[40:41], v[24:27], off offset:576
	s_mov_b64 s[22:23], 0x28000
	s_nop 0
	v_add_co_u32_e32 v26, vcc, s5, v150
	v_lshl_add_u64 v[24:25], v[150:151], 0, s[22:23]
	s_nop 0
	v_addc_co_u32_e32 v27, vcc, 0, v151, vcc
	global_store_dwordx4 v[26:27], v[36:39], off
	global_store_dwordx4 v[24:25], v[32:35], off offset:64
	global_store_dwordx4 v[24:25], v[12:15], off offset:512
	global_store_dwordx4 v[24:25], v[8:11], off offset:576
	s_mov_b64 s[22:23], 0x2c000
	s_nop 0
	v_add_co_u32_e32 v10, vcc, 0x2c000, v150
	v_lshl_add_u64 v[8:9], v[150:151], 0, s[22:23]
	s_nop 0
	v_addc_co_u32_e32 v11, vcc, 0, v151, vcc
	s_and_b64 vcc, exec, s[0:1]
	s_mov_b64 s[22:23], s[18:19]
	global_store_dwordx4 v[10:11], v[20:23], off
	global_store_dwordx4 v[8:9], v[16:19], off offset:64
	global_store_dwordx4 v[8:9], v[4:7], off offset:512
	global_store_dwordx4 v[8:9], v[0:3], off offset:576
	s_cbranch_vccz .LBB0_638
	s_waitcnt vmcnt(0)
	s_cmpk_gt_u32 s30, 0xff
	s_cbranch_scc1 .LBB0_645
	s_barrier

.LBB0_822:
	s_add_u32 s12, s10, 0x100
	s_addc_u32 s13, s11, 0
	s_add_i32 s42, 0, 0x10000
	v_add_u32_e32 v158, s42, v147
	ds_read_b128 v[142:145], v158
	ds_read_b128 v[150:153], v158 offset:1024
	ds_read_b128 v[154:157], v158 offset:2048
	ds_read_b128 v[158:161], v158 offset:3072
	s_cmp_eq_u32 s41, 8
	s_cselect_b32 s17, s5, s13
	s_cselect_b32 s16, s4, s12
	s_cselect_b32 s15, s7, s40
	s_cselect_b32 s14, s6, s39
	v_lshl_add_u64 v[198:199], s[10:11], 0, v[138:139]
	s_add_i32 m0, s24, 0xc000
	ds_read_b128 v[162:165], v149
	ds_read_b128 v[166:169], v149 offset:1024
	ds_read_b128 v[170:173], v149 offset:2048
	ds_read_b128 v[174:177], v149 offset:3072
	ds_read_b128 v[178:181], v149 offset:4096
	ds_read_b128 v[182:185], v149 offset:5120
	ds_read_b128 v[186:189], v149 offset:6144
	ds_read_b128 v[190:193], v149 offset:7168
	global_load_lds_dwordx4 v[198:199], off
	v_lshl_add_u64 v[198:199], s[10:11], 0, v[140:141]
	s_add_i32 m0, s24, 0xe000
	s_nop 0
	global_load_lds_dwordx4 v[198:199], off
	s_waitcnt lgkmcnt(8)
	s_barrier
	s_waitcnt lgkmcnt(0)
	s_setprio 1
	s_waitcnt lgkmcnt(0)
	v_mfma_f32_16x16x32_bf16 v[126:129], v[142:145], v[162:165], v[126:129]
	v_mfma_f32_16x16x32_bf16 v[122:125], v[154:157], v[162:165], v[122:125]
	v_mfma_f32_16x16x32_bf16 v[110:113], v[142:145], v[170:173], v[110:113]
	v_mfma_f32_16x16x32_bf16 v[106:109], v[154:157], v[170:173], v[106:109]
	v_mfma_f32_16x16x32_bf16 v[94:97], v[142:145], v[178:181], v[94:97]
	v_mfma_f32_16x16x32_bf16 v[90:93], v[154:157], v[178:181], v[90:93]
	v_mfma_f32_16x16x32_bf16 v[78:81], v[142:145], v[186:189], v[78:81]
	v_mfma_f32_16x16x32_bf16 v[74:77], v[154:157], v[186:189], v[74:77]
	v_mfma_f32_16x16x32_bf16 v[126:129], v[150:153], v[166:169], v[126:129]
	v_mfma_f32_16x16x32_bf16 v[122:125], v[158:161], v[166:169], v[122:125]
	v_mfma_f32_16x16x32_bf16 v[110:113], v[150:153], v[174:177], v[110:113]
	v_mfma_f32_16x16x32_bf16 v[106:109], v[158:161], v[174:177], v[106:109]
	v_mfma_f32_16x16x32_bf16 v[94:97], v[150:153], v[182:185], v[94:97]
	v_mfma_f32_16x16x32_bf16 v[90:93], v[158:161], v[182:185], v[90:93]
	v_mfma_f32_16x16x32_bf16 v[78:81], v[150:153], v[190:193], v[78:81]
	v_mfma_f32_16x16x32_bf16 v[74:77], v[158:161], v[190:193], v[74:77]
	s_setprio 0
	s_barrier
	s_add_i32 s43, 0, 0x14000
	s_add_i32 s10, s42, s23
	v_add_u32_e32 v210, s43, v147
	v_lshl_add_u64 v[214:215], s[14:15], 0, v[134:135]
	s_mov_b32 m0, s10
	ds_read_b128 v[198:201], v210
	ds_read_b128 v[202:205], v210 offset:1024
	ds_read_b128 v[206:209], v210 offset:2048
	ds_read_b128 v[210:213], v210 offset:3072
	global_load_lds_dwordx4 v[214:215], off
	v_lshl_add_u64 v[216:217], s[14:15], 0, v[130:131]
	s_add_i32 m0, s10, 0x2000
	s_nop 0
	global_load_lds_dwordx4 v[216:217], off
	s_barrier
	s_waitcnt lgkmcnt(0)
	s_setprio 1
	s_waitcnt lgkmcnt(0)
	v_mfma_f32_16x16x32_bf16 v[118:121], v[198:201], v[162:165], v[118:121]
	v_mfma_f32_16x16x32_bf16 v[114:117], v[206:209], v[162:165], v[114:117]
	v_mfma_f32_16x16x32_bf16 v[102:105], v[198:201], v[170:173], v[102:105]
	v_mfma_f32_16x16x32_bf16 v[98:101], v[206:209], v[170:173], v[98:101]
	v_mfma_f32_16x16x32_bf16 v[86:89], v[198:201], v[178:181], v[86:89]
	v_mfma_f32_16x16x32_bf16 v[82:85], v[206:209], v[178:181], v[82:85]
	v_mfma_f32_16x16x32_bf16 v[70:73], v[198:201], v[186:189], v[70:73]
	v_mfma_f32_16x16x32_bf16 v[66:69], v[206:209], v[186:189], v[66:69]
	v_mfma_f32_16x16x32_bf16 v[118:121], v[202:205], v[166:169], v[118:121]
	v_mfma_f32_16x16x32_bf16 v[114:117], v[210:213], v[166:169], v[114:117]
	v_mfma_f32_16x16x32_bf16 v[102:105], v[202:205], v[174:177], v[102:105]
	v_mfma_f32_16x16x32_bf16 v[98:101], v[210:213], v[174:177], v[98:101]
	v_mfma_f32_16x16x32_bf16 v[86:89], v[202:205], v[182:185], v[86:89]
	v_mfma_f32_16x16x32_bf16 v[82:85], v[210:213], v[182:185], v[82:85]
	v_mfma_f32_16x16x32_bf16 v[70:73], v[202:205], v[190:193], v[70:73]
	v_mfma_f32_16x16x32_bf16 v[66:69], v[210:213], v[190:193], v[66:69]
	s_setprio 0
	s_mov_b32 m0, s24
	v_lshl_add_u64 v[218:219], s[16:17], 0, v[136:137]
	s_barrier
	ds_read_b128 v[162:165], v149 offset:16384
	ds_read_b128 v[166:169], v149 offset:17408
	ds_read_b128 v[170:173], v149 offset:18432
	ds_read_b128 v[174:177], v149 offset:19456
	ds_read_b128 v[178:181], v149 offset:20480
	ds_read_b128 v[182:185], v149 offset:21504
	ds_read_b128 v[186:189], v149 offset:22528
	ds_read_b128 v[190:193], v149 offset:23552
	global_load_lds_dwordx4 v[218:219], off
	v_lshl_add_u64 v[220:221], s[16:17], 0, v[132:133]
	s_mov_b32 m0, s25
	s_nop 0
	global_load_lds_dwordx4 v[220:221], off
	s_barrier
	s_waitcnt lgkmcnt(0)
	s_setprio 1
	s_waitcnt lgkmcnt(0)
	v_mfma_f32_16x16x32_bf16 v[62:65], v[142:145], v[162:165], v[62:65]
	v_mfma_f32_16x16x32_bf16 v[58:61], v[154:157], v[162:165], v[58:61]
	v_mfma_f32_16x16x32_bf16 v[44:47], v[142:145], v[170:173], v[44:47]
	v_mfma_f32_16x16x32_bf16 v[40:43], v[154:157], v[170:173], v[40:43]
	v_mfma_f32_16x16x32_bf16 v[28:31], v[142:145], v[178:181], v[28:31]
	v_mfma_f32_16x16x32_bf16 v[24:27], v[154:157], v[178:181], v[24:27]
	v_mfma_f32_16x16x32_bf16 v[12:15], v[142:145], v[186:189], v[12:15]
	v_mfma_f32_16x16x32_bf16 v[8:11], v[154:157], v[186:189], v[8:11]
	v_mfma_f32_16x16x32_bf16 v[62:65], v[150:153], v[166:169], v[62:65]
	v_mfma_f32_16x16x32_bf16 v[58:61], v[158:161], v[166:169], v[58:61]
	v_mfma_f32_16x16x32_bf16 v[44:47], v[150:153], v[174:177], v[44:47]
	v_mfma_f32_16x16x32_bf16 v[40:43], v[158:161], v[174:177], v[40:43]
	v_mfma_f32_16x16x32_bf16 v[28:31], v[150:153], v[182:185], v[28:31]
	v_mfma_f32_16x16x32_bf16 v[24:27], v[158:161], v[182:185], v[24:27]
	v_mfma_f32_16x16x32_bf16 v[12:15], v[150:153], v[190:193], v[12:15]
	v_mfma_f32_16x16x32_bf16 v[8:11], v[158:161], v[190:193], v[8:11]
	s_setprio 0
	s_barrier
	s_add_u32 s10, s14, 0x30000
	s_addc_u32 s11, s15, 0
	s_add_i32 s42, s43, s23
	s_mov_b32 m0, s42
	s_nop 0
	global_load_lds_dwordx4 v134, s[10:11]
	s_add_i32 m0, s42, 0x2000
	s_nop 0
	global_load_lds_dwordx4 v130, s[10:11]
	s_waitcnt vmcnt(6)
	s_barrier
	s_setprio 1
	v_mfma_f32_16x16x32_bf16 v[54:57], v[198:201], v[162:165], v[54:57]
	v_mfma_f32_16x16x32_bf16 v[50:53], v[206:209], v[162:165], v[50:53]
	v_mfma_f32_16x16x32_bf16 v[36:39], v[198:201], v[170:173], v[36:39]
	v_mfma_f32_16x16x32_bf16 v[32:35], v[206:209], v[170:173], v[32:35]
	v_mfma_f32_16x16x32_bf16 v[20:23], v[198:201], v[178:181], v[20:23]
	v_mfma_f32_16x16x32_bf16 v[16:19], v[206:209], v[178:181], v[16:19]
	v_mfma_f32_16x16x32_bf16 v[4:7], v[198:201], v[186:189], v[4:7]
	v_mfma_f32_16x16x32_bf16 v[0:3], v[206:209], v[186:189], v[0:3]
	v_mfma_f32_16x16x32_bf16 v[54:57], v[202:205], v[166:169], v[54:57]
	v_mfma_f32_16x16x32_bf16 v[50:53], v[210:213], v[166:169], v[50:53]
	v_mfma_f32_16x16x32_bf16 v[36:39], v[202:205], v[174:177], v[36:39]
	v_mfma_f32_16x16x32_bf16 v[32:35], v[210:213], v[174:177], v[32:35]
	v_mfma_f32_16x16x32_bf16 v[20:23], v[202:205], v[182:185], v[20:23]
	v_mfma_f32_16x16x32_bf16 v[16:19], v[210:213], v[182:185], v[16:19]
	v_mfma_f32_16x16x32_bf16 v[4:7], v[202:205], v[190:193], v[4:7]
	v_mfma_f32_16x16x32_bf16 v[0:3], v[210:213], v[190:193], v[0:3]
	s_setprio 0
	s_add_i32 s42, 0, 0x18000
	v_add_u32_e32 v158, s42, v147
	s_barrier
	ds_read_b128 v[142:145], v158
	ds_read_b128 v[150:153], v158 offset:1024
	ds_read_b128 v[154:157], v158 offset:2048
	ds_read_b128 v[158:161], v158 offset:3072
	s_add_u32 s10, s16, 0x30000
	s_addc_u32 s11, s17, 0
	s_mov_b32 m0, s26
	ds_read_b128 v[162:165], v149 offset:32768
	ds_read_b128 v[166:169], v149 offset:33792
	ds_read_b128 v[170:173], v149 offset:34816
	ds_read_b128 v[174:177], v149 offset:35840
	ds_read_b128 v[178:181], v149 offset:36864
	ds_read_b128 v[182:185], v149 offset:37888
	ds_read_b128 v[186:189], v149 offset:38912
	ds_read_b128 v[190:193], v149 offset:39936
	global_load_lds_dwordx4 v136, s[10:11]
	s_mov_b32 m0, s27
	s_nop 0
	global_load_lds_dwordx4 v132, s[10:11]
	s_waitcnt lgkmcnt(8)
	s_barrier
	s_waitcnt lgkmcnt(0)
	s_setprio 1
	s_waitcnt lgkmcnt(0)
	v_mfma_f32_16x16x32_bf16 v[126:129], v[142:145], v[162:165], v[126:129]
	v_mfma_f32_16x16x32_bf16 v[122:125], v[154:157], v[162:165], v[122:125]
	v_mfma_f32_16x16x32_bf16 v[110:113], v[142:145], v[170:173], v[110:113]
	v_mfma_f32_16x16x32_bf16 v[106:109], v[154:157], v[170:173], v[106:109]
	v_mfma_f32_16x16x32_bf16 v[94:97], v[142:145], v[178:181], v[94:97]
	v_mfma_f32_16x16x32_bf16 v[90:93], v[154:157], v[178:181], v[90:93]
	v_mfma_f32_16x16x32_bf16 v[78:81], v[142:145], v[186:189], v[78:81]
	v_mfma_f32_16x16x32_bf16 v[74:77], v[154:157], v[186:189], v[74:77]
	v_mfma_f32_16x16x32_bf16 v[126:129], v[150:153], v[166:169], v[126:129]
	v_mfma_f32_16x16x32_bf16 v[122:125], v[158:161], v[166:169], v[122:125]
	v_mfma_f32_16x16x32_bf16 v[110:113], v[150:153], v[174:177], v[110:113]
	v_mfma_f32_16x16x32_bf16 v[106:109], v[158:161], v[174:177], v[106:109]
	v_mfma_f32_16x16x32_bf16 v[94:97], v[150:153], v[182:185], v[94:97]
	v_mfma_f32_16x16x32_bf16 v[90:93], v[158:161], v[182:185], v[90:93]
	v_mfma_f32_16x16x32_bf16 v[78:81], v[150:153], v[190:193], v[78:81]
	v_mfma_f32_16x16x32_bf16 v[74:77], v[158:161], v[190:193], v[74:77]
	s_setprio 0
	s_barrier
	s_add_i32 s16, 0, 0x1c000
	s_add_i32 s10, s42, s23
	v_add_u32_e32 v210, s16, v147
	v_lshl_add_u64 v[214:215], v[214:215], 0, s[66:67]
	s_mov_b32 m0, s10
	ds_read_b128 v[198:201], v210
	ds_read_b128 v[202:205], v210 offset:1024
	ds_read_b128 v[206:209], v210 offset:2048
	ds_read_b128 v[210:213], v210 offset:3072
	global_load_lds_dwordx4 v[214:215], off
	v_lshl_add_u64 v[214:215], v[216:217], 0, s[66:67]
	s_add_i32 m0, s10, 0x2000
	s_nop 0
	global_load_lds_dwordx4 v[214:215], off
	s_barrier
	s_waitcnt lgkmcnt(0)
	s_setprio 1
	s_waitcnt lgkmcnt(0)
	v_mfma_f32_16x16x32_bf16 v[118:121], v[198:201], v[162:165], v[118:121]
	v_mfma_f32_16x16x32_bf16 v[114:117], v[206:209], v[162:165], v[114:117]
	v_mfma_f32_16x16x32_bf16 v[102:105], v[198:201], v[170:173], v[102:105]
	v_mfma_f32_16x16x32_bf16 v[98:101], v[206:209], v[170:173], v[98:101]
	v_mfma_f32_16x16x32_bf16 v[86:89], v[198:201], v[178:181], v[86:89]
	v_mfma_f32_16x16x32_bf16 v[82:85], v[206:209], v[178:181], v[82:85]
	v_mfma_f32_16x16x32_bf16 v[70:73], v[198:201], v[186:189], v[70:73]
	v_mfma_f32_16x16x32_bf16 v[66:69], v[206:209], v[186:189], v[66:69]
	v_mfma_f32_16x16x32_bf16 v[118:121], v[202:205], v[166:169], v[118:121]
	v_mfma_f32_16x16x32_bf16 v[114:117], v[210:213], v[166:169], v[114:117]
	v_mfma_f32_16x16x32_bf16 v[102:105], v[202:205], v[174:177], v[102:105]
	v_mfma_f32_16x16x32_bf16 v[98:101], v[210:213], v[174:177], v[98:101]
	v_mfma_f32_16x16x32_bf16 v[86:89], v[202:205], v[182:185], v[86:89]
	v_mfma_f32_16x16x32_bf16 v[82:85], v[210:213], v[182:185], v[82:85]
	v_mfma_f32_16x16x32_bf16 v[70:73], v[202:205], v[190:193], v[70:73]
	v_mfma_f32_16x16x32_bf16 v[66:69], v[210:213], v[190:193], v[66:69]
	s_setprio 0
	s_mov_b32 m0, s28
	v_lshl_add_u64 v[214:215], v[218:219], 0, s[66:67]
	s_barrier
	ds_read_b128 v[162:165], v149 offset:49152
	ds_read_b128 v[166:169], v149 offset:50176
	ds_read_b128 v[170:173], v149 offset:51200
	ds_read_b128 v[174:177], v149 offset:52224
	ds_read_b128 v[178:181], v149 offset:53248
	ds_read_b128 v[182:185], v149 offset:54272
	ds_read_b128 v[186:189], v149 offset:55296
	ds_read_b128 v[190:193], v149 offset:56320
	global_load_lds_dwordx4 v[214:215], off
	v_lshl_add_u64 v[214:215], v[220:221], 0, s[66:67]
	s_mov_b32 m0, s29
	s_nop 0
	global_load_lds_dwordx4 v[214:215], off
	s_barrier
	s_waitcnt lgkmcnt(0)
	s_setprio 1
	s_waitcnt lgkmcnt(0)
	v_mfma_f32_16x16x32_bf16 v[62:65], v[142:145], v[162:165], v[62:65]
	v_mfma_f32_16x16x32_bf16 v[58:61], v[154:157], v[162:165], v[58:61]
	v_mfma_f32_16x16x32_bf16 v[44:47], v[142:145], v[170:173], v[44:47]
	v_mfma_f32_16x16x32_bf16 v[40:43], v[154:157], v[170:173], v[40:43]
	v_mfma_f32_16x16x32_bf16 v[28:31], v[142:145], v[178:181], v[28:31]
	v_mfma_f32_16x16x32_bf16 v[24:27], v[154:157], v[178:181], v[24:27]
	v_mfma_f32_16x16x32_bf16 v[12:15], v[142:145], v[186:189], v[12:15]
	v_mfma_f32_16x16x32_bf16 v[8:11], v[154:157], v[186:189], v[8:11]
	v_mfma_f32_16x16x32_bf16 v[62:65], v[150:153], v[166:169], v[62:65]
	v_mfma_f32_16x16x32_bf16 v[58:61], v[158:161], v[166:169], v[58:61]
	v_mfma_f32_16x16x32_bf16 v[44:47], v[150:153], v[174:177], v[44:47]
	v_mfma_f32_16x16x32_bf16 v[40:43], v[158:161], v[174:177], v[40:43]
	v_mfma_f32_16x16x32_bf16 v[28:31], v[150:153], v[182:185], v[28:31]
	v_mfma_f32_16x16x32_bf16 v[24:27], v[158:161], v[182:185], v[24:27]
	v_mfma_f32_16x16x32_bf16 v[12:15], v[150:153], v[190:193], v[12:15]
	v_mfma_f32_16x16x32_bf16 v[8:11], v[158:161], v[190:193], v[8:11]
	s_setprio 0
	s_barrier
	s_add_u32 s10, s14, 0x30080
	s_addc_u32 s11, s15, 0
	s_add_i32 s14, s16, s23
	s_mov_b32 m0, s14
	s_nop 0
	global_load_lds_dwordx4 v134, s[10:11]
	s_add_i32 m0, s14, 0x2000
	s_nop 0
	global_load_lds_dwordx4 v130, s[10:11]
	s_waitcnt vmcnt(6)
	s_barrier
	s_setprio 1
	v_mfma_f32_16x16x32_bf16 v[54:57], v[198:201], v[162:165], v[54:57]
	v_mfma_f32_16x16x32_bf16 v[50:53], v[206:209], v[162:165], v[50:53]
	v_mfma_f32_16x16x32_bf16 v[36:39], v[198:201], v[170:173], v[36:39]
	v_mfma_f32_16x16x32_bf16 v[32:35], v[206:209], v[170:173], v[32:35]
	v_mfma_f32_16x16x32_bf16 v[20:23], v[198:201], v[178:181], v[20:23]
	v_mfma_f32_16x16x32_bf16 v[16:19], v[206:209], v[178:181], v[16:19]
	v_mfma_f32_16x16x32_bf16 v[4:7], v[198:201], v[186:189], v[4:7]
	v_mfma_f32_16x16x32_bf16 v[0:3], v[206:209], v[186:189], v[0:3]
	v_mfma_f32_16x16x32_bf16 v[54:57], v[202:205], v[166:169], v[54:57]
	v_mfma_f32_16x16x32_bf16 v[50:53], v[210:213], v[166:169], v[50:53]
	v_mfma_f32_16x16x32_bf16 v[36:39], v[202:205], v[174:177], v[36:39]
	v_mfma_f32_16x16x32_bf16 v[32:35], v[210:213], v[174:177], v[32:35]
	v_mfma_f32_16x16x32_bf16 v[20:23], v[202:205], v[182:185], v[20:23]
	v_mfma_f32_16x16x32_bf16 v[16:19], v[210:213], v[182:185], v[16:19]
	v_mfma_f32_16x16x32_bf16 v[4:7], v[202:205], v[190:193], v[4:7]
	v_mfma_f32_16x16x32_bf16 v[0:3], v[210:213], v[190:193], v[0:3]
	s_setprio 0
	s_add_i32 s41, s41, 2
	s_add_u32 s39, s39, 0x100
	s_addc_u32 s40, s40, 0
	s_cmp_gt_u32 s41, 9
	s_mov_b64 s[10:11], s[12:13]
	s_barrier
	s_cbranch_scc0 .LBB0_822
	v_lshl_add_u32 v142, s38, 8, v146
	v_ashrrev_i32_e32 v143, 31, v142
	v_lshlrev_b64 v[144:145], 14, v[142:143]
	v_mul_f32_e32 v143, 0x3d372713, v126
	v_mul_f32_e32 v143, v126, v143
	v_fma_f32 v143, v126, v143, v126
	v_mul_f32_e32 v143, 0xbfcc422a, v143
	v_mul_f32_e32 v143, 0x3fb8aa3b, v143
	v_exp_f32_e32 v150, v143
	v_mul_f32_e32 v143, 0x3d372713, v122
	v_mul_f32_e32 v143, v122, v143
	v_fma_f32 v143, v122, v143, v122
	v_mul_f32_e32 v143, 0xbfcc422a, v143
	v_mul_f32_e32 v143, 0x3fb8aa3b, v143
	v_exp_f32_e32 v152, v143
	v_mul_f32_e32 v143, 0x3d372713, v127
	v_mul_f32_e32 v143, v127, v143
	v_fma_f32 v143, v127, v143, v127
	v_mul_f32_e32 v143, 0xbfcc422a, v143
	v_mul_f32_e32 v143, 0x3fb8aa3b, v143
	v_exp_f32_e32 v151, v143
	v_lshl_or_b32 v154, s37, 8, v148
	s_lshl_b32 s10, s36, 4
	s_ashr_i32 s11, s10, 31
	v_pk_add_f32 v[150:151], v[150:151], 1.0 op_sel_hi:[1,0]
	s_lshl_b64 s[10:11], s[10:11], 1
	s_mov_b32 s36, s31
	s_mov_b32 s37, s35
	s_mov_b32 s38, s34
	v_rcp_f32_e32 v143, v151
	s_nop 0
	v_mul_f32_e32 v143, v127, v143
	s_nop 0
	v_rcp_f32_e32 v127, v150
	s_nop 0
	v_mul_f32_e32 v150, v126, v127
	v_mul_f32_e32 v126, 0x3d372713, v123
	v_mul_f32_e32 v126, v123, v126
	v_fma_f32 v126, v123, v126, v123
	v_mul_f32_e32 v126, 0xbfcc422a, v126
	v_mul_f32_e32 v126, 0x3fb8aa3b, v126
	v_exp_f32_e32 v153, v126
	v_cvt_pk_bf16_f32 v150, v150, v143
	v_pk_add_f32 v[126:127], v[152:153], 1.0 op_sel_hi:[1,0]
	s_nop 0
	s_nop 0
	v_rcp_f32_e32 v151, v127
	s_nop 0
	v_mul_f32_e32 v152, v123, v151
	s_nop 0
	v_rcp_f32_e32 v123, v126
	s_nop 0
	v_mul_f32_e32 v153, v122, v123
	v_mul_f32_e32 v123, 0x3d372713, v124
	v_mul_f32_e32 v123, v124, v123
	v_fma_f32 v123, v124, v123, v124
	v_mul_f32_e32 v123, 0xbfcc422a, v123
	v_mul_f32_e32 v123, 0x3fb8aa3b, v123
	v_mul_f32_e32 v122, 0x3d372713, v128
	v_exp_f32_e32 v126, v123
	v_mul_f32_e32 v123, 0x3d372713, v129
	v_mul_f32_e32 v122, v128, v122
	v_mul_f32_e32 v123, v129, v123
	v_fma_f32 v122, v128, v122, v128
	v_fma_f32 v123, v129, v123, v129
	v_mul_f32_e32 v122, 0xbfcc422a, v122
	v_mul_f32_e32 v123, 0xbfcc422a, v123
	v_mul_f32_e32 v122, 0x3fb8aa3b, v122
	v_mul_f32_e32 v123, 0x3fb8aa3b, v123
	v_exp_f32_e32 v122, v122
	v_exp_f32_e32 v123, v123
	v_cvt_pk_bf16_f32 v152, v153, v152
	v_pk_add_f32 v[122:123], v[122:123], 1.0 op_sel_hi:[1,0]
	s_nop 0
	s_nop 0
	v_rcp_f32_e32 v127, v123
	s_nop 0
	v_mul_f32_e32 v129, v129, v127
	s_nop 0
	v_rcp_f32_e32 v123, v122
	s_nop 0
	v_mul_f32_e32 v128, v128, v123
	v_mul_f32_e32 v122, 0x3d372713, v125
	v_mul_f32_e32 v122, v125, v122
	v_fma_f32 v122, v125, v122, v125
	v_mul_f32_e32 v122, 0xbfcc422a, v122
	v_mul_f32_e32 v122, 0x3fb8aa3b, v122
	v_exp_f32_e32 v127, v122
	s_nop 0
	v_pk_add_f32 v[122:123], v[126:127], 1.0 op_sel_hi:[1,0]
	s_nop 0
	s_nop 0
	v_rcp_f32_e32 v126, v123
	s_nop 0
	v_mul_f32_e32 v123, v125, v126
	s_nop 0
	v_ashrrev_i32_e32 v126, 4, v154
	v_ashrrev_i32_e32 v127, 31, v126
	v_rcp_f32_e32 v125, v122
	s_nop 0
	v_mul_f32_e32 v122, v124, v125
	v_lshlrev_b64 v[124:125], 9, v[126:127]
	v_mul_f32_e32 v127, 0x3d372713, v118
	v_cvt_pk_bf16_f32 v153, v122, v123
	v_lshl_add_u64 v[122:123], s[0:1], 0, v[144:145]
	v_mul_f32_e32 v127, v118, v127
	v_cvt_pk_bf16_f32 v151, v128, v129
	v_lshl_add_u64 v[128:129], v[122:123], 0, v[124:125]
	v_fma_f32 v127, v118, v127, v118
	v_lshl_add_u64 v[128:129], v[128:129], 0, s[10:11]
	v_mul_f32_e32 v127, 0xbfcc422a, v127
	v_lshl_add_u64 v[128:129], v[128:129], 0, v[48:49]
	v_mul_f32_e32 v127, 0x3fb8aa3b, v127
	global_store_dwordx4 v[128:129], v[150:153], off
	v_exp_f32_e32 v128, v127
	v_mul_f32_e32 v127, 0x3d372713, v114
	v_mul_f32_e32 v127, v114, v127
	v_fma_f32 v127, v114, v127, v114
	v_mul_f32_e32 v127, 0xbfcc422a, v127
	v_mul_f32_e32 v127, 0x3fb8aa3b, v127
	v_exp_f32_e32 v144, v127
	v_mul_f32_e32 v127, 0x3d372713, v119
	v_mul_f32_e32 v127, v119, v127
	v_fma_f32 v127, v119, v127, v119
	v_mul_f32_e32 v127, 0xbfcc422a, v127
	v_mul_f32_e32 v127, 0x3fb8aa3b, v127
	v_exp_f32_e32 v129, v127
	s_nop 0
	v_pk_add_f32 v[128:129], v[128:129], 1.0 op_sel_hi:[1,0]
	s_nop 0
	s_nop 0
	v_rcp_f32_e32 v127, v129
	s_nop 0
	v_mul_f32_e32 v127, v119, v127
	s_nop 0
	v_rcp_f32_e32 v119, v128
	s_nop 0
	v_mul_f32_e32 v128, v118, v119
	v_mul_f32_e32 v118, 0x3d372713, v115
	v_mul_f32_e32 v118, v115, v118
	v_fma_f32 v118, v115, v118, v115
	v_mul_f32_e32 v118, 0xbfcc422a, v118
	v_mul_f32_e32 v118, 0x3fb8aa3b, v118
	v_exp_f32_e32 v145, v118
	s_nop 0
	v_pk_add_f32 v[118:119], v[144:145], 1.0 op_sel_hi:[1,0]
	s_nop 0
	s_nop 0
	v_rcp_f32_e32 v129, v119
	s_nop 0
	v_mul_f32_e32 v129, v115, v129
	s_nop 0
	v_rcp_f32_e32 v115, v118
	s_nop 0
	v_mul_f32_e32 v143, v114, v115
	v_mul_f32_e32 v115, 0x3d372713, v116
	v_mul_f32_e32 v115, v116, v115
	v_fma_f32 v115, v116, v115, v116
	v_mul_f32_e32 v115, 0xbfcc422a, v115
	v_mul_f32_e32 v115, 0x3fb8aa3b, v115
	v_mul_f32_e32 v114, 0x3d372713, v120
	v_exp_f32_e32 v118, v115
	v_mul_f32_e32 v115, 0x3d372713, v121
	v_mul_f32_e32 v114, v120, v114
	v_mul_f32_e32 v115, v121, v115
	v_fma_f32 v114, v120, v114, v120
	v_fma_f32 v115, v121, v115, v121
	v_mul_f32_e32 v114, 0xbfcc422a, v114
	v_mul_f32_e32 v115, 0xbfcc422a, v115
	v_mul_f32_e32 v114, 0x3fb8aa3b, v114
	v_mul_f32_e32 v115, 0x3fb8aa3b, v115
	v_exp_f32_e32 v114, v114
	v_exp_f32_e32 v115, v115
	s_nop 0
	v_pk_add_f32 v[114:115], v[114:115], 1.0 op_sel_hi:[1,0]
	s_nop 0
	s_nop 0
	v_rcp_f32_e32 v119, v115
	s_nop 0
	v_mul_f32_e32 v121, v121, v119
	s_nop 0
	v_rcp_f32_e32 v115, v114
	s_nop 0
	v_mul_f32_e32 v120, v120, v115
	v_mul_f32_e32 v114, 0x3d372713, v117
	v_mul_f32_e32 v114, v117, v114
	v_fma_f32 v114, v117, v114, v117
	v_mul_f32_e32 v114, 0xbfcc422a, v114
	v_mul_f32_e32 v114, 0x3fb8aa3b, v114
	v_exp_f32_e32 v119, v114
	s_nop 0
	v_pk_add_f32 v[114:115], v[118:119], 1.0 op_sel_hi:[1,0]
	s_nop 0
	s_nop 0
	v_rcp_f32_e32 v118, v115
	s_nop 0
	v_mul_f32_e32 v115, v117, v118
	s_nop 0
	v_rcp_f32_e32 v117, v114
	s_nop 0
	v_mul_f32_e32 v119, v116, v117
	v_or_b32_e32 v114, 8, v126
	v_cvt_pk_bf16_f32 v119, v119, v115
	v_ashrrev_i32_e32 v115, 31, v114
	v_lshlrev_b64 v[114:115], 9, v[114:115]
	v_cvt_pk_bf16_f32 v117, v120, v121
	v_lshl_add_u64 v[120:121], v[122:123], 0, v[114:115]
	v_lshl_add_u64 v[120:121], v[120:121], 0, s[10:11]
	v_cvt_pk_bf16_f32 v116, v128, v127
	v_cvt_pk_bf16_f32 v118, v143, v129
	v_lshl_add_u64 v[120:121], v[120:121], 0, v[48:49]
	global_store_dwordx4 v[120:121], v[116:119], off
	s_nop 1
	v_mul_f32_e32 v119, 0x3d372713, v106
	v_mul_f32_e32 v119, v106, v119
	v_fma_f32 v119, v106, v119, v106
	v_mul_f32_e32 v119, 0xbfcc422a, v119
	v_mul_f32_e32 v119, 0x3fb8aa3b, v119
	v_mul_f32_e32 v118, 0x3d372713, v110
	v_exp_f32_e32 v120, v119
	v_mul_f32_e32 v119, 0x3d372713, v111
	v_mul_f32_e32 v118, v110, v118
	v_mul_f32_e32 v119, v111, v119
	v_fma_f32 v118, v110, v118, v110
	v_fma_f32 v119, v111, v119, v111
	v_mul_f32_e32 v118, 0xbfcc422a, v118
	v_mul_f32_e32 v119, 0xbfcc422a, v119
	v_mul_f32_e32 v118, 0x3fb8aa3b, v118
	v_mul_f32_e32 v119, 0x3fb8aa3b, v119
	v_exp_f32_e32 v118, v118
	v_exp_f32_e32 v119, v119
	v_or_b32_e32 v116, 16, v142
	v_ashrrev_i32_e32 v117, 31, v116
	v_lshlrev_b64 v[116:117], 14, v[116:117]
	v_pk_add_f32 v[118:119], v[118:119], 1.0 op_sel_hi:[1,0]
	s_nop 0
	s_nop 0
	v_rcp_f32_e32 v121, v119
	s_nop 0
	v_mul_f32_e32 v119, v111, v121
	s_nop 0
	v_rcp_f32_e32 v111, v118
	s_nop 0
	v_mul_f32_e32 v118, v110, v111
	v_mul_f32_e32 v110, 0x3d372713, v107
	v_mul_f32_e32 v110, v107, v110
	v_fma_f32 v110, v107, v110, v107
	v_mul_f32_e32 v110, 0xbfcc422a, v110
	v_mul_f32_e32 v110, 0x3fb8aa3b, v110
	v_exp_f32_e32 v121, v110
	s_nop 0
	v_pk_add_f32 v[110:111], v[120:121], 1.0 op_sel_hi:[1,0]
	s_nop 0
	s_nop 0
	v_rcp_f32_e32 v120, v111
	s_nop 0
	v_mul_f32_e32 v120, v107, v120
	s_nop 0
	v_rcp_f32_e32 v107, v110
	s_nop 0
	v_mul_f32_e32 v121, v106, v107
	v_mul_f32_e32 v107, 0x3d372713, v108
	v_mul_f32_e32 v107, v108, v107
	v_fma_f32 v107, v108, v107, v108
	v_mul_f32_e32 v107, 0xbfcc422a, v107
	v_mul_f32_e32 v107, 0x3fb8aa3b, v107
	v_mul_f32_e32 v106, 0x3d372713, v112
	v_exp_f32_e32 v110, v107
	v_mul_f32_e32 v107, 0x3d372713, v113
	v_mul_f32_e32 v106, v112, v106
	v_mul_f32_e32 v107, v113, v107
	v_fma_f32 v106, v112, v106, v112
	v_fma_f32 v107, v113, v107, v113
	v_mul_f32_e32 v106, 0xbfcc422a, v106
	v_mul_f32_e32 v107, 0xbfcc422a, v107
	v_mul_f32_e32 v106, 0x3fb8aa3b, v106
	v_mul_f32_e32 v107, 0x3fb8aa3b, v107
	v_exp_f32_e32 v106, v106
	v_exp_f32_e32 v107, v107
	s_nop 0
	v_pk_add_f32 v[106:107], v[106:107], 1.0 op_sel_hi:[1,0]
	s_nop 0
	s_nop 0
	v_rcp_f32_e32 v111, v107
	s_nop 0
	v_mul_f32_e32 v113, v113, v111
	s_nop 0
	v_rcp_f32_e32 v107, v106
	s_nop 0
	v_mul_f32_e32 v112, v112, v107
	v_mul_f32_e32 v106, 0x3d372713, v109
	v_mul_f32_e32 v106, v109, v106
	v_fma_f32 v106, v109, v106, v109
	v_mul_f32_e32 v106, 0xbfcc422a, v106
	v_mul_f32_e32 v106, 0x3fb8aa3b, v106
	v_exp_f32_e32 v111, v106
	s_nop 0
	v_pk_add_f32 v[106:107], v[110:111], 1.0 op_sel_hi:[1,0]
	s_nop 0
	s_nop 0
	v_rcp_f32_e32 v110, v107
	s_nop 0
	v_mul_f32_e32 v107, v109, v110
	s_nop 0
	v_rcp_f32_e32 v109, v106
	s_nop 0
	v_mul_f32_e32 v106, v108, v109
	v_cvt_pk_bf16_f32 v111, v106, v107
	v_lshl_add_u64 v[106:107], s[0:1], 0, v[116:117]
	v_cvt_pk_bf16_f32 v109, v112, v113
	v_lshl_add_u64 v[112:113], v[106:107], 0, v[124:125]
	v_lshl_add_u64 v[112:113], v[112:113], 0, s[10:11]
	v_cvt_pk_bf16_f32 v108, v118, v119
	v_cvt_pk_bf16_f32 v110, v121, v120
	v_lshl_add_u64 v[112:113], v[112:113], 0, v[48:49]
	global_store_dwordx4 v[112:113], v[108:111], off
	s_nop 1
	v_mul_f32_e32 v109, 0x3d372713, v98
	v_mul_f32_e32 v109, v98, v109
	v_fma_f32 v109, v98, v109, v98
	v_mul_f32_e32 v109, 0xbfcc422a, v109
	v_mul_f32_e32 v109, 0x3fb8aa3b, v109
	v_mul_f32_e32 v108, 0x3d372713, v102
	v_exp_f32_e32 v110, v109
	v_mul_f32_e32 v109, 0x3d372713, v103
	v_mul_f32_e32 v108, v102, v108
	v_mul_f32_e32 v109, v103, v109
	v_fma_f32 v108, v102, v108, v102
	v_fma_f32 v109, v103, v109, v103
	v_mul_f32_e32 v108, 0xbfcc422a, v108
	v_mul_f32_e32 v109, 0xbfcc422a, v109
	v_mul_f32_e32 v108, 0x3fb8aa3b, v108
	v_mul_f32_e32 v109, 0x3fb8aa3b, v109
	v_exp_f32_e32 v108, v108
	v_exp_f32_e32 v109, v109
	s_nop 0
	v_pk_add_f32 v[108:109], v[108:109], 1.0 op_sel_hi:[1,0]
	s_nop 0
	s_nop 0
	v_rcp_f32_e32 v111, v109
	s_nop 0
	v_mul_f32_e32 v109, v103, v111
	s_nop 0
	v_rcp_f32_e32 v103, v108
	s_nop 0
	v_mul_f32_e32 v108, v102, v103
	v_mul_f32_e32 v102, 0x3d372713, v99
	v_mul_f32_e32 v102, v99, v102
	v_fma_f32 v102, v99, v102, v99
	v_mul_f32_e32 v102, 0xbfcc422a, v102
	v_mul_f32_e32 v102, 0x3fb8aa3b, v102
	v_exp_f32_e32 v111, v102
	s_nop 0
	v_pk_add_f32 v[102:103], v[110:111], 1.0 op_sel_hi:[1,0]
	s_nop 0
	s_nop 0
	v_rcp_f32_e32 v110, v103
	s_nop 0
	v_mul_f32_e32 v110, v99, v110
	s_nop 0
	v_rcp_f32_e32 v99, v102
	s_nop 0
	v_mul_f32_e32 v111, v98, v99
	v_mul_f32_e32 v99, 0x3d372713, v100
	v_mul_f32_e32 v99, v100, v99
	v_fma_f32 v99, v100, v99, v100
	v_mul_f32_e32 v99, 0xbfcc422a, v99
	v_mul_f32_e32 v99, 0x3fb8aa3b, v99
	v_mul_f32_e32 v98, 0x3d372713, v104
	v_exp_f32_e32 v102, v99
	v_mul_f32_e32 v99, 0x3d372713, v105
	v_mul_f32_e32 v98, v104, v98
	v_mul_f32_e32 v99, v105, v99
	v_fma_f32 v98, v104, v98, v104
	v_fma_f32 v99, v105, v99, v105
	v_mul_f32_e32 v98, 0xbfcc422a, v98
	v_mul_f32_e32 v99, 0xbfcc422a, v99
	v_mul_f32_e32 v98, 0x3fb8aa3b, v98
	v_mul_f32_e32 v99, 0x3fb8aa3b, v99
	v_exp_f32_e32 v98, v98
	v_exp_f32_e32 v99, v99
	s_nop 0
	v_pk_add_f32 v[98:99], v[98:99], 1.0 op_sel_hi:[1,0]
	s_nop 0
	s_nop 0
	v_rcp_f32_e32 v103, v99
	s_nop 0
	v_mul_f32_e32 v105, v105, v103
	s_nop 0
	v_rcp_f32_e32 v99, v98
	s_nop 0
	v_mul_f32_e32 v104, v104, v99
	v_mul_f32_e32 v98, 0x3d372713, v101
	v_mul_f32_e32 v98, v101, v98
	v_fma_f32 v98, v101, v98, v101
	v_mul_f32_e32 v98, 0xbfcc422a, v98
	v_mul_f32_e32 v98, 0x3fb8aa3b, v98
	v_exp_f32_e32 v103, v98
	s_nop 0
	v_pk_add_f32 v[98:99], v[102:103], 1.0 op_sel_hi:[1,0]
	s_nop 0
	s_nop 0
	v_rcp_f32_e32 v102, v99
	s_nop 0
	v_mul_f32_e32 v101, v101, v102
	s_nop 0
	v_rcp_f32_e32 v99, v98
	s_nop 0
	v_mul_f32_e32 v102, v100, v99
	v_cvt_pk_bf16_f32 v101, v102, v101
	v_lshl_add_u64 v[102:103], v[106:107], 0, v[114:115]
	v_lshl_add_u64 v[102:103], v[102:103], 0, s[10:11]
	v_cvt_pk_bf16_f32 v98, v108, v109
	v_cvt_pk_bf16_f32 v99, v104, v105
	v_cvt_pk_bf16_f32 v100, v111, v110
	v_lshl_add_u64 v[102:103], v[102:103], 0, v[48:49]
	global_store_dwordx4 v[102:103], v[98:101], off
	s_nop 1
	v_mul_f32_e32 v101, 0x3d372713, v90
	v_mul_f32_e32 v101, v90, v101
	v_fma_f32 v101, v90, v101, v90
	v_mul_f32_e32 v101, 0xbfcc422a, v101
	v_mul_f32_e32 v101, 0x3fb8aa3b, v101
	v_mul_f32_e32 v100, 0x3d372713, v94
	v_exp_f32_e32 v102, v101
	v_mul_f32_e32 v101, 0x3d372713, v95
	v_mul_f32_e32 v100, v94, v100
	v_mul_f32_e32 v101, v95, v101
	v_fma_f32 v100, v94, v100, v94
	v_fma_f32 v101, v95, v101, v95
	v_mul_f32_e32 v100, 0xbfcc422a, v100
	v_mul_f32_e32 v101, 0xbfcc422a, v101
	v_mul_f32_e32 v100, 0x3fb8aa3b, v100
	v_mul_f32_e32 v101, 0x3fb8aa3b, v101
	v_exp_f32_e32 v100, v100
	v_exp_f32_e32 v101, v101
	v_or_b32_e32 v98, 32, v142
	v_ashrrev_i32_e32 v99, 31, v98
	v_lshlrev_b64 v[98:99], 14, v[98:99]
	v_pk_add_f32 v[100:101], v[100:101], 1.0 op_sel_hi:[1,0]
	s_nop 0
	s_nop 0
	v_rcp_f32_e32 v103, v101
	s_nop 0
	v_mul_f32_e32 v101, v95, v103
	s_nop 0
	v_rcp_f32_e32 v95, v100
	s_nop 0
	v_mul_f32_e32 v100, v94, v95
	v_mul_f32_e32 v94, 0x3d372713, v91
	v_mul_f32_e32 v94, v91, v94
	v_fma_f32 v94, v91, v94, v91
	v_mul_f32_e32 v94, 0xbfcc422a, v94
	v_mul_f32_e32 v94, 0x3fb8aa3b, v94
	v_exp_f32_e32 v103, v94
	s_nop 0
	v_pk_add_f32 v[94:95], v[102:103], 1.0 op_sel_hi:[1,0]
	s_nop 0
	s_nop 0
	v_rcp_f32_e32 v102, v95
	s_nop 0
	v_mul_f32_e32 v102, v91, v102
	s_nop 0
	v_rcp_f32_e32 v91, v94
	s_nop 0
	v_mul_f32_e32 v103, v90, v91
	v_mul_f32_e32 v91, 0x3d372713, v92
	v_mul_f32_e32 v91, v92, v91
	v_fma_f32 v91, v92, v91, v92
	v_mul_f32_e32 v91, 0xbfcc422a, v91
	v_mul_f32_e32 v91, 0x3fb8aa3b, v91
	v_mul_f32_e32 v90, 0x3d372713, v96
	v_exp_f32_e32 v94, v91
	v_mul_f32_e32 v91, 0x3d372713, v97
	v_mul_f32_e32 v90, v96, v90
	v_mul_f32_e32 v91, v97, v91
	v_fma_f32 v90, v96, v90, v96
	v_fma_f32 v91, v97, v91, v97
	v_mul_f32_e32 v90, 0xbfcc422a, v90
	v_mul_f32_e32 v91, 0xbfcc422a, v91
	v_mul_f32_e32 v90, 0x3fb8aa3b, v90
	v_mul_f32_e32 v91, 0x3fb8aa3b, v91
	v_exp_f32_e32 v90, v90
	v_exp_f32_e32 v91, v91
	s_nop 0
	v_pk_add_f32 v[90:91], v[90:91], 1.0 op_sel_hi:[1,0]
	s_nop 0
	s_nop 0
	v_rcp_f32_e32 v95, v91
	s_nop 0
	v_mul_f32_e32 v97, v97, v95
	s_nop 0
	v_rcp_f32_e32 v91, v90
	s_nop 0
	v_mul_f32_e32 v96, v96, v91
	v_mul_f32_e32 v90, 0x3d372713, v93
	v_mul_f32_e32 v90, v93, v90
	v_fma_f32 v90, v93, v90, v93
	v_mul_f32_e32 v90, 0xbfcc422a, v90
	v_mul_f32_e32 v90, 0x3fb8aa3b, v90
	v_exp_f32_e32 v95, v90
	s_nop 0
	v_pk_add_f32 v[90:91], v[94:95], 1.0 op_sel_hi:[1,0]
	s_nop 0
	s_nop 0
	v_rcp_f32_e32 v94, v91
	s_nop 0
	v_mul_f32_e32 v91, v93, v94
	s_nop 0
	v_rcp_f32_e32 v93, v90
	s_nop 0
	v_mul_f32_e32 v90, v92, v93
	v_cvt_pk_bf16_f32 v95, v90, v91
	v_lshl_add_u64 v[90:91], s[0:1], 0, v[98:99]
	v_cvt_pk_bf16_f32 v93, v96, v97
	v_lshl_add_u64 v[96:97], v[90:91], 0, v[124:125]
	v_lshl_add_u64 v[96:97], v[96:97], 0, s[10:11]
	v_cvt_pk_bf16_f32 v92, v100, v101
	v_cvt_pk_bf16_f32 v94, v103, v102
	v_lshl_add_u64 v[96:97], v[96:97], 0, v[48:49]
	global_store_dwordx4 v[96:97], v[92:95], off
	s_nop 1
	v_mul_f32_e32 v93, 0x3d372713, v82
	v_mul_f32_e32 v93, v82, v93
	v_fma_f32 v93, v82, v93, v82
	v_mul_f32_e32 v93, 0xbfcc422a, v93
	v_mul_f32_e32 v93, 0x3fb8aa3b, v93
	v_mul_f32_e32 v92, 0x3d372713, v86
	v_exp_f32_e32 v94, v93
	v_mul_f32_e32 v93, 0x3d372713, v87
	v_mul_f32_e32 v92, v86, v92
	v_mul_f32_e32 v93, v87, v93
	v_fma_f32 v92, v86, v92, v86
	v_fma_f32 v93, v87, v93, v87
	v_mul_f32_e32 v92, 0xbfcc422a, v92
	v_mul_f32_e32 v93, 0xbfcc422a, v93
	v_mul_f32_e32 v92, 0x3fb8aa3b, v92
	v_mul_f32_e32 v93, 0x3fb8aa3b, v93
	v_exp_f32_e32 v92, v92
	v_exp_f32_e32 v93, v93
	s_nop 0
	v_pk_add_f32 v[92:93], v[92:93], 1.0 op_sel_hi:[1,0]
	s_nop 0
	s_nop 0
	v_rcp_f32_e32 v95, v93
	s_nop 0
	v_mul_f32_e32 v93, v87, v95
	s_nop 0
	v_rcp_f32_e32 v87, v92
	s_nop 0
	v_mul_f32_e32 v92, v86, v87
	v_mul_f32_e32 v86, 0x3d372713, v83
	v_mul_f32_e32 v86, v83, v86
	v_fma_f32 v86, v83, v86, v83
	v_mul_f32_e32 v86, 0xbfcc422a, v86
	v_mul_f32_e32 v86, 0x3fb8aa3b, v86
	v_exp_f32_e32 v95, v86
	s_nop 0
	v_pk_add_f32 v[86:87], v[94:95], 1.0 op_sel_hi:[1,0]
	s_nop 0
	s_nop 0
	v_rcp_f32_e32 v94, v87
	s_nop 0
	v_mul_f32_e32 v94, v83, v94
	s_nop 0
	v_rcp_f32_e32 v83, v86
	s_nop 0
	v_mul_f32_e32 v95, v82, v83
	v_mul_f32_e32 v83, 0x3d372713, v84
	v_mul_f32_e32 v83, v84, v83
	v_fma_f32 v83, v84, v83, v84
	v_mul_f32_e32 v83, 0xbfcc422a, v83
	v_mul_f32_e32 v83, 0x3fb8aa3b, v83
	v_mul_f32_e32 v82, 0x3d372713, v88
	v_exp_f32_e32 v86, v83
	v_mul_f32_e32 v83, 0x3d372713, v89
	v_mul_f32_e32 v82, v88, v82
	v_mul_f32_e32 v83, v89, v83
	v_fma_f32 v82, v88, v82, v88
	v_fma_f32 v83, v89, v83, v89
	v_mul_f32_e32 v82, 0xbfcc422a, v82
	v_mul_f32_e32 v83, 0xbfcc422a, v83
	v_mul_f32_e32 v82, 0x3fb8aa3b, v82
	v_mul_f32_e32 v83, 0x3fb8aa3b, v83
	v_exp_f32_e32 v82, v82
	v_exp_f32_e32 v83, v83
	s_nop 0
	v_pk_add_f32 v[82:83], v[82:83], 1.0 op_sel_hi:[1,0]
	s_nop 0
	s_nop 0
	v_rcp_f32_e32 v87, v83
	s_nop 0
	v_mul_f32_e32 v89, v89, v87
	s_nop 0
	v_rcp_f32_e32 v83, v82
	s_nop 0
	v_mul_f32_e32 v88, v88, v83
	v_mul_f32_e32 v82, 0x3d372713, v85
	v_mul_f32_e32 v82, v85, v82
	v_fma_f32 v82, v85, v82, v85
	v_mul_f32_e32 v82, 0xbfcc422a, v82
	v_mul_f32_e32 v82, 0x3fb8aa3b, v82
	v_exp_f32_e32 v87, v82
	s_nop 0
	v_pk_add_f32 v[82:83], v[86:87], 1.0 op_sel_hi:[1,0]
	s_nop 0
	s_nop 0
	v_rcp_f32_e32 v86, v83
	s_nop 0
	v_mul_f32_e32 v85, v85, v86
	s_nop 0
	v_rcp_f32_e32 v83, v82
	s_nop 0
	v_mul_f32_e32 v86, v84, v83
	v_cvt_pk_bf16_f32 v85, v86, v85
	v_lshl_add_u64 v[86:87], v[90:91], 0, v[114:115]
	v_lshl_add_u64 v[86:87], v[86:87], 0, s[10:11]
	v_cvt_pk_bf16_f32 v82, v92, v93
	v_cvt_pk_bf16_f32 v83, v88, v89
	v_cvt_pk_bf16_f32 v84, v95, v94
	v_lshl_add_u64 v[86:87], v[86:87], 0, v[48:49]
	global_store_dwordx4 v[86:87], v[82:85], off
	s_nop 1
	v_mul_f32_e32 v85, 0x3d372713, v74
	v_mul_f32_e32 v85, v74, v85
	v_fma_f32 v85, v74, v85, v74
	v_mul_f32_e32 v85, 0xbfcc422a, v85
	v_mul_f32_e32 v85, 0x3fb8aa3b, v85
	v_mul_f32_e32 v84, 0x3d372713, v78
	v_exp_f32_e32 v86, v85
	v_mul_f32_e32 v85, 0x3d372713, v79
	v_mul_f32_e32 v84, v78, v84
	v_mul_f32_e32 v85, v79, v85
	v_fma_f32 v84, v78, v84, v78
	v_fma_f32 v85, v79, v85, v79
	v_mul_f32_e32 v84, 0xbfcc422a, v84
	v_mul_f32_e32 v85, 0xbfcc422a, v85
	v_mul_f32_e32 v84, 0x3fb8aa3b, v84
	v_mul_f32_e32 v85, 0x3fb8aa3b, v85
	v_exp_f32_e32 v84, v84
	v_exp_f32_e32 v85, v85
	v_or_b32_e32 v82, 48, v142
	v_ashrrev_i32_e32 v83, 31, v82
	v_lshlrev_b64 v[82:83], 14, v[82:83]
	v_pk_add_f32 v[84:85], v[84:85], 1.0 op_sel_hi:[1,0]
	s_nop 0
	s_nop 0
	v_rcp_f32_e32 v87, v85
	s_nop 0
	v_mul_f32_e32 v85, v79, v87
	s_nop 0
	v_rcp_f32_e32 v79, v84
	s_nop 0
	v_mul_f32_e32 v84, v78, v79
	v_mul_f32_e32 v78, 0x3d372713, v75
	v_mul_f32_e32 v78, v75, v78
	v_fma_f32 v78, v75, v78, v75
	v_mul_f32_e32 v78, 0xbfcc422a, v78
	v_mul_f32_e32 v78, 0x3fb8aa3b, v78
	v_exp_f32_e32 v87, v78
	s_nop 0
	v_pk_add_f32 v[78:79], v[86:87], 1.0 op_sel_hi:[1,0]
	s_nop 0
	s_nop 0
	v_rcp_f32_e32 v86, v79
	s_nop 0
	v_mul_f32_e32 v86, v75, v86
	s_nop 0
	v_rcp_f32_e32 v75, v78
	s_nop 0
	v_mul_f32_e32 v87, v74, v75
	v_mul_f32_e32 v75, 0x3d372713, v76
	v_mul_f32_e32 v75, v76, v75
	v_fma_f32 v75, v76, v75, v76
	v_mul_f32_e32 v75, 0xbfcc422a, v75
	v_mul_f32_e32 v75, 0x3fb8aa3b, v75
	v_mul_f32_e32 v74, 0x3d372713, v80
	v_exp_f32_e32 v78, v75
	v_mul_f32_e32 v75, 0x3d372713, v81
	v_mul_f32_e32 v74, v80, v74
	v_mul_f32_e32 v75, v81, v75
	v_fma_f32 v74, v80, v74, v80
	v_fma_f32 v75, v81, v75, v81
	v_mul_f32_e32 v74, 0xbfcc422a, v74
	v_mul_f32_e32 v75, 0xbfcc422a, v75
	v_mul_f32_e32 v74, 0x3fb8aa3b, v74
	v_mul_f32_e32 v75, 0x3fb8aa3b, v75
	v_exp_f32_e32 v74, v74
	v_exp_f32_e32 v75, v75
	s_nop 0
	v_pk_add_f32 v[74:75], v[74:75], 1.0 op_sel_hi:[1,0]
	s_nop 0
	s_nop 0
	v_rcp_f32_e32 v79, v75
	s_nop 0
	v_mul_f32_e32 v81, v81, v79
	s_nop 0
	v_rcp_f32_e32 v75, v74
	s_nop 0
	v_mul_f32_e32 v80, v80, v75
	v_mul_f32_e32 v74, 0x3d372713, v77
	v_mul_f32_e32 v74, v77, v74
	v_fma_f32 v74, v77, v74, v77
	v_mul_f32_e32 v74, 0xbfcc422a, v74
	v_mul_f32_e32 v74, 0x3fb8aa3b, v74
	v_exp_f32_e32 v79, v74
	s_nop 0
	v_pk_add_f32 v[74:75], v[78:79], 1.0 op_sel_hi:[1,0]
	s_nop 0
	s_nop 0
	v_rcp_f32_e32 v78, v75
	s_nop 0
	v_mul_f32_e32 v75, v77, v78
	s_nop 0
	v_rcp_f32_e32 v77, v74
	s_nop 0
	v_mul_f32_e32 v74, v76, v77
	v_cvt_pk_bf16_f32 v79, v74, v75
	v_lshl_add_u64 v[74:75], s[0:1], 0, v[82:83]
	v_cvt_pk_bf16_f32 v77, v80, v81
	v_lshl_add_u64 v[80:81], v[74:75], 0, v[124:125]
	v_lshl_add_u64 v[80:81], v[80:81], 0, s[10:11]
	v_cvt_pk_bf16_f32 v76, v84, v85
	v_cvt_pk_bf16_f32 v78, v87, v86
	v_lshl_add_u64 v[80:81], v[80:81], 0, v[48:49]
	global_store_dwordx4 v[80:81], v[76:79], off
	s_nop 1
	v_mul_f32_e32 v77, 0x3d372713, v66
	v_mul_f32_e32 v77, v66, v77
	v_fma_f32 v77, v66, v77, v66
	v_mul_f32_e32 v77, 0xbfcc422a, v77
	v_mul_f32_e32 v77, 0x3fb8aa3b, v77
	v_mul_f32_e32 v76, 0x3d372713, v70
	v_exp_f32_e32 v78, v77
	v_mul_f32_e32 v77, 0x3d372713, v71
	v_mul_f32_e32 v76, v70, v76
	v_mul_f32_e32 v77, v71, v77
	v_fma_f32 v76, v70, v76, v70
	v_fma_f32 v77, v71, v77, v71
	v_mul_f32_e32 v76, 0xbfcc422a, v76
	v_mul_f32_e32 v77, 0xbfcc422a, v77
	v_mul_f32_e32 v76, 0x3fb8aa3b, v76
	v_mul_f32_e32 v77, 0x3fb8aa3b, v77
	v_exp_f32_e32 v76, v76
	v_exp_f32_e32 v77, v77
	s_nop 0
	v_pk_add_f32 v[76:77], v[76:77], 1.0 op_sel_hi:[1,0]
	s_nop 0
	s_nop 0
	v_rcp_f32_e32 v79, v77
	s_nop 0
	v_mul_f32_e32 v77, v71, v79
	s_nop 0
	v_rcp_f32_e32 v71, v76
	s_nop 0
	v_mul_f32_e32 v76, v70, v71
	v_mul_f32_e32 v70, 0x3d372713, v67
	v_mul_f32_e32 v70, v67, v70
	v_fma_f32 v70, v67, v70, v67
	v_mul_f32_e32 v70, 0xbfcc422a, v70
	v_mul_f32_e32 v70, 0x3fb8aa3b, v70
	v_exp_f32_e32 v79, v70
	s_nop 0
	v_pk_add_f32 v[70:71], v[78:79], 1.0 op_sel_hi:[1,0]
	s_nop 0
	s_nop 0
	v_rcp_f32_e32 v78, v71
	s_nop 0
	v_mul_f32_e32 v78, v67, v78
	s_nop 0
	v_rcp_f32_e32 v67, v70
	s_nop 0
	v_mul_f32_e32 v79, v66, v67
	v_mul_f32_e32 v67, 0x3d372713, v68
	v_mul_f32_e32 v67, v68, v67
	v_fma_f32 v67, v68, v67, v68
	v_mul_f32_e32 v67, 0xbfcc422a, v67
	v_mul_f32_e32 v67, 0x3fb8aa3b, v67
	v_mul_f32_e32 v66, 0x3d372713, v72
	v_exp_f32_e32 v70, v67
	v_mul_f32_e32 v67, 0x3d372713, v73
	v_mul_f32_e32 v66, v72, v66
	v_mul_f32_e32 v67, v73, v67
	v_fma_f32 v66, v72, v66, v72
	v_fma_f32 v67, v73, v67, v73
	v_mul_f32_e32 v66, 0xbfcc422a, v66
	v_mul_f32_e32 v67, 0xbfcc422a, v67
	v_mul_f32_e32 v66, 0x3fb8aa3b, v66
	v_mul_f32_e32 v67, 0x3fb8aa3b, v67
	v_exp_f32_e32 v66, v66
	v_exp_f32_e32 v67, v67
	s_nop 0
	v_pk_add_f32 v[66:67], v[66:67], 1.0 op_sel_hi:[1,0]
	s_nop 0
	s_nop 0
	v_rcp_f32_e32 v71, v67
	s_nop 0
	v_mul_f32_e32 v73, v73, v71
	s_nop 0
	v_rcp_f32_e32 v67, v66
	s_nop 0
	v_mul_f32_e32 v72, v72, v67
	v_mul_f32_e32 v66, 0x3d372713, v69
	v_mul_f32_e32 v66, v69, v66
	v_fma_f32 v66, v69, v66, v69
	v_mul_f32_e32 v66, 0xbfcc422a, v66
	v_mul_f32_e32 v66, 0x3fb8aa3b, v66
	v_exp_f32_e32 v71, v66
	s_nop 0
	v_pk_add_f32 v[66:67], v[70:71], 1.0 op_sel_hi:[1,0]
	s_nop 0
	s_nop 0
	v_rcp_f32_e32 v70, v67
	s_nop 0
	v_mul_f32_e32 v69, v69, v70
	s_nop 0
	v_rcp_f32_e32 v67, v66
	s_nop 0
	v_mul_f32_e32 v70, v68, v67
	v_cvt_pk_bf16_f32 v69, v70, v69
	v_lshl_add_u64 v[70:71], v[74:75], 0, v[114:115]
	v_lshl_add_u64 v[70:71], v[70:71], 0, s[10:11]
	v_cvt_pk_bf16_f32 v66, v76, v77
	v_cvt_pk_bf16_f32 v67, v72, v73
	v_cvt_pk_bf16_f32 v68, v79, v78
	v_lshl_add_u64 v[70:71], v[70:71], 0, v[48:49]
	global_store_dwordx4 v[70:71], v[66:69], off
	s_nop 1
	v_mul_f32_e32 v67, 0x3d372713, v58
	v_mul_f32_e32 v67, v58, v67
	v_fma_f32 v67, v58, v67, v58
	v_mul_f32_e32 v67, 0xbfcc422a, v67
	v_mul_f32_e32 v67, 0x3fb8aa3b, v67
	v_mul_f32_e32 v66, 0x3d372713, v62
	v_exp_f32_e32 v68, v67
	v_mul_f32_e32 v67, 0x3d372713, v63
	v_mul_f32_e32 v66, v62, v66
	v_mul_f32_e32 v67, v63, v67
	v_fma_f32 v66, v62, v66, v62
	v_fma_f32 v67, v63, v67, v63
	v_mul_f32_e32 v66, 0xbfcc422a, v66
	v_mul_f32_e32 v67, 0xbfcc422a, v67
	v_mul_f32_e32 v66, 0x3fb8aa3b, v66
	v_mul_f32_e32 v67, 0x3fb8aa3b, v67
	v_exp_f32_e32 v66, v66
	v_exp_f32_e32 v67, v67
	s_nop 0
	v_pk_add_f32 v[66:67], v[66:67], 1.0 op_sel_hi:[1,0]
	s_nop 0
	s_nop 0
	v_rcp_f32_e32 v69, v67
	s_nop 0
	v_mul_f32_e32 v67, v63, v69
	s_nop 0
	v_rcp_f32_e32 v63, v66
	s_nop 0
	v_mul_f32_e32 v66, v62, v63
	v_mul_f32_e32 v62, 0x3d372713, v59
	v_mul_f32_e32 v62, v59, v62
	v_fma_f32 v62, v59, v62, v59
	v_mul_f32_e32 v62, 0xbfcc422a, v62
	v_mul_f32_e32 v62, 0x3fb8aa3b, v62
	v_exp_f32_e32 v69, v62
	s_nop 0
	v_pk_add_f32 v[62:63], v[68:69], 1.0 op_sel_hi:[1,0]
	s_nop 0
	s_nop 0
	v_rcp_f32_e32 v68, v63
	s_nop 0
	v_mul_f32_e32 v68, v59, v68
	s_nop 0
	v_rcp_f32_e32 v59, v62
	s_nop 0
	v_mul_f32_e32 v69, v58, v59
	v_mul_f32_e32 v59, 0x3d372713, v60
	v_mul_f32_e32 v59, v60, v59
	v_fma_f32 v59, v60, v59, v60
	v_mul_f32_e32 v59, 0xbfcc422a, v59
	v_mul_f32_e32 v59, 0x3fb8aa3b, v59
	v_mul_f32_e32 v58, 0x3d372713, v64
	v_exp_f32_e32 v62, v59
	v_mul_f32_e32 v59, 0x3d372713, v65
	v_mul_f32_e32 v58, v64, v58
	v_mul_f32_e32 v59, v65, v59
	v_fma_f32 v58, v64, v58, v64
	v_fma_f32 v59, v65, v59, v65
	v_mul_f32_e32 v58, 0xbfcc422a, v58
	v_mul_f32_e32 v59, 0xbfcc422a, v59
	v_mul_f32_e32 v58, 0x3fb8aa3b, v58
	v_mul_f32_e32 v59, 0x3fb8aa3b, v59
	v_exp_f32_e32 v58, v58
	v_exp_f32_e32 v59, v59
	s_nop 0
	v_pk_add_f32 v[58:59], v[58:59], 1.0 op_sel_hi:[1,0]
	s_nop 0
	s_nop 0
	v_rcp_f32_e32 v63, v59
	s_nop 0
	v_mul_f32_e32 v65, v65, v63
	s_nop 0
	v_rcp_f32_e32 v59, v58
	s_nop 0
	v_mul_f32_e32 v64, v64, v59
	v_mul_f32_e32 v58, 0x3d372713, v61
	v_mul_f32_e32 v58, v61, v58
	v_fma_f32 v58, v61, v58, v61
	v_mul_f32_e32 v58, 0xbfcc422a, v58
	v_mul_f32_e32 v58, 0x3fb8aa3b, v58
	v_exp_f32_e32 v63, v58
	s_nop 0
	v_pk_add_f32 v[58:59], v[62:63], 1.0 op_sel_hi:[1,0]
	s_nop 0
	s_nop 0
	v_rcp_f32_e32 v62, v59
	s_nop 0
	v_mul_f32_e32 v59, v61, v62
	s_mov_b64 s[12:13], 0x200000
	v_rcp_f32_e32 v61, v58
	s_nop 0
	v_mul_f32_e32 v58, v60, v61
	v_cvt_pk_bf16_f32 v63, v58, v59
	v_lshl_add_u64 v[58:59], v[122:123], 0, s[12:13]
	v_cvt_pk_bf16_f32 v61, v64, v65
	v_lshl_add_u64 v[64:65], v[58:59], 0, v[124:125]
	v_lshl_add_u64 v[64:65], v[64:65], 0, s[10:11]
	v_cvt_pk_bf16_f32 v60, v66, v67
	v_cvt_pk_bf16_f32 v62, v69, v68
	v_lshl_add_u64 v[64:65], v[64:65], 0, v[48:49]
	global_store_dwordx4 v[64:65], v[60:63], off
	s_nop 1
	v_mul_f32_e32 v61, 0x3d372713, v50
	v_mul_f32_e32 v61, v50, v61
	v_fma_f32 v61, v50, v61, v50
	v_mul_f32_e32 v61, 0xbfcc422a, v61
	v_mul_f32_e32 v61, 0x3fb8aa3b, v61
	v_mul_f32_e32 v60, 0x3d372713, v54
	v_exp_f32_e32 v62, v61
	v_mul_f32_e32 v61, 0x3d372713, v55
	v_mul_f32_e32 v60, v54, v60
	v_mul_f32_e32 v61, v55, v61
	v_fma_f32 v60, v54, v60, v54
	v_fma_f32 v61, v55, v61, v55
	v_mul_f32_e32 v60, 0xbfcc422a, v60
	v_mul_f32_e32 v61, 0xbfcc422a, v61
	v_mul_f32_e32 v60, 0x3fb8aa3b, v60
	v_mul_f32_e32 v61, 0x3fb8aa3b, v61
	v_exp_f32_e32 v60, v60
	v_exp_f32_e32 v61, v61
	s_nop 0
	v_pk_add_f32 v[60:61], v[60:61], 1.0 op_sel_hi:[1,0]
	s_nop 0
	s_nop 0
	v_rcp_f32_e32 v63, v61
	s_nop 0
	v_mul_f32_e32 v61, v55, v63
	s_nop 0
	v_rcp_f32_e32 v55, v60
	s_nop 0
	v_mul_f32_e32 v60, v54, v55
	v_mul_f32_e32 v54, 0x3d372713, v51
	v_mul_f32_e32 v54, v51, v54
	v_fma_f32 v54, v51, v54, v51
	v_mul_f32_e32 v54, 0xbfcc422a, v54
	v_mul_f32_e32 v54, 0x3fb8aa3b, v54
	v_exp_f32_e32 v63, v54
	s_nop 0
	v_pk_add_f32 v[54:55], v[62:63], 1.0 op_sel_hi:[1,0]
	s_nop 0
	s_nop 0
	v_rcp_f32_e32 v62, v55
	s_nop 0
	v_mul_f32_e32 v62, v51, v62
	s_nop 0
	v_rcp_f32_e32 v51, v54
	s_nop 0
	v_mul_f32_e32 v63, v50, v51
	v_mul_f32_e32 v51, 0x3d372713, v52
	v_mul_f32_e32 v51, v52, v51
	v_fma_f32 v51, v52, v51, v52
	v_mul_f32_e32 v51, 0xbfcc422a, v51
	v_mul_f32_e32 v51, 0x3fb8aa3b, v51
	v_mul_f32_e32 v50, 0x3d372713, v56
	v_exp_f32_e32 v54, v51
	v_mul_f32_e32 v51, 0x3d372713, v57
	v_mul_f32_e32 v50, v56, v50
	v_mul_f32_e32 v51, v57, v51
	v_fma_f32 v50, v56, v50, v56
	v_fma_f32 v51, v57, v51, v57
	v_mul_f32_e32 v50, 0xbfcc422a, v50
	v_mul_f32_e32 v51, 0xbfcc422a, v51
	v_mul_f32_e32 v50, 0x3fb8aa3b, v50
	v_mul_f32_e32 v51, 0x3fb8aa3b, v51
	v_exp_f32_e32 v50, v50
	v_exp_f32_e32 v51, v51
	s_nop 0
	v_pk_add_f32 v[50:51], v[50:51], 1.0 op_sel_hi:[1,0]
	s_nop 0
	s_nop 0
	v_rcp_f32_e32 v55, v51
	s_nop 0
	v_mul_f32_e32 v57, v57, v55
	s_nop 0
	v_rcp_f32_e32 v51, v50
	s_nop 0
	v_mul_f32_e32 v56, v56, v51
	v_mul_f32_e32 v50, 0x3d372713, v53
	v_mul_f32_e32 v50, v53, v50
	v_fma_f32 v50, v53, v50, v53
	v_mul_f32_e32 v50, 0xbfcc422a, v50
	v_mul_f32_e32 v50, 0x3fb8aa3b, v50
	v_exp_f32_e32 v55, v50
	s_nop 0
	v_pk_add_f32 v[50:51], v[54:55], 1.0 op_sel_hi:[1,0]
	s_nop 0
	s_nop 0
	v_rcp_f32_e32 v54, v51
	s_nop 0
	v_mul_f32_e32 v53, v53, v54
	s_nop 0
	v_rcp_f32_e32 v51, v50
	s_nop 0
	v_mul_f32_e32 v54, v52, v51
	v_cvt_pk_bf16_f32 v53, v54, v53
	v_lshl_add_u64 v[54:55], v[58:59], 0, v[114:115]
	v_lshl_add_u64 v[54:55], v[54:55], 0, s[10:11]
	v_cvt_pk_bf16_f32 v50, v60, v61
	v_cvt_pk_bf16_f32 v51, v56, v57
	v_cvt_pk_bf16_f32 v52, v63, v62
	v_lshl_add_u64 v[54:55], v[54:55], 0, v[48:49]
	global_store_dwordx4 v[54:55], v[50:53], off
	s_nop 1
	v_mul_f32_e32 v51, 0x3d372713, v40
	v_mul_f32_e32 v51, v40, v51
	v_fma_f32 v51, v40, v51, v40
	v_mul_f32_e32 v51, 0xbfcc422a, v51
	v_mul_f32_e32 v51, 0x3fb8aa3b, v51
	v_mul_f32_e32 v50, 0x3d372713, v44
	v_exp_f32_e32 v52, v51
	v_mul_f32_e32 v51, 0x3d372713, v45
	v_mul_f32_e32 v50, v44, v50
	v_mul_f32_e32 v51, v45, v51
	v_fma_f32 v50, v44, v50, v44
	v_fma_f32 v51, v45, v51, v45
	v_mul_f32_e32 v50, 0xbfcc422a, v50
	v_mul_f32_e32 v51, 0xbfcc422a, v51
	v_mul_f32_e32 v50, 0x3fb8aa3b, v50
	v_mul_f32_e32 v51, 0x3fb8aa3b, v51
	v_exp_f32_e32 v50, v50
	v_exp_f32_e32 v51, v51
	s_nop 0
	v_pk_add_f32 v[50:51], v[50:51], 1.0 op_sel_hi:[1,0]
	s_nop 0
	s_nop 0
	v_rcp_f32_e32 v53, v51
	s_nop 0
	v_mul_f32_e32 v51, v45, v53
	s_nop 0
	v_rcp_f32_e32 v45, v50
	s_nop 0
	v_mul_f32_e32 v50, v44, v45
	v_mul_f32_e32 v44, 0x3d372713, v41
	v_mul_f32_e32 v44, v41, v44
	v_fma_f32 v44, v41, v44, v41
	v_mul_f32_e32 v44, 0xbfcc422a, v44
	v_mul_f32_e32 v44, 0x3fb8aa3b, v44
	v_exp_f32_e32 v53, v44
	s_nop 0
	v_pk_add_f32 v[44:45], v[52:53], 1.0 op_sel_hi:[1,0]
	s_nop 0
	s_nop 0
	v_rcp_f32_e32 v52, v45
	s_nop 0
	v_mul_f32_e32 v52, v41, v52
	s_nop 0
	v_rcp_f32_e32 v41, v44
	s_nop 0
	v_mul_f32_e32 v53, v40, v41
	v_mul_f32_e32 v41, 0x3d372713, v42
	v_mul_f32_e32 v41, v42, v41
	v_fma_f32 v41, v42, v41, v42
	v_mul_f32_e32 v41, 0xbfcc422a, v41
	v_mul_f32_e32 v41, 0x3fb8aa3b, v41
	v_mul_f32_e32 v40, 0x3d372713, v46
	v_exp_f32_e32 v44, v41
	v_mul_f32_e32 v41, 0x3d372713, v47
	v_mul_f32_e32 v40, v46, v40
	v_mul_f32_e32 v41, v47, v41
	v_fma_f32 v40, v46, v40, v46
	v_fma_f32 v41, v47, v41, v47
	v_mul_f32_e32 v40, 0xbfcc422a, v40
	v_mul_f32_e32 v41, 0xbfcc422a, v41
	v_mul_f32_e32 v40, 0x3fb8aa3b, v40
	v_mul_f32_e32 v41, 0x3fb8aa3b, v41
	v_exp_f32_e32 v40, v40
	v_exp_f32_e32 v41, v41
	s_nop 0
	v_pk_add_f32 v[40:41], v[40:41], 1.0 op_sel_hi:[1,0]
	s_nop 0
	s_nop 0
	v_rcp_f32_e32 v45, v41
	s_nop 0
	v_mul_f32_e32 v47, v47, v45
	s_nop 0
	v_rcp_f32_e32 v41, v40
	s_nop 0
	v_mul_f32_e32 v46, v46, v41
	v_mul_f32_e32 v40, 0x3d372713, v43
	v_mul_f32_e32 v40, v43, v40
	v_fma_f32 v40, v43, v40, v43
	v_mul_f32_e32 v40, 0xbfcc422a, v40
	v_mul_f32_e32 v40, 0x3fb8aa3b, v40
	v_exp_f32_e32 v45, v40
	s_nop 0
	v_pk_add_f32 v[40:41], v[44:45], 1.0 op_sel_hi:[1,0]
	s_nop 0
	s_nop 0
	v_rcp_f32_e32 v44, v41
	s_nop 0
	v_mul_f32_e32 v41, v43, v44
	s_mov_b64 s[12:13], 0x240000
	v_rcp_f32_e32 v43, v40
	s_nop 0
	v_mul_f32_e32 v40, v42, v43
	v_cvt_pk_bf16_f32 v45, v40, v41
	v_lshl_add_u64 v[40:41], v[122:123], 0, s[12:13]
	v_cvt_pk_bf16_f32 v43, v46, v47
	v_lshl_add_u64 v[46:47], v[40:41], 0, v[124:125]
	v_lshl_add_u64 v[46:47], v[46:47], 0, s[10:11]
	v_cvt_pk_bf16_f32 v42, v50, v51
	v_cvt_pk_bf16_f32 v44, v53, v52
	v_lshl_add_u64 v[46:47], v[46:47], 0, v[48:49]
	global_store_dwordx4 v[46:47], v[42:45], off
	s_nop 1
	v_mul_f32_e32 v43, 0x3d372713, v32
	v_mul_f32_e32 v43, v32, v43
	v_fma_f32 v43, v32, v43, v32
	v_mul_f32_e32 v43, 0xbfcc422a, v43
	v_mul_f32_e32 v43, 0x3fb8aa3b, v43
	v_mul_f32_e32 v42, 0x3d372713, v36
	v_exp_f32_e32 v44, v43
	v_mul_f32_e32 v43, 0x3d372713, v37
	v_mul_f32_e32 v42, v36, v42
	v_mul_f32_e32 v43, v37, v43
	v_fma_f32 v42, v36, v42, v36
	v_fma_f32 v43, v37, v43, v37
	v_mul_f32_e32 v42, 0xbfcc422a, v42
	v_mul_f32_e32 v43, 0xbfcc422a, v43
	v_mul_f32_e32 v42, 0x3fb8aa3b, v42
	v_mul_f32_e32 v43, 0x3fb8aa3b, v43
	v_exp_f32_e32 v42, v42
	v_exp_f32_e32 v43, v43
	s_nop 0
	v_pk_add_f32 v[42:43], v[42:43], 1.0 op_sel_hi:[1,0]
	s_nop 0
	s_nop 0
	v_rcp_f32_e32 v45, v43
	s_nop 0
	v_mul_f32_e32 v43, v37, v45
	s_nop 0
	v_rcp_f32_e32 v37, v42
	s_nop 0
	v_mul_f32_e32 v42, v36, v37
	v_mul_f32_e32 v36, 0x3d372713, v33
	v_mul_f32_e32 v36, v33, v36
	v_fma_f32 v36, v33, v36, v33
	v_mul_f32_e32 v36, 0xbfcc422a, v36
	v_mul_f32_e32 v36, 0x3fb8aa3b, v36
	v_exp_f32_e32 v45, v36
	s_nop 0
	v_pk_add_f32 v[36:37], v[44:45], 1.0 op_sel_hi:[1,0]
	s_nop 0
	s_nop 0
	v_rcp_f32_e32 v44, v37
	s_nop 0
	v_mul_f32_e32 v44, v33, v44
	s_nop 0
	v_rcp_f32_e32 v33, v36
	s_nop 0
	v_mul_f32_e32 v45, v32, v33
	v_mul_f32_e32 v33, 0x3d372713, v34
	v_mul_f32_e32 v33, v34, v33
	v_fma_f32 v33, v34, v33, v34
	v_mul_f32_e32 v33, 0xbfcc422a, v33
	v_mul_f32_e32 v33, 0x3fb8aa3b, v33
	v_mul_f32_e32 v32, 0x3d372713, v38
	v_exp_f32_e32 v36, v33
	v_mul_f32_e32 v33, 0x3d372713, v39
	v_mul_f32_e32 v32, v38, v32
	v_mul_f32_e32 v33, v39, v33
	v_fma_f32 v32, v38, v32, v38
	v_fma_f32 v33, v39, v33, v39
	v_mul_f32_e32 v32, 0xbfcc422a, v32
	v_mul_f32_e32 v33, 0xbfcc422a, v33
	v_mul_f32_e32 v32, 0x3fb8aa3b, v32
	v_mul_f32_e32 v33, 0x3fb8aa3b, v33
	v_exp_f32_e32 v32, v32
	v_exp_f32_e32 v33, v33
	s_nop 0
	v_pk_add_f32 v[32:33], v[32:33], 1.0 op_sel_hi:[1,0]
	s_nop 0
	s_nop 0
	v_rcp_f32_e32 v37, v33
	s_nop 0
	v_mul_f32_e32 v39, v39, v37
	s_nop 0
	v_rcp_f32_e32 v33, v32
	s_nop 0
	v_mul_f32_e32 v38, v38, v33
	v_mul_f32_e32 v32, 0x3d372713, v35
	v_mul_f32_e32 v32, v35, v32
	v_fma_f32 v32, v35, v32, v35
	v_mul_f32_e32 v32, 0xbfcc422a, v32
	v_mul_f32_e32 v32, 0x3fb8aa3b, v32
	v_exp_f32_e32 v37, v32
	s_nop 0
	v_pk_add_f32 v[32:33], v[36:37], 1.0 op_sel_hi:[1,0]
	s_nop 0
	s_nop 0
	v_rcp_f32_e32 v36, v33
	s_nop 0
	v_mul_f32_e32 v35, v35, v36
	s_nop 0
	v_rcp_f32_e32 v33, v32
	s_nop 0
	v_mul_f32_e32 v36, v34, v33
	v_cvt_pk_bf16_f32 v35, v36, v35
	v_lshl_add_u64 v[36:37], v[40:41], 0, v[114:115]
	v_lshl_add_u64 v[36:37], v[36:37], 0, s[10:11]
	v_cvt_pk_bf16_f32 v32, v42, v43
	v_cvt_pk_bf16_f32 v33, v38, v39
	v_cvt_pk_bf16_f32 v34, v45, v44
	v_lshl_add_u64 v[36:37], v[36:37], 0, v[48:49]
	global_store_dwordx4 v[36:37], v[32:35], off
	s_nop 1
	v_mul_f32_e32 v33, 0x3d372713, v24
	v_mul_f32_e32 v33, v24, v33
	v_fma_f32 v33, v24, v33, v24
	v_mul_f32_e32 v33, 0xbfcc422a, v33
	v_mul_f32_e32 v33, 0x3fb8aa3b, v33
	v_mul_f32_e32 v32, 0x3d372713, v28
	v_exp_f32_e32 v34, v33
	v_mul_f32_e32 v33, 0x3d372713, v29
	v_mul_f32_e32 v32, v28, v32
	v_mul_f32_e32 v33, v29, v33
	v_fma_f32 v32, v28, v32, v28
	v_fma_f32 v33, v29, v33, v29
	v_mul_f32_e32 v32, 0xbfcc422a, v32
	v_mul_f32_e32 v33, 0xbfcc422a, v33
	v_mul_f32_e32 v32, 0x3fb8aa3b, v32
	v_mul_f32_e32 v33, 0x3fb8aa3b, v33
	v_exp_f32_e32 v32, v32
	v_exp_f32_e32 v33, v33
	s_nop 0
	v_pk_add_f32 v[32:33], v[32:33], 1.0 op_sel_hi:[1,0]
	s_nop 0
	s_nop 0
	v_rcp_f32_e32 v35, v33
	s_nop 0
	v_mul_f32_e32 v33, v29, v35
	s_nop 0
	v_rcp_f32_e32 v29, v32
	s_nop 0
	v_mul_f32_e32 v32, v28, v29
	v_mul_f32_e32 v28, 0x3d372713, v25
	v_mul_f32_e32 v28, v25, v28
	v_fma_f32 v28, v25, v28, v25
	v_mul_f32_e32 v28, 0xbfcc422a, v28
	v_mul_f32_e32 v28, 0x3fb8aa3b, v28
	v_exp_f32_e32 v35, v28
	s_nop 0
	v_pk_add_f32 v[28:29], v[34:35], 1.0 op_sel_hi:[1,0]
	s_nop 0
	s_nop 0
	v_rcp_f32_e32 v34, v29
	s_nop 0
	v_mul_f32_e32 v34, v25, v34
	s_nop 0
	v_rcp_f32_e32 v25, v28
	s_nop 0
	v_mul_f32_e32 v35, v24, v25
	v_mul_f32_e32 v25, 0x3d372713, v26
	v_mul_f32_e32 v25, v26, v25
	v_fma_f32 v25, v26, v25, v26
	v_mul_f32_e32 v25, 0xbfcc422a, v25
	v_mul_f32_e32 v25, 0x3fb8aa3b, v25
	v_mul_f32_e32 v24, 0x3d372713, v30
	v_exp_f32_e32 v28, v25
	v_mul_f32_e32 v25, 0x3d372713, v31
	v_mul_f32_e32 v24, v30, v24
	v_mul_f32_e32 v25, v31, v25
	v_fma_f32 v24, v30, v24, v30
	v_fma_f32 v25, v31, v25, v31
	v_mul_f32_e32 v24, 0xbfcc422a, v24
	v_mul_f32_e32 v25, 0xbfcc422a, v25
	v_mul_f32_e32 v24, 0x3fb8aa3b, v24
	v_mul_f32_e32 v25, 0x3fb8aa3b, v25
	v_exp_f32_e32 v24, v24
	v_exp_f32_e32 v25, v25
	s_nop 0
	v_pk_add_f32 v[24:25], v[24:25], 1.0 op_sel_hi:[1,0]
	s_nop 0
	s_nop 0
	v_rcp_f32_e32 v29, v25
	s_nop 0
	v_mul_f32_e32 v31, v31, v29
	s_nop 0
	v_rcp_f32_e32 v25, v24
	s_nop 0
	v_mul_f32_e32 v30, v30, v25
	v_mul_f32_e32 v24, 0x3d372713, v27
	v_mul_f32_e32 v24, v27, v24
	v_fma_f32 v24, v27, v24, v27
	v_mul_f32_e32 v24, 0xbfcc422a, v24
	v_mul_f32_e32 v24, 0x3fb8aa3b, v24
	v_exp_f32_e32 v29, v24
	s_nop 0
	v_pk_add_f32 v[24:25], v[28:29], 1.0 op_sel_hi:[1,0]
	s_nop 0
	s_nop 0
	v_rcp_f32_e32 v28, v25
	s_nop 0
	v_mul_f32_e32 v25, v27, v28
	s_mov_b64 s[12:13], 0x280000
	v_rcp_f32_e32 v27, v24
	s_nop 0
	v_mul_f32_e32 v24, v26, v27
	v_cvt_pk_bf16_f32 v29, v24, v25
	v_lshl_add_u64 v[24:25], v[122:123], 0, s[12:13]
	v_cvt_pk_bf16_f32 v27, v30, v31
	v_lshl_add_u64 v[30:31], v[24:25], 0, v[124:125]
	v_lshl_add_u64 v[30:31], v[30:31], 0, s[10:11]
	v_cvt_pk_bf16_f32 v26, v32, v33
	v_cvt_pk_bf16_f32 v28, v35, v34
	v_lshl_add_u64 v[30:31], v[30:31], 0, v[48:49]
	global_store_dwordx4 v[30:31], v[26:29], off
	s_nop 1
	v_mul_f32_e32 v27, 0x3d372713, v16
	v_mul_f32_e32 v27, v16, v27
	v_fma_f32 v27, v16, v27, v16
	v_mul_f32_e32 v27, 0xbfcc422a, v27
	v_mul_f32_e32 v27, 0x3fb8aa3b, v27
	v_mul_f32_e32 v26, 0x3d372713, v20
	v_exp_f32_e32 v28, v27
	v_mul_f32_e32 v27, 0x3d372713, v21
	v_mul_f32_e32 v26, v20, v26
	v_mul_f32_e32 v27, v21, v27
	v_fma_f32 v26, v20, v26, v20
	v_fma_f32 v27, v21, v27, v21
	v_mul_f32_e32 v26, 0xbfcc422a, v26
	v_mul_f32_e32 v27, 0xbfcc422a, v27
	v_mul_f32_e32 v26, 0x3fb8aa3b, v26
	v_mul_f32_e32 v27, 0x3fb8aa3b, v27
	v_exp_f32_e32 v26, v26
	v_exp_f32_e32 v27, v27
	s_nop 0
	v_pk_add_f32 v[26:27], v[26:27], 1.0 op_sel_hi:[1,0]
	s_nop 0
	s_nop 0
	v_rcp_f32_e32 v29, v27
	s_nop 0
	v_mul_f32_e32 v27, v21, v29
	s_nop 0
	v_rcp_f32_e32 v21, v26
	s_nop 0
	v_mul_f32_e32 v26, v20, v21
	v_mul_f32_e32 v20, 0x3d372713, v17
	v_mul_f32_e32 v20, v17, v20
	v_fma_f32 v20, v17, v20, v17
	v_mul_f32_e32 v20, 0xbfcc422a, v20
	v_mul_f32_e32 v20, 0x3fb8aa3b, v20
	v_exp_f32_e32 v29, v20
	s_nop 0
	v_pk_add_f32 v[20:21], v[28:29], 1.0 op_sel_hi:[1,0]
	s_nop 0
	s_nop 0
	v_rcp_f32_e32 v28, v21
	s_nop 0
	v_mul_f32_e32 v28, v17, v28
	s_nop 0
	v_rcp_f32_e32 v17, v20
	s_nop 0
	v_mul_f32_e32 v29, v16, v17
	v_mul_f32_e32 v17, 0x3d372713, v18
	v_mul_f32_e32 v17, v18, v17
	v_fma_f32 v17, v18, v17, v18
	v_mul_f32_e32 v17, 0xbfcc422a, v17
	v_mul_f32_e32 v17, 0x3fb8aa3b, v17
	v_mul_f32_e32 v16, 0x3d372713, v22
	v_exp_f32_e32 v20, v17
	v_mul_f32_e32 v17, 0x3d372713, v23
	v_mul_f32_e32 v16, v22, v16
	v_mul_f32_e32 v17, v23, v17
	v_fma_f32 v16, v22, v16, v22
	v_fma_f32 v17, v23, v17, v23
	v_mul_f32_e32 v16, 0xbfcc422a, v16
	v_mul_f32_e32 v17, 0xbfcc422a, v17
	v_mul_f32_e32 v16, 0x3fb8aa3b, v16
	v_mul_f32_e32 v17, 0x3fb8aa3b, v17
	v_exp_f32_e32 v16, v16
	v_exp_f32_e32 v17, v17
	s_nop 0
	v_pk_add_f32 v[16:17], v[16:17], 1.0 op_sel_hi:[1,0]
	s_nop 0
	s_nop 0
	v_rcp_f32_e32 v21, v17
	s_nop 0
	v_mul_f32_e32 v23, v23, v21
	s_nop 0
	v_rcp_f32_e32 v17, v16
	s_nop 0
	v_mul_f32_e32 v22, v22, v17
	v_mul_f32_e32 v16, 0x3d372713, v19
	v_mul_f32_e32 v16, v19, v16
	v_fma_f32 v16, v19, v16, v19
	v_mul_f32_e32 v16, 0xbfcc422a, v16
	v_mul_f32_e32 v16, 0x3fb8aa3b, v16
	v_exp_f32_e32 v21, v16
	s_nop 0
	v_pk_add_f32 v[16:17], v[20:21], 1.0 op_sel_hi:[1,0]
	s_nop 0
	s_nop 0
	v_rcp_f32_e32 v20, v17
	s_nop 0
	v_mul_f32_e32 v19, v19, v20
	s_nop 0
	v_rcp_f32_e32 v17, v16
	s_nop 0
	v_mul_f32_e32 v20, v18, v17
	v_cvt_pk_bf16_f32 v19, v20, v19
	v_lshl_add_u64 v[20:21], v[24:25], 0, v[114:115]
	v_lshl_add_u64 v[20:21], v[20:21], 0, s[10:11]
	v_cvt_pk_bf16_f32 v16, v26, v27
	v_cvt_pk_bf16_f32 v17, v22, v23
	v_cvt_pk_bf16_f32 v18, v29, v28
	v_lshl_add_u64 v[20:21], v[20:21], 0, v[48:49]
	global_store_dwordx4 v[20:21], v[16:19], off
	s_nop 1
	v_mul_f32_e32 v17, 0x3d372713, v8
	v_mul_f32_e32 v17, v8, v17
	v_fma_f32 v17, v8, v17, v8
	v_mul_f32_e32 v17, 0xbfcc422a, v17
	v_mul_f32_e32 v17, 0x3fb8aa3b, v17
	v_mul_f32_e32 v16, 0x3d372713, v12
	v_exp_f32_e32 v18, v17
	v_mul_f32_e32 v17, 0x3d372713, v13
	v_mul_f32_e32 v16, v12, v16
	v_mul_f32_e32 v17, v13, v17
	v_fma_f32 v16, v12, v16, v12
	v_fma_f32 v17, v13, v17, v13
	v_mul_f32_e32 v16, 0xbfcc422a, v16
	v_mul_f32_e32 v17, 0xbfcc422a, v17
	v_mul_f32_e32 v16, 0x3fb8aa3b, v16
	v_mul_f32_e32 v17, 0x3fb8aa3b, v17
	v_exp_f32_e32 v16, v16
	v_exp_f32_e32 v17, v17
	s_nop 0
	v_pk_add_f32 v[16:17], v[16:17], 1.0 op_sel_hi:[1,0]
	s_nop 0
	s_nop 0
	v_rcp_f32_e32 v19, v17
	s_nop 0
	v_mul_f32_e32 v17, v13, v19
	s_nop 0
	v_rcp_f32_e32 v13, v16
	s_nop 0
	v_mul_f32_e32 v16, v12, v13
	v_mul_f32_e32 v12, 0x3d372713, v9
	v_mul_f32_e32 v12, v9, v12
	v_fma_f32 v12, v9, v12, v9
	v_mul_f32_e32 v12, 0xbfcc422a, v12
	v_mul_f32_e32 v12, 0x3fb8aa3b, v12
	v_exp_f32_e32 v19, v12
	s_nop 0
	v_pk_add_f32 v[12:13], v[18:19], 1.0 op_sel_hi:[1,0]
	s_nop 0
	s_nop 0
	v_rcp_f32_e32 v18, v13
	s_nop 0
	v_mul_f32_e32 v18, v9, v18
	s_nop 0
	v_rcp_f32_e32 v9, v12
	s_nop 0
	v_mul_f32_e32 v19, v8, v9
	v_mul_f32_e32 v9, 0x3d372713, v10
	v_mul_f32_e32 v9, v10, v9
	v_fma_f32 v9, v10, v9, v10
	v_mul_f32_e32 v9, 0xbfcc422a, v9
	v_mul_f32_e32 v9, 0x3fb8aa3b, v9
	v_mul_f32_e32 v8, 0x3d372713, v14
	v_exp_f32_e32 v12, v9
	v_mul_f32_e32 v9, 0x3d372713, v15
	v_mul_f32_e32 v8, v14, v8
	v_mul_f32_e32 v9, v15, v9
	v_fma_f32 v8, v14, v8, v14
	v_fma_f32 v9, v15, v9, v15
	v_mul_f32_e32 v8, 0xbfcc422a, v8
	v_mul_f32_e32 v9, 0xbfcc422a, v9
	v_mul_f32_e32 v8, 0x3fb8aa3b, v8
	v_mul_f32_e32 v9, 0x3fb8aa3b, v9
	v_exp_f32_e32 v8, v8
	v_exp_f32_e32 v9, v9
	s_nop 0
	v_pk_add_f32 v[8:9], v[8:9], 1.0 op_sel_hi:[1,0]
	s_nop 0
	s_nop 0
	v_rcp_f32_e32 v13, v9
	s_nop 0
	v_mul_f32_e32 v15, v15, v13
	s_nop 0
	v_rcp_f32_e32 v9, v8
	s_nop 0
	v_mul_f32_e32 v14, v14, v9
	v_mul_f32_e32 v8, 0x3d372713, v11
	v_mul_f32_e32 v8, v11, v8
	v_fma_f32 v8, v11, v8, v11
	v_mul_f32_e32 v8, 0xbfcc422a, v8
	v_mul_f32_e32 v8, 0x3fb8aa3b, v8
	v_exp_f32_e32 v13, v8
	s_nop 0
	v_pk_add_f32 v[8:9], v[12:13], 1.0 op_sel_hi:[1,0]
	s_nop 0
	s_nop 0
	v_rcp_f32_e32 v12, v9
	s_nop 0
	v_mul_f32_e32 v9, v11, v12
	s_mov_b64 s[12:13], 0x2c0000
	v_rcp_f32_e32 v11, v8
	s_nop 0
	v_mul_f32_e32 v8, v10, v11
	v_cvt_pk_bf16_f32 v13, v8, v9
	v_lshl_add_u64 v[8:9], v[122:123], 0, s[12:13]
	v_cvt_pk_bf16_f32 v11, v14, v15
	v_lshl_add_u64 v[14:15], v[8:9], 0, v[124:125]
	v_lshl_add_u64 v[14:15], v[14:15], 0, s[10:11]
	v_cvt_pk_bf16_f32 v10, v16, v17
	v_cvt_pk_bf16_f32 v12, v19, v18
	v_lshl_add_u64 v[14:15], v[14:15], 0, v[48:49]
	global_store_dwordx4 v[14:15], v[10:13], off
	s_nop 1
	v_mul_f32_e32 v11, 0x3d372713, v0
	v_mul_f32_e32 v11, v0, v11
	v_fma_f32 v11, v0, v11, v0
	v_mul_f32_e32 v11, 0xbfcc422a, v11
	v_mul_f32_e32 v11, 0x3fb8aa3b, v11
	v_mul_f32_e32 v10, 0x3d372713, v4
	v_exp_f32_e32 v12, v11
	v_mul_f32_e32 v11, 0x3d372713, v5
	v_mul_f32_e32 v10, v4, v10
	v_mul_f32_e32 v11, v5, v11
	v_fma_f32 v10, v4, v10, v4
	v_fma_f32 v11, v5, v11, v5
	v_mul_f32_e32 v10, 0xbfcc422a, v10
	v_mul_f32_e32 v11, 0xbfcc422a, v11
	v_mul_f32_e32 v10, 0x3fb8aa3b, v10
	v_mul_f32_e32 v11, 0x3fb8aa3b, v11
	v_exp_f32_e32 v10, v10
	v_exp_f32_e32 v11, v11
	s_nop 0
	v_pk_add_f32 v[10:11], v[10:11], 1.0 op_sel_hi:[1,0]
	s_nop 0
	s_nop 0
	v_rcp_f32_e32 v13, v11
	s_nop 0
	v_mul_f32_e32 v11, v5, v13
	s_nop 0
	v_rcp_f32_e32 v5, v10
	s_nop 0
	v_mul_f32_e32 v10, v4, v5
	v_mul_f32_e32 v4, 0x3d372713, v1
	v_mul_f32_e32 v4, v1, v4
	v_fma_f32 v4, v1, v4, v1
	v_mul_f32_e32 v4, 0xbfcc422a, v4
	v_mul_f32_e32 v4, 0x3fb8aa3b, v4
	v_exp_f32_e32 v13, v4
	s_nop 0
	v_pk_add_f32 v[4:5], v[12:13], 1.0 op_sel_hi:[1,0]
	s_nop 0
	s_nop 0
	v_rcp_f32_e32 v12, v5
	s_nop 0
	v_mul_f32_e32 v12, v1, v12
	s_nop 0
	v_rcp_f32_e32 v1, v4
	s_nop 0
	v_mul_f32_e32 v13, v0, v1
	v_mul_f32_e32 v1, 0x3d372713, v2
	v_mul_f32_e32 v1, v2, v1
	v_fma_f32 v1, v2, v1, v2
	v_mul_f32_e32 v1, 0xbfcc422a, v1
	v_mul_f32_e32 v1, 0x3fb8aa3b, v1
	v_mul_f32_e32 v0, 0x3d372713, v6
	v_exp_f32_e32 v4, v1
	v_mul_f32_e32 v1, 0x3d372713, v7
	v_mul_f32_e32 v0, v6, v0
	v_mul_f32_e32 v1, v7, v1
	v_fma_f32 v0, v6, v0, v6
	v_fma_f32 v1, v7, v1, v7
	v_mul_f32_e32 v0, 0xbfcc422a, v0
	v_mul_f32_e32 v1, 0xbfcc422a, v1
	v_mul_f32_e32 v0, 0x3fb8aa3b, v0
	v_mul_f32_e32 v1, 0x3fb8aa3b, v1
	v_exp_f32_e32 v0, v0
	v_exp_f32_e32 v1, v1
	s_nop 0
	v_pk_add_f32 v[0:1], v[0:1], 1.0 op_sel_hi:[1,0]
	s_nop 0
	s_nop 0
	v_rcp_f32_e32 v5, v1
	s_nop 0
	v_mul_f32_e32 v7, v7, v5
	s_nop 0
	v_rcp_f32_e32 v1, v0
	s_nop 0
	v_mul_f32_e32 v6, v6, v1
	v_mul_f32_e32 v0, 0x3d372713, v3
	v_mul_f32_e32 v0, v3, v0
	v_fma_f32 v0, v3, v0, v3
	v_mul_f32_e32 v0, 0xbfcc422a, v0
	v_mul_f32_e32 v0, 0x3fb8aa3b, v0
	v_exp_f32_e32 v5, v0
	s_nop 0
	v_pk_add_f32 v[0:1], v[4:5], 1.0 op_sel_hi:[1,0]
	s_nop 0
	s_nop 0
	v_rcp_f32_e32 v4, v1
	s_nop 0
	v_mul_f32_e32 v3, v3, v4
	s_mov_b64 s[12:13], s[6:7]
	v_rcp_f32_e32 v1, v0
	s_nop 0
	v_mul_f32_e32 v4, v2, v1
	v_cvt_pk_bf16_f32 v3, v4, v3
	v_lshl_add_u64 v[4:5], v[8:9], 0, v[114:115]
	v_lshl_add_u64 v[4:5], v[4:5], 0, s[10:11]
	v_cvt_pk_bf16_f32 v0, v10, v11
	v_cvt_pk_bf16_f32 v1, v6, v7
	v_cvt_pk_bf16_f32 v2, v13, v12
	v_lshl_add_u64 v[4:5], v[4:5], 0, v[48:49]
	s_and_b64 vcc, exec, s[8:9]
	s_mov_b64 s[10:11], s[4:5]
	global_store_dwordx4 v[4:5], v[0:3], off
	s_cbranch_vccz .LBB0_819
	s_waitcnt vmcnt(0)
	s_cmpk_gt_u32 s18, 0xff
	s_cbranch_scc1 .LBB0_826
	s_barrier

.LBB0_1056:
	s_add_i32 s56, s28, 2
	s_add_u32 s29, s24, 0xfffc0080
	s_addc_u32 s30, s25, -1
	s_add_i32 s57, 0, 0x10000
	v_add_u32_e32 v142, s57, v216
	ds_read_b128 v[130:133], v142
	ds_read_b128 v[134:137], v142 offset:1024
	ds_read_b128 v[138:141], v142 offset:2048
	ds_read_b128 v[142:145], v142 offset:3072
	s_cmp_eq_u32 s17, s28
	s_cselect_b32 s28, s22, s19
	s_cselect_b32 s31, s21, s30
	s_cselect_b32 s30, s20, s29
	s_cselect_b32 s29, s23, s27
	s_add_i32 m0, s39, 0xc000
	ds_read_b128 v[146:149], v217
	ds_read_b128 v[150:153], v217 offset:1024
	ds_read_b128 v[154:157], v217 offset:2048
	ds_read_b128 v[158:161], v217 offset:3072
	ds_read_b128 v[162:165], v217 offset:4096
	ds_read_b128 v[166:169], v217 offset:5120
	ds_read_b128 v[170:173], v217 offset:6144
	ds_read_b128 v[174:177], v217 offset:7168
	global_load_lds_dwordx4 v204, s[24:25]
	s_add_i32 m0, s39, 0xe000
	s_nop 0
	global_load_lds_dwordx4 v206, s[24:25]
	s_waitcnt lgkmcnt(8)
	s_barrier
	s_waitcnt lgkmcnt(0)
	s_setprio 1
	s_waitcnt lgkmcnt(0)
	v_mfma_f32_16x16x32_bf16 v[126:129], v[130:133], v[146:149], v[126:129]
	v_mfma_f32_16x16x32_bf16 v[122:125], v[138:141], v[146:149], v[122:125]
	v_mfma_f32_16x16x32_bf16 v[118:121], v[130:133], v[154:157], v[118:121]
	v_mfma_f32_16x16x32_bf16 v[114:117], v[138:141], v[154:157], v[114:117]
	v_mfma_f32_16x16x32_bf16 v[102:105], v[130:133], v[162:165], v[102:105]
	v_mfma_f32_16x16x32_bf16 v[98:101], v[138:141], v[162:165], v[98:101]
	v_mfma_f32_16x16x32_bf16 v[86:89], v[130:133], v[170:173], v[86:89]
	v_mfma_f32_16x16x32_bf16 v[82:85], v[138:141], v[170:173], v[82:85]
	v_mfma_f32_16x16x32_bf16 v[126:129], v[134:137], v[150:153], v[126:129]
	v_mfma_f32_16x16x32_bf16 v[122:125], v[142:145], v[150:153], v[122:125]
	v_mfma_f32_16x16x32_bf16 v[118:121], v[134:137], v[158:161], v[118:121]
	v_mfma_f32_16x16x32_bf16 v[114:117], v[142:145], v[158:161], v[114:117]
	v_mfma_f32_16x16x32_bf16 v[102:105], v[134:137], v[166:169], v[102:105]
	v_mfma_f32_16x16x32_bf16 v[98:101], v[142:145], v[166:169], v[98:101]
	v_mfma_f32_16x16x32_bf16 v[86:89], v[134:137], v[174:177], v[86:89]
	v_mfma_f32_16x16x32_bf16 v[82:85], v[142:145], v[174:177], v[82:85]
	s_setprio 0
	s_barrier
	s_add_i32 s60, 0, 0x14000
	s_add_i32 s57, s57, s38
	v_add_u32_e32 v190, s60, v216
	v_lshl_add_u64 v[208:209], s[28:29], 0, v[48:49]
	s_mov_b32 m0, s57
	ds_read_b128 v[178:181], v190
	ds_read_b128 v[182:185], v190 offset:1024
	ds_read_b128 v[186:189], v190 offset:2048
	ds_read_b128 v[190:193], v190 offset:3072
	global_load_lds_dwordx4 v[208:209], off
	v_lshl_add_u64 v[210:211], s[28:29], 0, v[202:203]
	s_add_i32 m0, s57, 0x2000
	s_nop 0
	global_load_lds_dwordx4 v[210:211], off
	s_barrier
	s_waitcnt lgkmcnt(0)
	s_setprio 1
	s_waitcnt lgkmcnt(0)
	v_mfma_f32_16x16x32_bf16 v[110:113], v[178:181], v[146:149], v[110:113]
	v_mfma_f32_16x16x32_bf16 v[106:109], v[186:189], v[146:149], v[106:109]
	v_mfma_f32_16x16x32_bf16 v[94:97], v[178:181], v[154:157], v[94:97]
	v_mfma_f32_16x16x32_bf16 v[90:93], v[186:189], v[154:157], v[90:93]
	v_mfma_f32_16x16x32_bf16 v[78:81], v[178:181], v[162:165], v[78:81]
	v_mfma_f32_16x16x32_bf16 v[74:77], v[186:189], v[162:165], v[74:77]
	v_mfma_f32_16x16x32_bf16 v[70:73], v[178:181], v[170:173], v[70:73]
	v_mfma_f32_16x16x32_bf16 v[66:69], v[186:189], v[170:173], v[66:69]
	v_mfma_f32_16x16x32_bf16 v[110:113], v[182:185], v[150:153], v[110:113]
	v_mfma_f32_16x16x32_bf16 v[106:109], v[190:193], v[150:153], v[106:109]
	v_mfma_f32_16x16x32_bf16 v[94:97], v[182:185], v[158:161], v[94:97]
	v_mfma_f32_16x16x32_bf16 v[90:93], v[190:193], v[158:161], v[90:93]
	v_mfma_f32_16x16x32_bf16 v[78:81], v[182:185], v[166:169], v[78:81]
	v_mfma_f32_16x16x32_bf16 v[74:77], v[190:193], v[166:169], v[74:77]
	v_mfma_f32_16x16x32_bf16 v[70:73], v[182:185], v[174:177], v[70:73]
	v_mfma_f32_16x16x32_bf16 v[66:69], v[190:193], v[174:177], v[66:69]
	s_setprio 0
	s_mov_b32 m0, s39
	v_lshl_add_u64 v[212:213], s[30:31], 0, v[198:199]
	s_barrier
	ds_read_b128 v[146:149], v217 offset:16384
	ds_read_b128 v[150:153], v217 offset:17408
	ds_read_b128 v[154:157], v217 offset:18432
	ds_read_b128 v[158:161], v217 offset:19456
	ds_read_b128 v[162:165], v217 offset:20480
	ds_read_b128 v[166:169], v217 offset:21504
	ds_read_b128 v[170:173], v217 offset:22528
	ds_read_b128 v[174:177], v217 offset:23552
	global_load_lds_dwordx4 v[212:213], off
	v_lshl_add_u64 v[218:219], s[30:31], 0, v[200:201]
	s_mov_b32 m0, s40
	s_nop 0
	global_load_lds_dwordx4 v[218:219], off
	s_barrier
	s_waitcnt lgkmcnt(0)
	s_setprio 1
	s_waitcnt lgkmcnt(0)
	v_mfma_f32_16x16x32_bf16 v[62:65], v[130:133], v[146:149], v[62:65]
	v_mfma_f32_16x16x32_bf16 v[58:61], v[138:141], v[146:149], v[58:61]
	v_mfma_f32_16x16x32_bf16 v[54:57], v[130:133], v[154:157], v[54:57]
	v_mfma_f32_16x16x32_bf16 v[50:53], v[138:141], v[154:157], v[50:53]
	v_mfma_f32_16x16x32_bf16 v[36:39], v[130:133], v[162:165], v[36:39]
	v_mfma_f32_16x16x32_bf16 v[32:35], v[138:141], v[162:165], v[32:35]
	v_mfma_f32_16x16x32_bf16 v[20:23], v[130:133], v[170:173], v[20:23]
	v_mfma_f32_16x16x32_bf16 v[16:19], v[138:141], v[170:173], v[16:19]
	v_mfma_f32_16x16x32_bf16 v[62:65], v[134:137], v[150:153], v[62:65]
	v_mfma_f32_16x16x32_bf16 v[58:61], v[142:145], v[150:153], v[58:61]
	v_mfma_f32_16x16x32_bf16 v[54:57], v[134:137], v[158:161], v[54:57]
	v_mfma_f32_16x16x32_bf16 v[50:53], v[142:145], v[158:161], v[50:53]
	v_mfma_f32_16x16x32_bf16 v[36:39], v[134:137], v[166:169], v[36:39]
	v_mfma_f32_16x16x32_bf16 v[32:35], v[142:145], v[166:169], v[32:35]
	v_mfma_f32_16x16x32_bf16 v[20:23], v[134:137], v[174:177], v[20:23]
	v_mfma_f32_16x16x32_bf16 v[16:19], v[142:145], v[174:177], v[16:19]
	s_setprio 0
	s_barrier
	s_add_u32 s58, s28, 0x40000
	s_addc_u32 s59, s29, 0
	s_add_i32 s57, s60, s38
	v_lshl_add_u64 v[130:131], s[58:59], 0, v[48:49]
	s_mov_b32 m0, s57
	s_nop 0
	global_load_lds_dwordx4 v[130:131], off
	s_add_i32 m0, s57, 0x2000
	s_nop 0
	global_load_lds_dwordx4 v202, s[58:59]
	s_waitcnt vmcnt(6)
	s_barrier
	s_setprio 1
	v_mfma_f32_16x16x32_bf16 v[44:47], v[178:181], v[146:149], v[44:47]
	v_mfma_f32_16x16x32_bf16 v[40:43], v[186:189], v[146:149], v[40:43]
	v_mfma_f32_16x16x32_bf16 v[28:31], v[178:181], v[154:157], v[28:31]
	v_mfma_f32_16x16x32_bf16 v[24:27], v[186:189], v[154:157], v[24:27]
	v_mfma_f32_16x16x32_bf16 v[12:15], v[178:181], v[162:165], v[12:15]
	v_mfma_f32_16x16x32_bf16 v[8:11], v[186:189], v[162:165], v[8:11]
	v_mfma_f32_16x16x32_bf16 v[4:7], v[178:181], v[170:173], v[4:7]
	v_mfma_f32_16x16x32_bf16 v[0:3], v[186:189], v[170:173], v[0:3]
	v_mfma_f32_16x16x32_bf16 v[44:47], v[182:185], v[150:153], v[44:47]
	v_mfma_f32_16x16x32_bf16 v[40:43], v[190:193], v[150:153], v[40:43]
	v_mfma_f32_16x16x32_bf16 v[28:31], v[182:185], v[158:161], v[28:31]
	v_mfma_f32_16x16x32_bf16 v[24:27], v[190:193], v[158:161], v[24:27]
	v_mfma_f32_16x16x32_bf16 v[12:15], v[182:185], v[166:169], v[12:15]
	v_mfma_f32_16x16x32_bf16 v[8:11], v[190:193], v[166:169], v[8:11]
	v_mfma_f32_16x16x32_bf16 v[4:7], v[182:185], v[174:177], v[4:7]
	v_mfma_f32_16x16x32_bf16 v[0:3], v[190:193], v[174:177], v[0:3]
	s_setprio 0
	s_add_i32 s57, 0, 0x18000
	v_add_u32_e32 v142, s57, v216
	s_barrier
	ds_read_b128 v[130:133], v142
	ds_read_b128 v[134:137], v142 offset:1024
	ds_read_b128 v[138:141], v142 offset:2048
	ds_read_b128 v[142:145], v142 offset:3072
	s_add_u32 s30, s30, 0x40000
	s_addc_u32 s31, s31, 0
	s_mov_b32 m0, s41
	ds_read_b128 v[146:149], v217 offset:32768
	ds_read_b128 v[150:153], v217 offset:33792
	ds_read_b128 v[154:157], v217 offset:34816
	ds_read_b128 v[158:161], v217 offset:35840
	ds_read_b128 v[162:165], v217 offset:36864
	ds_read_b128 v[166:169], v217 offset:37888
	ds_read_b128 v[170:173], v217 offset:38912
	ds_read_b128 v[174:177], v217 offset:39936
	global_load_lds_dwordx4 v198, s[30:31]
	s_mov_b32 m0, s42
	s_nop 0
	global_load_lds_dwordx4 v200, s[30:31]
	s_waitcnt lgkmcnt(8)
	s_barrier
	s_waitcnt lgkmcnt(0)
	s_setprio 1
	s_waitcnt lgkmcnt(0)
	v_mfma_f32_16x16x32_bf16 v[126:129], v[130:133], v[146:149], v[126:129]
	v_mfma_f32_16x16x32_bf16 v[122:125], v[138:141], v[146:149], v[122:125]
	v_mfma_f32_16x16x32_bf16 v[118:121], v[130:133], v[154:157], v[118:121]
	v_mfma_f32_16x16x32_bf16 v[114:117], v[138:141], v[154:157], v[114:117]
	v_mfma_f32_16x16x32_bf16 v[102:105], v[130:133], v[162:165], v[102:105]
	v_mfma_f32_16x16x32_bf16 v[98:101], v[138:141], v[162:165], v[98:101]
	v_mfma_f32_16x16x32_bf16 v[86:89], v[130:133], v[170:173], v[86:89]
	v_mfma_f32_16x16x32_bf16 v[82:85], v[138:141], v[170:173], v[82:85]
	v_mfma_f32_16x16x32_bf16 v[126:129], v[134:137], v[150:153], v[126:129]
	v_mfma_f32_16x16x32_bf16 v[122:125], v[142:145], v[150:153], v[122:125]
	v_mfma_f32_16x16x32_bf16 v[118:121], v[134:137], v[158:161], v[118:121]
	v_mfma_f32_16x16x32_bf16 v[114:117], v[142:145], v[158:161], v[114:117]
	v_mfma_f32_16x16x32_bf16 v[102:105], v[134:137], v[166:169], v[102:105]
	v_mfma_f32_16x16x32_bf16 v[98:101], v[142:145], v[166:169], v[98:101]
	v_mfma_f32_16x16x32_bf16 v[86:89], v[134:137], v[174:177], v[86:89]
	v_mfma_f32_16x16x32_bf16 v[82:85], v[142:145], v[174:177], v[82:85]
	s_setprio 0
	s_barrier
	s_add_i32 s30, 0, 0x1c000
	s_add_i32 s31, s57, s38
	v_add_u32_e32 v190, s30, v216
	v_lshl_add_u64 v[208:209], v[208:209], 0, s[66:67]
	s_mov_b32 m0, s31
	ds_read_b128 v[178:181], v190
	ds_read_b128 v[182:185], v190 offset:1024
	ds_read_b128 v[186:189], v190 offset:2048
	ds_read_b128 v[190:193], v190 offset:3072
	global_load_lds_dwordx4 v[208:209], off
	v_lshl_add_u64 v[208:209], v[210:211], 0, s[66:67]
	s_add_i32 m0, s31, 0x2000
	s_nop 0
	global_load_lds_dwordx4 v[208:209], off
	s_barrier
	s_waitcnt lgkmcnt(0)
	s_setprio 1
	s_waitcnt lgkmcnt(0)
	v_mfma_f32_16x16x32_bf16 v[110:113], v[178:181], v[146:149], v[110:113]
	v_mfma_f32_16x16x32_bf16 v[106:109], v[186:189], v[146:149], v[106:109]
	v_mfma_f32_16x16x32_bf16 v[94:97], v[178:181], v[154:157], v[94:97]
	v_mfma_f32_16x16x32_bf16 v[90:93], v[186:189], v[154:157], v[90:93]
	v_mfma_f32_16x16x32_bf16 v[78:81], v[178:181], v[162:165], v[78:81]
	v_mfma_f32_16x16x32_bf16 v[74:77], v[186:189], v[162:165], v[74:77]
	v_mfma_f32_16x16x32_bf16 v[70:73], v[178:181], v[170:173], v[70:73]
	v_mfma_f32_16x16x32_bf16 v[66:69], v[186:189], v[170:173], v[66:69]
	v_mfma_f32_16x16x32_bf16 v[110:113], v[182:185], v[150:153], v[110:113]
	v_mfma_f32_16x16x32_bf16 v[106:109], v[190:193], v[150:153], v[106:109]
	v_mfma_f32_16x16x32_bf16 v[94:97], v[182:185], v[158:161], v[94:97]
	v_mfma_f32_16x16x32_bf16 v[90:93], v[190:193], v[158:161], v[90:93]
	v_mfma_f32_16x16x32_bf16 v[78:81], v[182:185], v[166:169], v[78:81]
	v_mfma_f32_16x16x32_bf16 v[74:77], v[190:193], v[166:169], v[74:77]
	v_mfma_f32_16x16x32_bf16 v[70:73], v[182:185], v[174:177], v[70:73]
	v_mfma_f32_16x16x32_bf16 v[66:69], v[190:193], v[174:177], v[66:69]
	s_setprio 0
	s_mov_b32 m0, s49
	v_lshl_add_u64 v[208:209], v[212:213], 0, s[66:67]
	s_barrier
	ds_read_b128 v[146:149], v217 offset:49152
	ds_read_b128 v[150:153], v217 offset:50176
	ds_read_b128 v[154:157], v217 offset:51200
	ds_read_b128 v[158:161], v217 offset:52224
	ds_read_b128 v[162:165], v217 offset:53248
	ds_read_b128 v[166:169], v217 offset:54272
	ds_read_b128 v[170:173], v217 offset:55296
	ds_read_b128 v[174:177], v217 offset:56320
	global_load_lds_dwordx4 v[208:209], off
	v_lshl_add_u64 v[208:209], v[218:219], 0, s[66:67]
	s_mov_b32 m0, s50
	s_nop 0
	global_load_lds_dwordx4 v[208:209], off
	s_barrier
	s_waitcnt lgkmcnt(0)
	s_setprio 1
	s_waitcnt lgkmcnt(0)
	v_mfma_f32_16x16x32_bf16 v[62:65], v[130:133], v[146:149], v[62:65]
	v_mfma_f32_16x16x32_bf16 v[58:61], v[138:141], v[146:149], v[58:61]
	v_mfma_f32_16x16x32_bf16 v[54:57], v[130:133], v[154:157], v[54:57]
	v_mfma_f32_16x16x32_bf16 v[50:53], v[138:141], v[154:157], v[50:53]
	v_mfma_f32_16x16x32_bf16 v[36:39], v[130:133], v[162:165], v[36:39]
	v_mfma_f32_16x16x32_bf16 v[32:35], v[138:141], v[162:165], v[32:35]
	v_mfma_f32_16x16x32_bf16 v[20:23], v[130:133], v[170:173], v[20:23]
	v_mfma_f32_16x16x32_bf16 v[16:19], v[138:141], v[170:173], v[16:19]
	v_mfma_f32_16x16x32_bf16 v[62:65], v[134:137], v[150:153], v[62:65]
	v_mfma_f32_16x16x32_bf16 v[58:61], v[142:145], v[150:153], v[58:61]
	v_mfma_f32_16x16x32_bf16 v[54:57], v[134:137], v[158:161], v[54:57]
	v_mfma_f32_16x16x32_bf16 v[50:53], v[142:145], v[158:161], v[50:53]
	v_mfma_f32_16x16x32_bf16 v[36:39], v[134:137], v[166:169], v[36:39]
	v_mfma_f32_16x16x32_bf16 v[32:35], v[142:145], v[166:169], v[32:35]
	v_mfma_f32_16x16x32_bf16 v[20:23], v[134:137], v[174:177], v[20:23]
	v_mfma_f32_16x16x32_bf16 v[16:19], v[142:145], v[174:177], v[16:19]
	s_setprio 0
	s_barrier
	s_add_u32 s28, s28, 0x40080
	s_addc_u32 s29, s29, 0
	s_add_i32 s30, s30, s38
	v_lshl_add_u64 v[130:131], s[28:29], 0, v[48:49]
	s_mov_b32 m0, s30
	s_nop 0
	global_load_lds_dwordx4 v[130:131], off
	s_add_i32 m0, s30, 0x2000
	s_nop 0
	global_load_lds_dwordx4 v202, s[28:29]
	s_waitcnt vmcnt(6)
	s_barrier
	s_setprio 1
	v_mfma_f32_16x16x32_bf16 v[44:47], v[178:181], v[146:149], v[44:47]
	v_mfma_f32_16x16x32_bf16 v[40:43], v[186:189], v[146:149], v[40:43]
	v_mfma_f32_16x16x32_bf16 v[28:31], v[178:181], v[154:157], v[28:31]
	v_mfma_f32_16x16x32_bf16 v[24:27], v[186:189], v[154:157], v[24:27]
	v_mfma_f32_16x16x32_bf16 v[12:15], v[178:181], v[162:165], v[12:15]
	v_mfma_f32_16x16x32_bf16 v[8:11], v[186:189], v[162:165], v[8:11]
	v_mfma_f32_16x16x32_bf16 v[4:7], v[178:181], v[170:173], v[4:7]
	v_mfma_f32_16x16x32_bf16 v[0:3], v[186:189], v[170:173], v[0:3]
	v_mfma_f32_16x16x32_bf16 v[44:47], v[182:185], v[150:153], v[44:47]
	v_mfma_f32_16x16x32_bf16 v[40:43], v[190:193], v[150:153], v[40:43]
	v_mfma_f32_16x16x32_bf16 v[28:31], v[182:185], v[158:161], v[28:31]
	v_mfma_f32_16x16x32_bf16 v[24:27], v[190:193], v[158:161], v[24:27]
	v_mfma_f32_16x16x32_bf16 v[12:15], v[182:185], v[166:169], v[12:15]
	v_mfma_f32_16x16x32_bf16 v[8:11], v[190:193], v[166:169], v[8:11]
	v_mfma_f32_16x16x32_bf16 v[4:7], v[182:185], v[174:177], v[4:7]
	v_mfma_f32_16x16x32_bf16 v[0:3], v[190:193], v[174:177], v[0:3]
	s_setprio 0
	s_add_u32 s24, s24, 0x100
	s_addc_u32 s25, s25, 0
	s_add_u32 s19, s19, 0x100
	s_addc_u32 s27, s27, 0
	s_cmp_ge_i32 s56, s1
	s_mov_b32 s28, s56
	s_barrier
	s_cbranch_scc0 .LBB0_1056
	v_mov_b32_e32 v130, v214
	v_mov_b32_e32 v131, v215
	s_bitcmp1_b32 s55, 0
	v_add_u32_e32 v134, s47, v130
	v_lshlrev_b32_e32 v130, 8, v134
	v_lshl_add_u32 v132, v131, 3, s48
	v_ashrrev_i32_e32 v131, 31, v130
	v_lshl_add_u64 v[130:131], v[130:131], 1, s[12:13]
	v_ashrrev_i32_e32 v133, 31, v132
	s_cselect_b64 s[28:29], -1, 0
	v_lshlrev_b32_e32 v208, 9, v215
	v_lshl_add_u32 v208, v214, 4, v208
	v_lshl_add_u32 v208, s47, 9, v208
	v_lshl_add_u32 v208, s48, 6, v208
	v_mov_b32_e32 v209, 0
	v_lshl_add_u64 v[208:209], v[208:209], 0, s[12:13]
	s_mov_b64 s[24:25], -1
	s_and_b64 vcc, exec, s[28:29]
	s_mov_b32 s57, s81
	s_cbranch_vccz .LBB0_1093
	s_mov_b64 s[24:25], 0x20000
	v_lshl_add_u64 v[130:131], v[208:209], 0, s[24:25]
	s_and_b32 s1, s55, -2
	s_mov_b64 s[24:25], 0x100
	s_cmp_lg_u32 s1, 4
	v_mov_b64_e32 v[210:211], v[130:131]
	s_cbranch_scc1 .LBB0_1060
	v_lshl_add_u32 v134, s26, 8, v134
	v_ashrrev_i32_e32 v135, 31, v134
	v_lshlrev_b64 v[134:135], 11, v[134:135]
	s_lshl_b32 s0, s0, 8
	v_lshl_add_u64 v[134:135], s[14:15], 0, v[134:135]
	s_ashr_i32 s1, s0, 31
	v_lshl_add_u64 v[134:135], s[0:1], 1, v[134:135]
	v_lshl_add_u64 v[210:211], v[132:133], 1, v[134:135]
	s_mov_b64 s[24:25], 0x400

.LBB0_1219:
	s_add_u32 s26, s24, 0xfffc0080
	s_addc_u32 s27, s25, -1
	s_add_i32 s31, 0, 0x10000
	v_add_u32_e32 v142, s31, v208
	ds_read_b128 v[130:133], v142
	ds_read_b128 v[134:137], v142 offset:1024
	ds_read_b128 v[138:141], v142 offset:2048
	ds_read_b128 v[142:145], v142 offset:3072
	s_cmp_eq_u32 s30, 12
	s_cselect_b32 s29, s19, s27
	s_cselect_b32 s28, s18, s26
	s_cselect_b32 s27, s21, s17
	s_cselect_b32 s26, s20, s15
	s_add_i32 m0, s41, 0xc000
	ds_read_b128 v[146:149], v210
	ds_read_b128 v[150:153], v210 offset:1024
	ds_read_b128 v[154:157], v210 offset:2048
	ds_read_b128 v[158:161], v210 offset:3072
	ds_read_b128 v[162:165], v210 offset:4096
	ds_read_b128 v[166:169], v210 offset:5120
	ds_read_b128 v[170:173], v210 offset:6144
	ds_read_b128 v[174:177], v210 offset:7168
	global_load_lds_dwordx4 v200, s[24:25]
	s_add_i32 m0, s41, 0xe000
	s_nop 0
	global_load_lds_dwordx4 v202, s[24:25]
	s_waitcnt lgkmcnt(8)
	s_barrier
	s_waitcnt lgkmcnt(0)
	s_setprio 1
	s_waitcnt lgkmcnt(0)
	v_mfma_f32_16x16x32_bf16 v[126:129], v[130:133], v[146:149], v[126:129]
	v_mfma_f32_16x16x32_bf16 v[122:125], v[138:141], v[146:149], v[122:125]
	v_mfma_f32_16x16x32_bf16 v[118:121], v[130:133], v[154:157], v[118:121]
	v_mfma_f32_16x16x32_bf16 v[106:109], v[138:141], v[154:157], v[106:109]
	v_mfma_f32_16x16x32_bf16 v[94:97], v[130:133], v[162:165], v[94:97]
	v_mfma_f32_16x16x32_bf16 v[90:93], v[138:141], v[162:165], v[90:93]
	v_mfma_f32_16x16x32_bf16 v[86:89], v[130:133], v[170:173], v[86:89]
	v_mfma_f32_16x16x32_bf16 v[74:77], v[138:141], v[170:173], v[74:77]
	v_mfma_f32_16x16x32_bf16 v[126:129], v[134:137], v[150:153], v[126:129]
	v_mfma_f32_16x16x32_bf16 v[122:125], v[142:145], v[150:153], v[122:125]
	v_mfma_f32_16x16x32_bf16 v[118:121], v[134:137], v[158:161], v[118:121]
	v_mfma_f32_16x16x32_bf16 v[106:109], v[142:145], v[158:161], v[106:109]
	v_mfma_f32_16x16x32_bf16 v[94:97], v[134:137], v[166:169], v[94:97]
	v_mfma_f32_16x16x32_bf16 v[90:93], v[142:145], v[166:169], v[90:93]
	v_mfma_f32_16x16x32_bf16 v[86:89], v[134:137], v[174:177], v[86:89]
	v_mfma_f32_16x16x32_bf16 v[74:77], v[142:145], v[174:177], v[74:77]
	s_setprio 0
	s_barrier
	s_add_i32 s50, 0, 0x14000
	s_add_i32 s31, s31, s40
	v_add_u32_e32 v204, s50, v208
	v_lshl_add_u64 v[212:213], s[26:27], 0, v[48:49]
	s_mov_b32 m0, s31
	ds_read_b128 v[178:181], v204
	ds_read_b128 v[182:185], v204 offset:1024
	ds_read_b128 v[186:189], v204 offset:2048
	ds_read_b128 v[204:207], v204 offset:3072
	global_load_lds_dwordx4 v[212:213], off
	v_lshl_add_u64 v[214:215], s[26:27], 0, v[190:191]
	s_add_i32 m0, s31, 0x2000
	s_nop 0
	global_load_lds_dwordx4 v[214:215], off
	s_barrier
	s_waitcnt lgkmcnt(0)
	s_setprio 1
	s_waitcnt lgkmcnt(0)
	v_mfma_f32_16x16x32_bf16 v[114:117], v[178:181], v[146:149], v[114:117]
	v_mfma_f32_16x16x32_bf16 v[110:113], v[186:189], v[146:149], v[110:113]
	v_mfma_f32_16x16x32_bf16 v[102:105], v[178:181], v[154:157], v[102:105]
	v_mfma_f32_16x16x32_bf16 v[98:101], v[186:189], v[154:157], v[98:101]
	v_mfma_f32_16x16x32_bf16 v[82:85], v[178:181], v[162:165], v[82:85]
	v_mfma_f32_16x16x32_bf16 v[78:81], v[186:189], v[162:165], v[78:81]
	v_mfma_f32_16x16x32_bf16 v[70:73], v[178:181], v[170:173], v[70:73]
	v_mfma_f32_16x16x32_bf16 v[66:69], v[186:189], v[170:173], v[66:69]
	v_mfma_f32_16x16x32_bf16 v[114:117], v[182:185], v[150:153], v[114:117]
	v_mfma_f32_16x16x32_bf16 v[110:113], v[204:207], v[150:153], v[110:113]
	v_mfma_f32_16x16x32_bf16 v[102:105], v[182:185], v[158:161], v[102:105]
	v_mfma_f32_16x16x32_bf16 v[98:101], v[204:207], v[158:161], v[98:101]
	v_mfma_f32_16x16x32_bf16 v[82:85], v[182:185], v[166:169], v[82:85]
	v_mfma_f32_16x16x32_bf16 v[78:81], v[204:207], v[166:169], v[78:81]
	v_mfma_f32_16x16x32_bf16 v[70:73], v[182:185], v[174:177], v[70:73]
	v_mfma_f32_16x16x32_bf16 v[66:69], v[204:207], v[174:177], v[66:69]
	s_setprio 0
	s_mov_b32 m0, s41
	v_lshl_add_u64 v[216:217], s[28:29], 0, v[48:49]
	s_barrier
	ds_read_b128 v[146:149], v210 offset:16384
	ds_read_b128 v[150:153], v210 offset:17408
	ds_read_b128 v[154:157], v210 offset:18432
	ds_read_b128 v[158:161], v210 offset:19456
	ds_read_b128 v[162:165], v210 offset:20480
	ds_read_b128 v[166:169], v210 offset:21504
	ds_read_b128 v[170:173], v210 offset:22528
	ds_read_b128 v[174:177], v210 offset:23552
	global_load_lds_dwordx4 v[216:217], off
	v_lshl_add_u64 v[218:219], s[28:29], 0, v[190:191]
	s_mov_b32 m0, s42
	s_nop 0
	global_load_lds_dwordx4 v[218:219], off
	s_barrier
	s_waitcnt lgkmcnt(0)
	s_setprio 1
	s_waitcnt lgkmcnt(0)
	v_mfma_f32_16x16x32_bf16 v[62:65], v[130:133], v[146:149], v[62:65]
	v_mfma_f32_16x16x32_bf16 v[58:61], v[138:141], v[146:149], v[58:61]
	v_mfma_f32_16x16x32_bf16 v[54:57], v[130:133], v[154:157], v[54:57]
	v_mfma_f32_16x16x32_bf16 v[40:43], v[138:141], v[154:157], v[40:43]
	v_mfma_f32_16x16x32_bf16 v[36:39], v[130:133], v[162:165], v[36:39]
	v_mfma_f32_16x16x32_bf16 v[24:27], v[138:141], v[162:165], v[24:27]
	v_mfma_f32_16x16x32_bf16 v[20:23], v[130:133], v[170:173], v[20:23]
	v_mfma_f32_16x16x32_bf16 v[8:11], v[138:141], v[170:173], v[8:11]
	v_mfma_f32_16x16x32_bf16 v[62:65], v[134:137], v[150:153], v[62:65]
	v_mfma_f32_16x16x32_bf16 v[58:61], v[142:145], v[150:153], v[58:61]
	v_mfma_f32_16x16x32_bf16 v[54:57], v[134:137], v[158:161], v[54:57]
	v_mfma_f32_16x16x32_bf16 v[40:43], v[142:145], v[158:161], v[40:43]
	v_mfma_f32_16x16x32_bf16 v[36:39], v[134:137], v[166:169], v[36:39]
	v_mfma_f32_16x16x32_bf16 v[24:27], v[142:145], v[166:169], v[24:27]
	v_mfma_f32_16x16x32_bf16 v[20:23], v[134:137], v[174:177], v[20:23]
	v_mfma_f32_16x16x32_bf16 v[8:11], v[142:145], v[174:177], v[8:11]
	s_setprio 0
	s_barrier
	s_add_u32 s34, s26, 0x40000
	s_addc_u32 s35, s27, 0
	s_add_i32 s31, s50, s40
	v_lshl_add_u64 v[130:131], s[34:35], 0, v[48:49]
	s_mov_b32 m0, s31
	s_nop 0
	global_load_lds_dwordx4 v[130:131], off
	s_add_i32 m0, s31, 0x2000
	s_nop 0
	global_load_lds_dwordx4 v190, s[34:35]
	s_waitcnt vmcnt(6)
	s_barrier
	s_setprio 1
	v_mfma_f32_16x16x32_bf16 v[50:53], v[178:181], v[146:149], v[50:53]
	v_mfma_f32_16x16x32_bf16 v[44:47], v[186:189], v[146:149], v[44:47]
	v_mfma_f32_16x16x32_bf16 v[32:35], v[178:181], v[154:157], v[32:35]
	v_mfma_f32_16x16x32_bf16 v[28:31], v[186:189], v[154:157], v[28:31]
	v_mfma_f32_16x16x32_bf16 v[16:19], v[178:181], v[162:165], v[16:19]
	v_mfma_f32_16x16x32_bf16 v[12:15], v[186:189], v[162:165], v[12:15]
	v_mfma_f32_16x16x32_bf16 v[4:7], v[178:181], v[170:173], v[4:7]
	v_mfma_f32_16x16x32_bf16 v[0:3], v[186:189], v[170:173], v[0:3]
	v_mfma_f32_16x16x32_bf16 v[50:53], v[182:185], v[150:153], v[50:53]
	v_mfma_f32_16x16x32_bf16 v[44:47], v[204:207], v[150:153], v[44:47]
	v_mfma_f32_16x16x32_bf16 v[32:35], v[182:185], v[158:161], v[32:35]
	v_mfma_f32_16x16x32_bf16 v[28:31], v[204:207], v[158:161], v[28:31]
	v_mfma_f32_16x16x32_bf16 v[16:19], v[182:185], v[166:169], v[16:19]
	v_mfma_f32_16x16x32_bf16 v[12:15], v[204:207], v[166:169], v[12:15]
	v_mfma_f32_16x16x32_bf16 v[4:7], v[182:185], v[174:177], v[4:7]
	v_mfma_f32_16x16x32_bf16 v[0:3], v[204:207], v[174:177], v[0:3]
	s_setprio 0
	s_add_i32 s31, 0, 0x18000
	v_add_u32_e32 v142, s31, v208
	s_barrier
	ds_read_b128 v[130:133], v142
	ds_read_b128 v[134:137], v142 offset:1024
	ds_read_b128 v[138:141], v142 offset:2048
	ds_read_b128 v[142:145], v142 offset:3072
	s_add_u32 s28, s28, 0x40000
	s_addc_u32 s29, s29, 0
	s_mov_b32 m0, s43
	v_lshl_add_u64 v[178:179], s[28:29], 0, v[48:49]
	ds_read_b128 v[146:149], v210 offset:32768
	ds_read_b128 v[150:153], v210 offset:33792
	ds_read_b128 v[154:157], v210 offset:34816
	ds_read_b128 v[158:161], v210 offset:35840
	ds_read_b128 v[162:165], v210 offset:36864
	ds_read_b128 v[166:169], v210 offset:37888
	ds_read_b128 v[170:173], v210 offset:38912
	ds_read_b128 v[174:177], v210 offset:39936
	global_load_lds_dwordx4 v[178:179], off
	s_mov_b32 m0, s44
	s_nop 0
	global_load_lds_dwordx4 v190, s[28:29]
	s_waitcnt lgkmcnt(8)
	s_barrier
	s_waitcnt lgkmcnt(0)
	s_setprio 1
	s_waitcnt lgkmcnt(0)
	v_mfma_f32_16x16x32_bf16 v[126:129], v[130:133], v[146:149], v[126:129]
	v_mfma_f32_16x16x32_bf16 v[122:125], v[138:141], v[146:149], v[122:125]
	v_mfma_f32_16x16x32_bf16 v[118:121], v[130:133], v[154:157], v[118:121]
	v_mfma_f32_16x16x32_bf16 v[106:109], v[138:141], v[154:157], v[106:109]
	v_mfma_f32_16x16x32_bf16 v[94:97], v[130:133], v[162:165], v[94:97]
	v_mfma_f32_16x16x32_bf16 v[90:93], v[138:141], v[162:165], v[90:93]
	v_mfma_f32_16x16x32_bf16 v[86:89], v[130:133], v[170:173], v[86:89]
	v_mfma_f32_16x16x32_bf16 v[74:77], v[138:141], v[170:173], v[74:77]
	v_mfma_f32_16x16x32_bf16 v[126:129], v[134:137], v[150:153], v[126:129]
	v_mfma_f32_16x16x32_bf16 v[122:125], v[142:145], v[150:153], v[122:125]
	v_mfma_f32_16x16x32_bf16 v[118:121], v[134:137], v[158:161], v[118:121]
	v_mfma_f32_16x16x32_bf16 v[106:109], v[142:145], v[158:161], v[106:109]
	v_mfma_f32_16x16x32_bf16 v[94:97], v[134:137], v[166:169], v[94:97]
	v_mfma_f32_16x16x32_bf16 v[90:93], v[142:145], v[166:169], v[90:93]
	v_mfma_f32_16x16x32_bf16 v[86:89], v[134:137], v[174:177], v[86:89]
	v_mfma_f32_16x16x32_bf16 v[74:77], v[142:145], v[174:177], v[74:77]
	s_setprio 0
	s_barrier
	s_add_i32 s28, 0, 0x1c000
	s_add_i32 s29, s31, s40
	v_add_u32_e32 v204, s28, v208
	v_lshl_add_u64 v[212:213], v[212:213], 0, s[66:67]
	s_mov_b32 m0, s29
	ds_read_b128 v[178:181], v204
	ds_read_b128 v[182:185], v204 offset:1024
	ds_read_b128 v[186:189], v204 offset:2048
	ds_read_b128 v[204:207], v204 offset:3072
	global_load_lds_dwordx4 v[212:213], off
	v_lshl_add_u64 v[212:213], v[214:215], 0, s[66:67]
	s_add_i32 m0, s29, 0x2000
	s_nop 0
	global_load_lds_dwordx4 v[212:213], off
	s_barrier
	s_waitcnt lgkmcnt(0)
	s_setprio 1
	s_waitcnt lgkmcnt(0)
	v_mfma_f32_16x16x32_bf16 v[114:117], v[178:181], v[146:149], v[114:117]
	v_mfma_f32_16x16x32_bf16 v[110:113], v[186:189], v[146:149], v[110:113]
	v_mfma_f32_16x16x32_bf16 v[102:105], v[178:181], v[154:157], v[102:105]
	v_mfma_f32_16x16x32_bf16 v[98:101], v[186:189], v[154:157], v[98:101]
	v_mfma_f32_16x16x32_bf16 v[82:85], v[178:181], v[162:165], v[82:85]
	v_mfma_f32_16x16x32_bf16 v[78:81], v[186:189], v[162:165], v[78:81]
	v_mfma_f32_16x16x32_bf16 v[70:73], v[178:181], v[170:173], v[70:73]
	v_mfma_f32_16x16x32_bf16 v[66:69], v[186:189], v[170:173], v[66:69]
	v_mfma_f32_16x16x32_bf16 v[114:117], v[182:185], v[150:153], v[114:117]
	v_mfma_f32_16x16x32_bf16 v[110:113], v[204:207], v[150:153], v[110:113]
	v_mfma_f32_16x16x32_bf16 v[102:105], v[182:185], v[158:161], v[102:105]
	v_mfma_f32_16x16x32_bf16 v[98:101], v[204:207], v[158:161], v[98:101]
	v_mfma_f32_16x16x32_bf16 v[82:85], v[182:185], v[166:169], v[82:85]
	v_mfma_f32_16x16x32_bf16 v[78:81], v[204:207], v[166:169], v[78:81]
	v_mfma_f32_16x16x32_bf16 v[70:73], v[182:185], v[174:177], v[70:73]
	v_mfma_f32_16x16x32_bf16 v[66:69], v[204:207], v[174:177], v[66:69]
	s_setprio 0
	s_mov_b32 m0, s47
	v_lshl_add_u64 v[212:213], v[216:217], 0, s[66:67]
	s_barrier
	ds_read_b128 v[146:149], v210 offset:49152
	ds_read_b128 v[150:153], v210 offset:50176
	ds_read_b128 v[154:157], v210 offset:51200
	ds_read_b128 v[158:161], v210 offset:52224
	ds_read_b128 v[162:165], v210 offset:53248
	ds_read_b128 v[166:169], v210 offset:54272
	ds_read_b128 v[170:173], v210 offset:55296
	ds_read_b128 v[174:177], v210 offset:56320
	global_load_lds_dwordx4 v[212:213], off
	v_lshl_add_u64 v[212:213], v[218:219], 0, s[66:67]
	s_mov_b32 m0, s48
	s_nop 0
	global_load_lds_dwordx4 v[212:213], off
	s_barrier
	s_waitcnt lgkmcnt(0)
	s_setprio 1
	s_waitcnt lgkmcnt(0)
	v_mfma_f32_16x16x32_bf16 v[62:65], v[130:133], v[146:149], v[62:65]
	v_mfma_f32_16x16x32_bf16 v[58:61], v[138:141], v[146:149], v[58:61]
	v_mfma_f32_16x16x32_bf16 v[54:57], v[130:133], v[154:157], v[54:57]
	v_mfma_f32_16x16x32_bf16 v[40:43], v[138:141], v[154:157], v[40:43]
	v_mfma_f32_16x16x32_bf16 v[36:39], v[130:133], v[162:165], v[36:39]
	v_mfma_f32_16x16x32_bf16 v[24:27], v[138:141], v[162:165], v[24:27]
	v_mfma_f32_16x16x32_bf16 v[20:23], v[130:133], v[170:173], v[20:23]
	v_mfma_f32_16x16x32_bf16 v[8:11], v[138:141], v[170:173], v[8:11]
	v_mfma_f32_16x16x32_bf16 v[62:65], v[134:137], v[150:153], v[62:65]
	v_mfma_f32_16x16x32_bf16 v[58:61], v[142:145], v[150:153], v[58:61]
	v_mfma_f32_16x16x32_bf16 v[54:57], v[134:137], v[158:161], v[54:57]
	v_mfma_f32_16x16x32_bf16 v[40:43], v[142:145], v[158:161], v[40:43]
	v_mfma_f32_16x16x32_bf16 v[36:39], v[134:137], v[166:169], v[36:39]
	v_mfma_f32_16x16x32_bf16 v[24:27], v[142:145], v[166:169], v[24:27]
	v_mfma_f32_16x16x32_bf16 v[20:23], v[134:137], v[174:177], v[20:23]
	v_mfma_f32_16x16x32_bf16 v[8:11], v[142:145], v[174:177], v[8:11]
	s_setprio 0
	s_barrier
	s_add_u32 s26, s26, 0x40080
	s_addc_u32 s27, s27, 0
	s_add_i32 s28, s28, s40
	v_lshl_add_u64 v[130:131], s[26:27], 0, v[48:49]
	s_mov_b32 m0, s28
	s_nop 0
	global_load_lds_dwordx4 v[130:131], off
	s_add_i32 m0, s28, 0x2000
	s_nop 0
	global_load_lds_dwordx4 v190, s[26:27]
	s_waitcnt vmcnt(6)
	s_barrier
	s_setprio 1
	v_mfma_f32_16x16x32_bf16 v[50:53], v[178:181], v[146:149], v[50:53]
	v_mfma_f32_16x16x32_bf16 v[44:47], v[186:189], v[146:149], v[44:47]
	v_mfma_f32_16x16x32_bf16 v[32:35], v[178:181], v[154:157], v[32:35]
	v_mfma_f32_16x16x32_bf16 v[28:31], v[186:189], v[154:157], v[28:31]
	v_mfma_f32_16x16x32_bf16 v[16:19], v[178:181], v[162:165], v[16:19]
	v_mfma_f32_16x16x32_bf16 v[12:15], v[186:189], v[162:165], v[12:15]
	v_mfma_f32_16x16x32_bf16 v[4:7], v[178:181], v[170:173], v[4:7]
	v_mfma_f32_16x16x32_bf16 v[0:3], v[186:189], v[170:173], v[0:3]
	v_mfma_f32_16x16x32_bf16 v[50:53], v[182:185], v[150:153], v[50:53]
	v_mfma_f32_16x16x32_bf16 v[44:47], v[204:207], v[150:153], v[44:47]
	v_mfma_f32_16x16x32_bf16 v[32:35], v[182:185], v[158:161], v[32:35]
	v_mfma_f32_16x16x32_bf16 v[28:31], v[204:207], v[158:161], v[28:31]
	v_mfma_f32_16x16x32_bf16 v[16:19], v[182:185], v[166:169], v[16:19]
	v_mfma_f32_16x16x32_bf16 v[12:15], v[204:207], v[166:169], v[12:15]
	v_mfma_f32_16x16x32_bf16 v[4:7], v[182:185], v[174:177], v[4:7]
	v_mfma_f32_16x16x32_bf16 v[0:3], v[204:207], v[174:177], v[0:3]
	s_setprio 0
	s_add_i32 s30, s30, 2
	s_add_u32 s24, s24, 0x100
	s_addc_u32 s25, s25, 0
	s_add_u32 s15, s15, 0x100
	s_addc_u32 s17, s17, 0
	s_cmp_gt_u32 s30, 13
	s_barrier
	s_cbranch_scc0 .LBB0_1219
	s_mul_hi_i32 s15, s22, 0x38e38e39
	s_lshr_b32 s17, s15, 31
	s_ashr_i32 s15, s15, 1
	s_add_i32 s24, s15, s17
	s_mul_i32 s15, s24, -9
	s_add_i32 s28, s15, s22
	s_cmp_eq_u32 s28, 0
	s_cselect_b64 s[26:27], -1, 0
	s_ashr_i32 s25, s24, 31
	s_cmp_lg_u32 s28, 0
	s_cbranch_scc0 .LBB0_1222
	s_ashr_i32 s29, s28, 31
	s_lshl_b64 s[28:29], s[28:29], 18
	s_lshl_b64 s[30:31], s[24:25], 21
	s_add_u32 s15, s28, s30
	s_addc_u32 s17, s29, s31
	s_add_u32 s28, s15, 0xfffc0000
	s_addc_u32 s29, s17, -1
	s_mov_b64 s[30:31], s[6:7]
	s_cbranch_execnz .LBB0_1215
	s_branch .LBB0_1214

.LBB0_1356:
	s_add_u32 s28, s26, 0xfffc0080
	s_addc_u32 s29, s27, -1
	s_add_i32 s46, 0, 0x10000
	v_add_u32_e32 v140, s46, v143
	ds_read_b128 v[146:149], v140
	ds_read_b128 v[150:153], v140 offset:1024
	ds_read_b128 v[154:157], v140 offset:2048
	ds_read_b128 v[158:161], v140 offset:3072
	s_cmp_eq_u32 s45, 12
	s_cselect_b32 s31, s19, s29
	s_cselect_b32 s30, s18, s28
	s_cselect_b32 s29, s21, s17
	s_cselect_b32 s28, s20, s15
	s_add_i32 m0, s23, 0xc000
	ds_read_b128 v[162:165], v145
	ds_read_b128 v[166:169], v145 offset:1024
	ds_read_b128 v[170:173], v145 offset:2048
	ds_read_b128 v[174:177], v145 offset:3072
	ds_read_b128 v[178:181], v145 offset:4096
	ds_read_b128 v[182:185], v145 offset:5120
	ds_read_b128 v[186:189], v145 offset:6144
	ds_read_b128 v[190:193], v145 offset:7168
	global_load_lds_dwordx4 v136, s[26:27]
	s_add_i32 m0, s23, 0xe000
	s_nop 0
	global_load_lds_dwordx4 v138, s[26:27]
	s_waitcnt lgkmcnt(8)
	s_barrier
	s_waitcnt lgkmcnt(0)
	s_setprio 1
	s_waitcnt lgkmcnt(0)
	v_mfma_f32_16x16x32_bf16 v[126:129], v[146:149], v[162:165], v[126:129]
	v_mfma_f32_16x16x32_bf16 v[118:121], v[154:157], v[162:165], v[118:121]
	v_mfma_f32_16x16x32_bf16 v[110:113], v[146:149], v[170:173], v[110:113]
	v_mfma_f32_16x16x32_bf16 v[102:105], v[154:157], v[170:173], v[102:105]
	v_mfma_f32_16x16x32_bf16 v[94:97], v[146:149], v[178:181], v[94:97]
	v_mfma_f32_16x16x32_bf16 v[86:89], v[154:157], v[178:181], v[86:89]
	v_mfma_f32_16x16x32_bf16 v[78:81], v[146:149], v[186:189], v[78:81]
	v_mfma_f32_16x16x32_bf16 v[70:73], v[154:157], v[186:189], v[70:73]
	v_mfma_f32_16x16x32_bf16 v[126:129], v[150:153], v[166:169], v[126:129]
	v_mfma_f32_16x16x32_bf16 v[118:121], v[158:161], v[166:169], v[118:121]
	v_mfma_f32_16x16x32_bf16 v[110:113], v[150:153], v[174:177], v[110:113]
	v_mfma_f32_16x16x32_bf16 v[102:105], v[158:161], v[174:177], v[102:105]
	v_mfma_f32_16x16x32_bf16 v[94:97], v[150:153], v[182:185], v[94:97]
	v_mfma_f32_16x16x32_bf16 v[86:89], v[158:161], v[182:185], v[86:89]
	v_mfma_f32_16x16x32_bf16 v[78:81], v[150:153], v[190:193], v[78:81]
	v_mfma_f32_16x16x32_bf16 v[70:73], v[158:161], v[190:193], v[70:73]
	s_setprio 0
	s_barrier
	s_add_i32 s48, 0, 0x14000
	v_add_u32_e32 v140, s48, v143
	s_add_i32 s46, s46, s37
	ds_read_b128 v[198:201], v140
	ds_read_b128 v[202:205], v140 offset:1024
	ds_read_b128 v[206:209], v140 offset:2048
	ds_read_b128 v[210:213], v140 offset:3072
	v_lshl_add_u64 v[140:141], s[28:29], 0, v[48:49]
	s_mov_b32 m0, s46
	v_lshl_add_u64 v[214:215], s[28:29], 0, v[130:131]
	global_load_lds_dwordx4 v[140:141], off
	s_add_i32 m0, s46, 0x2000
	s_nop 0
	global_load_lds_dwordx4 v[214:215], off
	s_barrier
	s_waitcnt lgkmcnt(0)
	s_setprio 1
	s_waitcnt lgkmcnt(0)
	v_mfma_f32_16x16x32_bf16 v[122:125], v[198:201], v[162:165], v[122:125]
	v_mfma_f32_16x16x32_bf16 v[114:117], v[206:209], v[162:165], v[114:117]
	v_mfma_f32_16x16x32_bf16 v[106:109], v[198:201], v[170:173], v[106:109]
	v_mfma_f32_16x16x32_bf16 v[98:101], v[206:209], v[170:173], v[98:101]
	v_mfma_f32_16x16x32_bf16 v[90:93], v[198:201], v[178:181], v[90:93]
	v_mfma_f32_16x16x32_bf16 v[82:85], v[206:209], v[178:181], v[82:85]
	v_mfma_f32_16x16x32_bf16 v[74:77], v[198:201], v[186:189], v[74:77]
	v_mfma_f32_16x16x32_bf16 v[66:69], v[206:209], v[186:189], v[66:69]
	v_mfma_f32_16x16x32_bf16 v[122:125], v[202:205], v[166:169], v[122:125]
	v_mfma_f32_16x16x32_bf16 v[114:117], v[210:213], v[166:169], v[114:117]
	v_mfma_f32_16x16x32_bf16 v[106:109], v[202:205], v[174:177], v[106:109]
	v_mfma_f32_16x16x32_bf16 v[98:101], v[210:213], v[174:177], v[98:101]
	v_mfma_f32_16x16x32_bf16 v[90:93], v[202:205], v[182:185], v[90:93]
	v_mfma_f32_16x16x32_bf16 v[82:85], v[210:213], v[182:185], v[82:85]
	v_mfma_f32_16x16x32_bf16 v[74:77], v[202:205], v[190:193], v[74:77]
	v_mfma_f32_16x16x32_bf16 v[66:69], v[210:213], v[190:193], v[66:69]
	s_setprio 0
	s_mov_b32 m0, s23
	v_lshl_add_u64 v[216:217], s[30:31], 0, v[134:135]
	s_barrier
	ds_read_b128 v[162:165], v145 offset:16384
	ds_read_b128 v[166:169], v145 offset:17408
	ds_read_b128 v[170:173], v145 offset:18432
	ds_read_b128 v[174:177], v145 offset:19456
	ds_read_b128 v[178:181], v145 offset:20480
	ds_read_b128 v[182:185], v145 offset:21504
	ds_read_b128 v[186:189], v145 offset:22528
	ds_read_b128 v[190:193], v145 offset:23552
	global_load_lds_dwordx4 v[216:217], off
	v_lshl_add_u64 v[218:219], s[30:31], 0, v[132:133]
	s_mov_b32 m0, s25
	s_nop 0
	global_load_lds_dwordx4 v[218:219], off
	s_barrier
	s_waitcnt lgkmcnt(0)
	s_setprio 1
	s_waitcnt lgkmcnt(0)
	v_mfma_f32_16x16x32_bf16 v[62:65], v[146:149], v[162:165], v[62:65]
	v_mfma_f32_16x16x32_bf16 v[54:57], v[154:157], v[162:165], v[54:57]
	v_mfma_f32_16x16x32_bf16 v[44:47], v[146:149], v[170:173], v[44:47]
	v_mfma_f32_16x16x32_bf16 v[36:39], v[154:157], v[170:173], v[36:39]
	v_mfma_f32_16x16x32_bf16 v[28:31], v[146:149], v[178:181], v[28:31]
	v_mfma_f32_16x16x32_bf16 v[20:23], v[154:157], v[178:181], v[20:23]
	v_mfma_f32_16x16x32_bf16 v[12:15], v[146:149], v[186:189], v[12:15]
	v_mfma_f32_16x16x32_bf16 v[4:7], v[154:157], v[186:189], v[4:7]
	v_mfma_f32_16x16x32_bf16 v[62:65], v[150:153], v[166:169], v[62:65]
	v_mfma_f32_16x16x32_bf16 v[54:57], v[158:161], v[166:169], v[54:57]
	v_mfma_f32_16x16x32_bf16 v[44:47], v[150:153], v[174:177], v[44:47]
	v_mfma_f32_16x16x32_bf16 v[36:39], v[158:161], v[174:177], v[36:39]
	v_mfma_f32_16x16x32_bf16 v[28:31], v[150:153], v[182:185], v[28:31]
	v_mfma_f32_16x16x32_bf16 v[20:23], v[158:161], v[182:185], v[20:23]
	v_mfma_f32_16x16x32_bf16 v[12:15], v[150:153], v[190:193], v[12:15]
	v_mfma_f32_16x16x32_bf16 v[4:7], v[158:161], v[190:193], v[4:7]
	s_setprio 0
	s_barrier
	s_add_u32 s46, s28, 0x40000
	s_addc_u32 s47, s29, 0
	s_add_i32 s48, s48, s37
	v_lshl_add_u64 v[146:147], s[46:47], 0, v[48:49]
	s_mov_b32 m0, s48
	s_nop 0
	global_load_lds_dwordx4 v[146:147], off
	v_lshl_add_u64 v[146:147], s[46:47], 0, v[130:131]
	s_add_i32 m0, s48, 0x2000
	s_nop 0
	global_load_lds_dwordx4 v[146:147], off
	s_waitcnt vmcnt(6)
	s_barrier
	s_setprio 1
	v_mfma_f32_16x16x32_bf16 v[58:61], v[198:201], v[162:165], v[58:61]
	v_mfma_f32_16x16x32_bf16 v[50:53], v[206:209], v[162:165], v[50:53]
	v_mfma_f32_16x16x32_bf16 v[40:43], v[198:201], v[170:173], v[40:43]
	v_mfma_f32_16x16x32_bf16 v[32:35], v[206:209], v[170:173], v[32:35]
	v_mfma_f32_16x16x32_bf16 v[24:27], v[198:201], v[178:181], v[24:27]
	v_mfma_f32_16x16x32_bf16 v[16:19], v[206:209], v[178:181], v[16:19]
	v_mfma_f32_16x16x32_bf16 v[8:11], v[198:201], v[186:189], v[8:11]
	v_mfma_f32_16x16x32_bf16 v[0:3], v[206:209], v[186:189], v[0:3]
	v_mfma_f32_16x16x32_bf16 v[58:61], v[202:205], v[166:169], v[58:61]
	v_mfma_f32_16x16x32_bf16 v[50:53], v[210:213], v[166:169], v[50:53]
	v_mfma_f32_16x16x32_bf16 v[40:43], v[202:205], v[174:177], v[40:43]
	v_mfma_f32_16x16x32_bf16 v[32:35], v[210:213], v[174:177], v[32:35]
	v_mfma_f32_16x16x32_bf16 v[24:27], v[202:205], v[182:185], v[24:27]
	v_mfma_f32_16x16x32_bf16 v[16:19], v[210:213], v[182:185], v[16:19]
	v_mfma_f32_16x16x32_bf16 v[8:11], v[202:205], v[190:193], v[8:11]
	v_mfma_f32_16x16x32_bf16 v[0:3], v[210:213], v[190:193], v[0:3]
	s_setprio 0
	s_add_i32 s46, 0, 0x18000
	v_add_u32_e32 v158, s46, v143
	s_barrier
	ds_read_b128 v[146:149], v158
	ds_read_b128 v[150:153], v158 offset:1024
	ds_read_b128 v[154:157], v158 offset:2048
	ds_read_b128 v[158:161], v158 offset:3072
	s_add_u32 s30, s30, 0x40000
	s_addc_u32 s31, s31, 0
	s_mov_b32 m0, s40
	ds_read_b128 v[162:165], v145 offset:32768
	ds_read_b128 v[166:169], v145 offset:33792
	ds_read_b128 v[170:173], v145 offset:34816
	ds_read_b128 v[174:177], v145 offset:35840
	ds_read_b128 v[178:181], v145 offset:36864
	ds_read_b128 v[182:185], v145 offset:37888
	ds_read_b128 v[186:189], v145 offset:38912
	ds_read_b128 v[190:193], v145 offset:39936
	global_load_lds_dwordx4 v134, s[30:31]
	s_mov_b32 m0, s41
	s_nop 0
	global_load_lds_dwordx4 v132, s[30:31]
	s_waitcnt lgkmcnt(8)
	s_barrier
	s_waitcnt lgkmcnt(0)
	s_setprio 1
	s_waitcnt lgkmcnt(0)
	v_mfma_f32_16x16x32_bf16 v[126:129], v[146:149], v[162:165], v[126:129]
	v_mfma_f32_16x16x32_bf16 v[118:121], v[154:157], v[162:165], v[118:121]
	v_mfma_f32_16x16x32_bf16 v[110:113], v[146:149], v[170:173], v[110:113]
	v_mfma_f32_16x16x32_bf16 v[102:105], v[154:157], v[170:173], v[102:105]
	v_mfma_f32_16x16x32_bf16 v[94:97], v[146:149], v[178:181], v[94:97]
	v_mfma_f32_16x16x32_bf16 v[86:89], v[154:157], v[178:181], v[86:89]
	v_mfma_f32_16x16x32_bf16 v[78:81], v[146:149], v[186:189], v[78:81]
	v_mfma_f32_16x16x32_bf16 v[70:73], v[154:157], v[186:189], v[70:73]
	v_mfma_f32_16x16x32_bf16 v[126:129], v[150:153], v[166:169], v[126:129]
	v_mfma_f32_16x16x32_bf16 v[118:121], v[158:161], v[166:169], v[118:121]
	v_mfma_f32_16x16x32_bf16 v[110:113], v[150:153], v[174:177], v[110:113]
	v_mfma_f32_16x16x32_bf16 v[102:105], v[158:161], v[174:177], v[102:105]
	v_mfma_f32_16x16x32_bf16 v[94:97], v[150:153], v[182:185], v[94:97]
	v_mfma_f32_16x16x32_bf16 v[86:89], v[158:161], v[182:185], v[86:89]
	v_mfma_f32_16x16x32_bf16 v[78:81], v[150:153], v[190:193], v[78:81]
	v_mfma_f32_16x16x32_bf16 v[70:73], v[158:161], v[190:193], v[70:73]
	s_setprio 0
	s_barrier
	s_add_i32 s30, 0, 0x1c000
	s_add_i32 s31, s46, s37
	v_add_u32_e32 v210, s30, v143
	v_lshl_add_u64 v[140:141], v[140:141], 0, s[66:67]
	s_mov_b32 m0, s31
	ds_read_b128 v[198:201], v210
	ds_read_b128 v[202:205], v210 offset:1024
	ds_read_b128 v[206:209], v210 offset:2048
	ds_read_b128 v[210:213], v210 offset:3072
	global_load_lds_dwordx4 v[140:141], off
	v_lshl_add_u64 v[140:141], v[214:215], 0, s[66:67]
	s_add_i32 m0, s31, 0x2000
	s_nop 0
	global_load_lds_dwordx4 v[140:141], off
	s_barrier
	s_waitcnt lgkmcnt(0)
	s_setprio 1
	s_waitcnt lgkmcnt(0)
	v_mfma_f32_16x16x32_bf16 v[122:125], v[198:201], v[162:165], v[122:125]
	v_mfma_f32_16x16x32_bf16 v[114:117], v[206:209], v[162:165], v[114:117]
	v_mfma_f32_16x16x32_bf16 v[106:109], v[198:201], v[170:173], v[106:109]
	v_mfma_f32_16x16x32_bf16 v[98:101], v[206:209], v[170:173], v[98:101]
	v_mfma_f32_16x16x32_bf16 v[90:93], v[198:201], v[178:181], v[90:93]
	v_mfma_f32_16x16x32_bf16 v[82:85], v[206:209], v[178:181], v[82:85]
	v_mfma_f32_16x16x32_bf16 v[74:77], v[198:201], v[186:189], v[74:77]
	v_mfma_f32_16x16x32_bf16 v[66:69], v[206:209], v[186:189], v[66:69]
	v_mfma_f32_16x16x32_bf16 v[122:125], v[202:205], v[166:169], v[122:125]
	v_mfma_f32_16x16x32_bf16 v[114:117], v[210:213], v[166:169], v[114:117]
	v_mfma_f32_16x16x32_bf16 v[106:109], v[202:205], v[174:177], v[106:109]
	v_mfma_f32_16x16x32_bf16 v[98:101], v[210:213], v[174:177], v[98:101]
	v_mfma_f32_16x16x32_bf16 v[90:93], v[202:205], v[182:185], v[90:93]
	v_mfma_f32_16x16x32_bf16 v[82:85], v[210:213], v[182:185], v[82:85]
	v_mfma_f32_16x16x32_bf16 v[74:77], v[202:205], v[190:193], v[74:77]
	v_mfma_f32_16x16x32_bf16 v[66:69], v[210:213], v[190:193], v[66:69]
	s_setprio 0
	s_mov_b32 m0, s42
	v_lshl_add_u64 v[140:141], v[216:217], 0, s[66:67]
	s_barrier
	ds_read_b128 v[162:165], v145 offset:49152
	ds_read_b128 v[166:169], v145 offset:50176
	ds_read_b128 v[170:173], v145 offset:51200
	ds_read_b128 v[174:177], v145 offset:52224
	ds_read_b128 v[178:181], v145 offset:53248
	ds_read_b128 v[182:185], v145 offset:54272
	ds_read_b128 v[186:189], v145 offset:55296
	ds_read_b128 v[190:193], v145 offset:56320
	global_load_lds_dwordx4 v[140:141], off
	v_lshl_add_u64 v[140:141], v[218:219], 0, s[66:67]
	s_mov_b32 m0, s43
	s_nop 0
	global_load_lds_dwordx4 v[140:141], off
	s_barrier
	s_waitcnt lgkmcnt(0)
	s_setprio 1
	s_waitcnt lgkmcnt(0)
	v_mfma_f32_16x16x32_bf16 v[62:65], v[146:149], v[162:165], v[62:65]
	v_mfma_f32_16x16x32_bf16 v[54:57], v[154:157], v[162:165], v[54:57]
	v_mfma_f32_16x16x32_bf16 v[44:47], v[146:149], v[170:173], v[44:47]
	v_mfma_f32_16x16x32_bf16 v[36:39], v[154:157], v[170:173], v[36:39]
	v_mfma_f32_16x16x32_bf16 v[28:31], v[146:149], v[178:181], v[28:31]
	v_mfma_f32_16x16x32_bf16 v[20:23], v[154:157], v[178:181], v[20:23]
	v_mfma_f32_16x16x32_bf16 v[12:15], v[146:149], v[186:189], v[12:15]
	v_mfma_f32_16x16x32_bf16 v[4:7], v[154:157], v[186:189], v[4:7]
	v_mfma_f32_16x16x32_bf16 v[62:65], v[150:153], v[166:169], v[62:65]
	v_mfma_f32_16x16x32_bf16 v[54:57], v[158:161], v[166:169], v[54:57]
	v_mfma_f32_16x16x32_bf16 v[44:47], v[150:153], v[174:177], v[44:47]
	v_mfma_f32_16x16x32_bf16 v[36:39], v[158:161], v[174:177], v[36:39]
	v_mfma_f32_16x16x32_bf16 v[28:31], v[150:153], v[182:185], v[28:31]
	v_mfma_f32_16x16x32_bf16 v[20:23], v[158:161], v[182:185], v[20:23]
	v_mfma_f32_16x16x32_bf16 v[12:15], v[150:153], v[190:193], v[12:15]
	v_mfma_f32_16x16x32_bf16 v[4:7], v[158:161], v[190:193], v[4:7]
	s_setprio 0
	s_barrier
	s_add_u32 s28, s28, 0x40080
	s_addc_u32 s29, s29, 0
	s_add_i32 s30, s30, s37
	v_lshl_add_u64 v[140:141], s[28:29], 0, v[48:49]
	s_mov_b32 m0, s30
	s_nop 0
	global_load_lds_dwordx4 v[140:141], off
	s_add_i32 m0, s30, 0x2000
	s_nop 0
	global_load_lds_dwordx4 v130, s[28:29]
	s_waitcnt vmcnt(6)
	s_barrier
	s_setprio 1
	v_mfma_f32_16x16x32_bf16 v[58:61], v[198:201], v[162:165], v[58:61]
	v_mfma_f32_16x16x32_bf16 v[50:53], v[206:209], v[162:165], v[50:53]
	v_mfma_f32_16x16x32_bf16 v[40:43], v[198:201], v[170:173], v[40:43]
	v_mfma_f32_16x16x32_bf16 v[32:35], v[206:209], v[170:173], v[32:35]
	v_mfma_f32_16x16x32_bf16 v[24:27], v[198:201], v[178:181], v[24:27]
	v_mfma_f32_16x16x32_bf16 v[16:19], v[206:209], v[178:181], v[16:19]
	v_mfma_f32_16x16x32_bf16 v[8:11], v[198:201], v[186:189], v[8:11]
	v_mfma_f32_16x16x32_bf16 v[0:3], v[206:209], v[186:189], v[0:3]
	v_mfma_f32_16x16x32_bf16 v[58:61], v[202:205], v[166:169], v[58:61]
	v_mfma_f32_16x16x32_bf16 v[50:53], v[210:213], v[166:169], v[50:53]
	v_mfma_f32_16x16x32_bf16 v[40:43], v[202:205], v[174:177], v[40:43]
	v_mfma_f32_16x16x32_bf16 v[32:35], v[210:213], v[174:177], v[32:35]
	v_mfma_f32_16x16x32_bf16 v[24:27], v[202:205], v[182:185], v[24:27]
	v_mfma_f32_16x16x32_bf16 v[16:19], v[210:213], v[182:185], v[16:19]
	v_mfma_f32_16x16x32_bf16 v[8:11], v[202:205], v[190:193], v[8:11]
	v_mfma_f32_16x16x32_bf16 v[0:3], v[210:213], v[190:193], v[0:3]
	s_setprio 0
	s_add_i32 s45, s45, 2
	s_add_u32 s26, s26, 0x100
	s_addc_u32 s27, s27, 0
	s_add_u32 s15, s15, 0x100
	s_addc_u32 s17, s17, 0
	s_cmp_gt_u32 s45, 13
	s_barrier
	s_cbranch_scc0 .LBB0_1356
	v_mul_f32_e32 v147, 0xbfb8aa3b, v126
	v_exp_f32_e32 v148, v147
	v_mul_f32_e32 v147, 0xbfb8aa3b, v118
	v_exp_f32_e32 v150, v147
	v_mul_f32_e32 v147, 0xbfb8aa3b, v127
	v_exp_f32_e32 v149, v147
	v_lshl_or_b32 v140, s22, 7, v144
	v_lshl_add_u32 v146, s24, 8, v142
	v_ashrrev_i32_e32 v141, 31, v140
	v_pk_add_f32 v[148:149], v[148:149], 1.0 op_sel_hi:[1,0]
	s_movk_i32 s15, 0x1600
	s_mov_b32 s22, s14
	s_mov_b32 s24, s16
	s_mov_b64 s[28:29], s[20:21]
	v_rcp_f32_e32 v147, v149
	s_nop 0
	v_mul_f32_e32 v127, v127, v147
	s_nop 0
	v_rcp_f32_e32 v147, v148
	s_nop 0
	v_mul_f32_e32 v126, v126, v147
	v_pk_mul_f32 v[122:123], v[122:123], v[126:127]
	v_mul_f32_e32 v126, 0xbfb8aa3b, v119
	v_exp_f32_e32 v151, v126
	s_nop 0
	v_pk_add_f32 v[126:127], v[150:151], 1.0 op_sel_hi:[1,0]
	s_nop 0
	s_nop 0
	v_rcp_f32_e32 v147, v127
	s_nop 0
	v_mul_f32_e32 v119, v119, v147
	s_nop 0
	v_rcp_f32_e32 v127, v126
	s_nop 0
	v_mul_f32_e32 v118, v118, v127
	v_pk_mul_f32 v[114:115], v[114:115], v[118:119]
	v_mul_f32_e32 v119, 0xbfb8aa3b, v120
	v_mul_f32_e32 v118, 0xbfb8aa3b, v128
	v_exp_f32_e32 v126, v119
	v_mul_f32_e32 v119, 0xbfb8aa3b, v129
	v_exp_f32_e32 v118, v118
	v_exp_f32_e32 v119, v119
	s_nop 0
	v_pk_add_f32 v[118:119], v[118:119], 1.0 op_sel_hi:[1,0]
	s_nop 0
	s_nop 0
	v_rcp_f32_e32 v127, v119
	s_nop 0
	v_mul_f32_e32 v119, v129, v127
	s_nop 0
	v_rcp_f32_e32 v127, v118
	s_nop 0
	v_mul_f32_e32 v118, v128, v127
	v_pk_mul_f32 v[124:125], v[124:125], v[118:119]
	v_mul_f32_e32 v118, 0xbfb8aa3b, v121
	v_exp_f32_e32 v127, v118
	s_nop 0
	v_pk_add_f32 v[118:119], v[126:127], 1.0 op_sel_hi:[1,0]
	s_nop 0
	s_nop 0
	v_rcp_f32_e32 v126, v119
	s_nop 0
	v_mul_f32_e32 v119, v121, v126
	s_nop 0
	v_rcp_f32_e32 v121, v118
	s_nop 0
	v_mul_f32_e32 v118, v120, v121
	v_pk_mul_f32 v[116:117], v[116:117], v[118:119]
	v_cvt_pk_bf16_f32 v120, v114, v115
	v_mov_b64_e32 v[114:115], s[12:13]
	v_cvt_pk_bf16_f32 v118, v122, v123
	v_cvt_pk_bf16_f32 v121, v116, v117
	v_mad_i64_i32 v[122:123], s[26:27], v146, s15, v[114:115]
	v_lshlrev_b64 v[116:117], 1, v[140:141]
	v_cvt_pk_bf16_f32 v119, v124, v125
	v_lshl_add_u64 v[122:123], v[122:123], 0, v[116:117]
	global_store_dwordx4 v[122:123], v[118:121], off
	s_nop 1
	v_mul_f32_e32 v119, 0xbfb8aa3b, v102
	v_mul_f32_e32 v118, 0xbfb8aa3b, v110
	v_exp_f32_e32 v120, v119
	v_mul_f32_e32 v119, 0xbfb8aa3b, v111
	v_exp_f32_e32 v118, v118
	v_exp_f32_e32 v119, v119
	s_nop 0
	v_pk_add_f32 v[118:119], v[118:119], 1.0 op_sel_hi:[1,0]
	s_nop 0
	s_nop 0
	v_rcp_f32_e32 v121, v119
	s_nop 0
	v_mul_f32_e32 v111, v111, v121
	s_nop 0
	v_rcp_f32_e32 v119, v118
	s_nop 0
	v_mul_f32_e32 v110, v110, v119
	v_pk_mul_f32 v[106:107], v[106:107], v[110:111]
	v_mul_f32_e32 v110, 0xbfb8aa3b, v103
	v_exp_f32_e32 v121, v110
	s_nop 0
	v_pk_add_f32 v[110:111], v[120:121], 1.0 op_sel_hi:[1,0]
	s_nop 0
	s_nop 0
	v_rcp_f32_e32 v118, v111
	s_nop 0
	v_mul_f32_e32 v103, v103, v118
	s_nop 0
	v_rcp_f32_e32 v111, v110
	s_nop 0
	v_mul_f32_e32 v102, v102, v111
	v_pk_mul_f32 v[102:103], v[98:99], v[102:103]
	v_mul_f32_e32 v99, 0xbfb8aa3b, v104
	v_mul_f32_e32 v98, 0xbfb8aa3b, v112
	v_exp_f32_e32 v110, v99
	v_mul_f32_e32 v99, 0xbfb8aa3b, v113
	v_exp_f32_e32 v98, v98
	v_exp_f32_e32 v99, v99
	s_nop 0
	v_pk_add_f32 v[98:99], v[98:99], 1.0 op_sel_hi:[1,0]
	s_nop 0
	s_nop 0
	v_rcp_f32_e32 v111, v99
	s_nop 0
	v_mul_f32_e32 v99, v113, v111
	s_nop 0
	v_rcp_f32_e32 v111, v98
	s_nop 0
	v_mul_f32_e32 v98, v112, v111
	v_pk_mul_f32 v[108:109], v[108:109], v[98:99]
	v_mul_f32_e32 v98, 0xbfb8aa3b, v105
	v_exp_f32_e32 v111, v98
	s_nop 0
	v_pk_add_f32 v[98:99], v[110:111], 1.0 op_sel_hi:[1,0]
	s_nop 0
	s_nop 0
	v_rcp_f32_e32 v110, v99
	s_nop 0
	v_mul_f32_e32 v99, v105, v110
	s_nop 0
	v_rcp_f32_e32 v105, v98
	s_nop 0
	v_mul_f32_e32 v98, v104, v105
	v_or_b32_e32 v110, 16, v146
	v_pk_mul_f32 v[104:105], v[100:101], v[98:99]
	v_cvt_pk_bf16_f32 v100, v102, v103
	v_mad_i64_i32 v[102:103], s[26:27], v110, s15, v[114:115]
	v_cvt_pk_bf16_f32 v98, v106, v107
	v_cvt_pk_bf16_f32 v99, v108, v109
	v_cvt_pk_bf16_f32 v101, v104, v105
	v_lshl_add_u64 v[102:103], v[102:103], 0, v[116:117]
	global_store_dwordx4 v[102:103], v[98:101], off
	s_nop 1
	v_mul_f32_e32 v99, 0xbfb8aa3b, v86
	v_mul_f32_e32 v98, 0xbfb8aa3b, v94
	v_exp_f32_e32 v100, v99
	v_mul_f32_e32 v99, 0xbfb8aa3b, v95
	v_exp_f32_e32 v98, v98
	v_exp_f32_e32 v99, v99
	s_nop 0
	v_pk_add_f32 v[98:99], v[98:99], 1.0 op_sel_hi:[1,0]
	s_nop 0
	s_nop 0
	v_rcp_f32_e32 v101, v99
	s_nop 0
	v_mul_f32_e32 v95, v95, v101
	s_nop 0
	v_rcp_f32_e32 v99, v98
	s_nop 0
	v_mul_f32_e32 v94, v94, v99
	v_pk_mul_f32 v[90:91], v[90:91], v[94:95]
	v_mul_f32_e32 v94, 0xbfb8aa3b, v87
	v_exp_f32_e32 v101, v94
	s_nop 0
	v_pk_add_f32 v[94:95], v[100:101], 1.0 op_sel_hi:[1,0]
	s_nop 0
	s_nop 0
	v_rcp_f32_e32 v98, v95
	s_nop 0
	v_mul_f32_e32 v87, v87, v98
	s_nop 0
	v_rcp_f32_e32 v95, v94
	s_nop 0
	v_mul_f32_e32 v86, v86, v95
	v_pk_mul_f32 v[86:87], v[82:83], v[86:87]
	v_mul_f32_e32 v83, 0xbfb8aa3b, v88
	v_mul_f32_e32 v82, 0xbfb8aa3b, v96
	v_exp_f32_e32 v94, v83
	v_mul_f32_e32 v83, 0xbfb8aa3b, v97
	v_exp_f32_e32 v82, v82
	v_exp_f32_e32 v83, v83
	s_nop 0
	v_pk_add_f32 v[82:83], v[82:83], 1.0 op_sel_hi:[1,0]
	s_nop 0
	s_nop 0
	v_rcp_f32_e32 v95, v83
	s_nop 0
	v_mul_f32_e32 v83, v97, v95
	s_nop 0
	v_rcp_f32_e32 v95, v82
	s_nop 0
	v_mul_f32_e32 v82, v96, v95
	v_pk_mul_f32 v[92:93], v[92:93], v[82:83]
	v_mul_f32_e32 v82, 0xbfb8aa3b, v89
	v_exp_f32_e32 v95, v82
	s_nop 0
	v_pk_add_f32 v[82:83], v[94:95], 1.0 op_sel_hi:[1,0]
	s_nop 0
	s_nop 0
	v_rcp_f32_e32 v94, v83
	s_nop 0
	v_mul_f32_e32 v83, v89, v94
	s_nop 0
	v_rcp_f32_e32 v89, v82
	s_nop 0
	v_mul_f32_e32 v82, v88, v89
	v_or_b32_e32 v94, 32, v146
	v_pk_mul_f32 v[88:89], v[84:85], v[82:83]
	v_cvt_pk_bf16_f32 v84, v86, v87
	v_mad_i64_i32 v[86:87], s[26:27], v94, s15, v[114:115]
	v_cvt_pk_bf16_f32 v82, v90, v91
	v_cvt_pk_bf16_f32 v83, v92, v93
	v_cvt_pk_bf16_f32 v85, v88, v89
	v_lshl_add_u64 v[86:87], v[86:87], 0, v[116:117]
	global_store_dwordx4 v[86:87], v[82:85], off
	s_nop 1
	v_mul_f32_e32 v83, 0xbfb8aa3b, v70
	v_mul_f32_e32 v82, 0xbfb8aa3b, v78
	v_exp_f32_e32 v84, v83
	v_mul_f32_e32 v83, 0xbfb8aa3b, v79
	v_exp_f32_e32 v82, v82
	v_exp_f32_e32 v83, v83
	s_nop 0
	v_pk_add_f32 v[82:83], v[82:83], 1.0 op_sel_hi:[1,0]
	s_nop 0
	s_nop 0
	v_rcp_f32_e32 v85, v83
	s_nop 0
	v_mul_f32_e32 v79, v79, v85
	s_nop 0
	v_rcp_f32_e32 v83, v82
	s_nop 0
	v_mul_f32_e32 v78, v78, v83
	v_pk_mul_f32 v[74:75], v[74:75], v[78:79]
	v_mul_f32_e32 v78, 0xbfb8aa3b, v71
	v_exp_f32_e32 v85, v78
	s_nop 0
	v_pk_add_f32 v[78:79], v[84:85], 1.0 op_sel_hi:[1,0]
	s_nop 0
	s_nop 0
	v_rcp_f32_e32 v82, v79
	s_nop 0
	v_mul_f32_e32 v71, v71, v82
	s_nop 0
	v_rcp_f32_e32 v79, v78
	s_nop 0
	v_mul_f32_e32 v70, v70, v79
	v_pk_mul_f32 v[70:71], v[66:67], v[70:71]
	v_mul_f32_e32 v67, 0xbfb8aa3b, v72
	v_mul_f32_e32 v66, 0xbfb8aa3b, v80
	v_exp_f32_e32 v78, v67
	v_mul_f32_e32 v67, 0xbfb8aa3b, v81
	v_exp_f32_e32 v66, v66
	v_exp_f32_e32 v67, v67
	s_nop 0
	v_pk_add_f32 v[66:67], v[66:67], 1.0 op_sel_hi:[1,0]
	s_nop 0
	s_nop 0
	v_rcp_f32_e32 v79, v67
	s_nop 0
	v_mul_f32_e32 v67, v81, v79
	s_nop 0
	v_rcp_f32_e32 v79, v66
	s_nop 0
	v_mul_f32_e32 v66, v80, v79
	v_pk_mul_f32 v[76:77], v[76:77], v[66:67]
	v_mul_f32_e32 v66, 0xbfb8aa3b, v73
	v_exp_f32_e32 v79, v66
	s_nop 0
	v_pk_add_f32 v[66:67], v[78:79], 1.0 op_sel_hi:[1,0]
	s_nop 0
	s_nop 0
	v_rcp_f32_e32 v78, v67
	s_nop 0
	v_mul_f32_e32 v67, v73, v78
	s_nop 0
	v_rcp_f32_e32 v73, v66
	s_nop 0
	v_mul_f32_e32 v66, v72, v73
	v_or_b32_e32 v78, 48, v146
	v_pk_mul_f32 v[72:73], v[68:69], v[66:67]
	v_cvt_pk_bf16_f32 v68, v70, v71
	v_mad_i64_i32 v[70:71], s[26:27], v78, s15, v[114:115]
	v_cvt_pk_bf16_f32 v66, v74, v75
	v_cvt_pk_bf16_f32 v67, v76, v77
	v_cvt_pk_bf16_f32 v69, v72, v73
	v_lshl_add_u64 v[70:71], v[70:71], 0, v[116:117]
	global_store_dwordx4 v[70:71], v[66:69], off
	v_add_u32_e32 v70, 0x80, v146
	s_nop 0
	v_mul_f32_e32 v67, 0xbfb8aa3b, v54
	v_mul_f32_e32 v66, 0xbfb8aa3b, v62
	v_exp_f32_e32 v68, v67
	v_mul_f32_e32 v67, 0xbfb8aa3b, v63
	v_exp_f32_e32 v66, v66
	v_exp_f32_e32 v67, v67
	s_nop 0
	v_pk_add_f32 v[66:67], v[66:67], 1.0 op_sel_hi:[1,0]
	s_nop 0
	s_nop 0
	v_rcp_f32_e32 v69, v67
	s_nop 0
	v_mul_f32_e32 v63, v63, v69
	s_nop 0
	v_rcp_f32_e32 v67, v66
	s_nop 0
	v_mul_f32_e32 v62, v62, v67
	v_pk_mul_f32 v[58:59], v[58:59], v[62:63]
	v_mul_f32_e32 v62, 0xbfb8aa3b, v55
	v_exp_f32_e32 v69, v62
	s_nop 0
	v_pk_add_f32 v[62:63], v[68:69], 1.0 op_sel_hi:[1,0]
	s_nop 0
	s_nop 0
	v_rcp_f32_e32 v66, v63
	s_nop 0
	v_mul_f32_e32 v55, v55, v66
	s_nop 0
	v_rcp_f32_e32 v63, v62
	s_nop 0
	v_mul_f32_e32 v54, v54, v63
	v_pk_mul_f32 v[54:55], v[50:51], v[54:55]
	v_mul_f32_e32 v51, 0xbfb8aa3b, v56
	v_mul_f32_e32 v50, 0xbfb8aa3b, v64
	v_exp_f32_e32 v62, v51
	v_mul_f32_e32 v51, 0xbfb8aa3b, v65
	v_exp_f32_e32 v50, v50
	v_exp_f32_e32 v51, v51
	s_nop 0
	v_pk_add_f32 v[50:51], v[50:51], 1.0 op_sel_hi:[1,0]
	s_nop 0
	s_nop 0
	v_rcp_f32_e32 v63, v51
	s_nop 0
	v_mul_f32_e32 v51, v65, v63
	s_nop 0
	v_rcp_f32_e32 v63, v50
	s_nop 0
	v_mul_f32_e32 v50, v64, v63
	v_pk_mul_f32 v[60:61], v[60:61], v[50:51]
	v_mul_f32_e32 v50, 0xbfb8aa3b, v57
	v_exp_f32_e32 v63, v50
	s_nop 0
	v_pk_add_f32 v[50:51], v[62:63], 1.0 op_sel_hi:[1,0]
	s_nop 0
	s_nop 0
	v_rcp_f32_e32 v62, v51
	s_nop 0
	v_mul_f32_e32 v51, v57, v62
	s_nop 0
	v_rcp_f32_e32 v57, v50
	s_nop 0
	v_mul_f32_e32 v50, v56, v57
	v_pk_mul_f32 v[56:57], v[52:53], v[50:51]
	v_cvt_pk_bf16_f32 v52, v54, v55
	v_mad_i64_i32 v[54:55], s[26:27], v70, s15, v[114:115]
	v_cvt_pk_bf16_f32 v50, v58, v59
	v_cvt_pk_bf16_f32 v51, v60, v61
	v_cvt_pk_bf16_f32 v53, v56, v57
	v_lshl_add_u64 v[54:55], v[54:55], 0, v[116:117]
	global_store_dwordx4 v[54:55], v[50:53], off
	s_nop 1
	v_mul_f32_e32 v51, 0xbfb8aa3b, v36
	v_mul_f32_e32 v50, 0xbfb8aa3b, v44
	v_exp_f32_e32 v52, v51
	v_mul_f32_e32 v51, 0xbfb8aa3b, v45
	v_exp_f32_e32 v50, v50
	v_exp_f32_e32 v51, v51
	s_nop 0
	v_pk_add_f32 v[50:51], v[50:51], 1.0 op_sel_hi:[1,0]
	s_nop 0
	s_nop 0
	v_rcp_f32_e32 v53, v51
	s_nop 0
	v_mul_f32_e32 v45, v45, v53
	s_nop 0
	v_rcp_f32_e32 v51, v50
	s_nop 0
	v_mul_f32_e32 v44, v44, v51
	v_pk_mul_f32 v[40:41], v[40:41], v[44:45]
	v_mul_f32_e32 v44, 0xbfb8aa3b, v37
	v_exp_f32_e32 v53, v44
	s_nop 0
	v_pk_add_f32 v[44:45], v[52:53], 1.0 op_sel_hi:[1,0]
	s_nop 0
	s_nop 0
	v_rcp_f32_e32 v50, v45
	s_nop 0
	v_mul_f32_e32 v37, v37, v50
	s_nop 0
	v_rcp_f32_e32 v45, v44
	s_nop 0
	v_mul_f32_e32 v36, v36, v45
	v_pk_mul_f32 v[36:37], v[32:33], v[36:37]
	v_mul_f32_e32 v33, 0xbfb8aa3b, v38
	v_mul_f32_e32 v32, 0xbfb8aa3b, v46
	v_exp_f32_e32 v44, v33
	v_mul_f32_e32 v33, 0xbfb8aa3b, v47
	v_exp_f32_e32 v32, v32
	v_exp_f32_e32 v33, v33
	s_nop 0
	v_pk_add_f32 v[32:33], v[32:33], 1.0 op_sel_hi:[1,0]
	s_nop 0
	s_nop 0
	v_rcp_f32_e32 v45, v33
	s_nop 0
	v_mul_f32_e32 v33, v47, v45
	s_nop 0
	v_rcp_f32_e32 v45, v32
	s_nop 0
	v_mul_f32_e32 v32, v46, v45
	v_pk_mul_f32 v[42:43], v[42:43], v[32:33]
	v_mul_f32_e32 v32, 0xbfb8aa3b, v39
	v_exp_f32_e32 v45, v32
	s_nop 0
	v_pk_add_f32 v[32:33], v[44:45], 1.0 op_sel_hi:[1,0]
	s_nop 0
	s_nop 0
	v_rcp_f32_e32 v44, v33
	s_nop 0
	v_mul_f32_e32 v33, v39, v44
	s_nop 0
	v_rcp_f32_e32 v39, v32
	s_nop 0
	v_mul_f32_e32 v32, v38, v39
	v_add_u32_e32 v44, 0x90, v146
	v_pk_mul_f32 v[38:39], v[34:35], v[32:33]
	v_cvt_pk_bf16_f32 v34, v36, v37
	v_mad_i64_i32 v[36:37], s[26:27], v44, s15, v[114:115]
	v_cvt_pk_bf16_f32 v32, v40, v41
	v_cvt_pk_bf16_f32 v33, v42, v43
	v_cvt_pk_bf16_f32 v35, v38, v39
	v_lshl_add_u64 v[36:37], v[36:37], 0, v[116:117]
	global_store_dwordx4 v[36:37], v[32:35], off
	s_nop 1
	v_mul_f32_e32 v33, 0xbfb8aa3b, v20
	v_mul_f32_e32 v32, 0xbfb8aa3b, v28
	v_exp_f32_e32 v34, v33
	v_mul_f32_e32 v33, 0xbfb8aa3b, v29
	v_exp_f32_e32 v32, v32
	v_exp_f32_e32 v33, v33
	s_nop 0
	v_pk_add_f32 v[32:33], v[32:33], 1.0 op_sel_hi:[1,0]
	s_nop 0
	s_nop 0
	v_rcp_f32_e32 v35, v33
	s_nop 0
	v_mul_f32_e32 v29, v29, v35
	s_nop 0
	v_rcp_f32_e32 v33, v32
	s_nop 0
	v_mul_f32_e32 v28, v28, v33
	v_pk_mul_f32 v[24:25], v[24:25], v[28:29]
	v_mul_f32_e32 v28, 0xbfb8aa3b, v21
	v_exp_f32_e32 v35, v28
	s_nop 0
	v_pk_add_f32 v[28:29], v[34:35], 1.0 op_sel_hi:[1,0]
	s_nop 0
	s_nop 0
	v_rcp_f32_e32 v32, v29
	s_nop 0
	v_mul_f32_e32 v21, v21, v32
	s_nop 0
	v_rcp_f32_e32 v29, v28
	s_nop 0
	v_mul_f32_e32 v20, v20, v29
	v_pk_mul_f32 v[20:21], v[16:17], v[20:21]
	v_mul_f32_e32 v17, 0xbfb8aa3b, v22
	v_mul_f32_e32 v16, 0xbfb8aa3b, v30
	v_exp_f32_e32 v28, v17
	v_mul_f32_e32 v17, 0xbfb8aa3b, v31
	v_exp_f32_e32 v16, v16
	v_exp_f32_e32 v17, v17
	s_nop 0
	v_pk_add_f32 v[16:17], v[16:17], 1.0 op_sel_hi:[1,0]
	s_nop 0
	s_nop 0
	v_rcp_f32_e32 v29, v17
	s_nop 0
	v_mul_f32_e32 v17, v31, v29
	s_nop 0
	v_rcp_f32_e32 v29, v16
	s_nop 0
	v_mul_f32_e32 v16, v30, v29
	v_pk_mul_f32 v[26:27], v[26:27], v[16:17]
	v_mul_f32_e32 v16, 0xbfb8aa3b, v23
	v_exp_f32_e32 v29, v16
	s_nop 0
	v_pk_add_f32 v[16:17], v[28:29], 1.0 op_sel_hi:[1,0]
	s_nop 0
	s_nop 0
	v_rcp_f32_e32 v28, v17
	s_nop 0
	v_mul_f32_e32 v17, v23, v28
	s_nop 0
	v_rcp_f32_e32 v23, v16
	s_nop 0
	v_mul_f32_e32 v16, v22, v23
	v_add_u32_e32 v28, 0xa0, v146
	v_pk_mul_f32 v[22:23], v[18:19], v[16:17]
	v_cvt_pk_bf16_f32 v18, v20, v21
	v_mad_i64_i32 v[20:21], s[26:27], v28, s15, v[114:115]
	v_cvt_pk_bf16_f32 v16, v24, v25
	v_cvt_pk_bf16_f32 v17, v26, v27
	v_cvt_pk_bf16_f32 v19, v22, v23
	v_lshl_add_u64 v[20:21], v[20:21], 0, v[116:117]
	global_store_dwordx4 v[20:21], v[16:19], off
	s_nop 1
	v_mul_f32_e32 v17, 0xbfb8aa3b, v4
	v_mul_f32_e32 v16, 0xbfb8aa3b, v12
	v_exp_f32_e32 v18, v17
	v_mul_f32_e32 v17, 0xbfb8aa3b, v13
	v_exp_f32_e32 v16, v16
	v_exp_f32_e32 v17, v17
	s_nop 0
	v_pk_add_f32 v[16:17], v[16:17], 1.0 op_sel_hi:[1,0]
	s_nop 0
	s_nop 0
	v_rcp_f32_e32 v19, v17
	s_nop 0
	v_mul_f32_e32 v13, v13, v19
	s_nop 0
	v_rcp_f32_e32 v17, v16
	s_nop 0
	v_mul_f32_e32 v12, v12, v17
	v_pk_mul_f32 v[8:9], v[8:9], v[12:13]
	v_mul_f32_e32 v12, 0xbfb8aa3b, v5
	v_exp_f32_e32 v19, v12
	s_nop 0
	v_pk_add_f32 v[12:13], v[18:19], 1.0 op_sel_hi:[1,0]
	s_nop 0
	s_nop 0
	v_rcp_f32_e32 v16, v13
	s_nop 0
	v_mul_f32_e32 v5, v5, v16
	s_nop 0
	v_rcp_f32_e32 v13, v12
	s_nop 0
	v_mul_f32_e32 v4, v4, v13
	v_pk_mul_f32 v[4:5], v[0:1], v[4:5]
	v_mul_f32_e32 v1, 0xbfb8aa3b, v6
	v_mul_f32_e32 v0, 0xbfb8aa3b, v14
	v_exp_f32_e32 v12, v1
	v_mul_f32_e32 v1, 0xbfb8aa3b, v15
	v_exp_f32_e32 v0, v0
	v_exp_f32_e32 v1, v1
	s_nop 0
	v_pk_add_f32 v[0:1], v[0:1], 1.0 op_sel_hi:[1,0]
	s_nop 0
	s_nop 0
	v_rcp_f32_e32 v13, v1
	s_nop 0
	v_mul_f32_e32 v1, v15, v13
	s_nop 0
	v_rcp_f32_e32 v13, v0
	s_nop 0
	v_mul_f32_e32 v0, v14, v13
	v_pk_mul_f32 v[10:11], v[10:11], v[0:1]
	v_mul_f32_e32 v0, 0xbfb8aa3b, v7
	v_exp_f32_e32 v13, v0
	s_nop 0
	v_pk_add_f32 v[0:1], v[12:13], 1.0 op_sel_hi:[1,0]
	s_nop 0
	s_nop 0
	v_rcp_f32_e32 v12, v1
	s_nop 0
	v_mul_f32_e32 v1, v7, v12
	s_nop 0
	v_rcp_f32_e32 v7, v0
	s_nop 0
	v_mul_f32_e32 v0, v6, v7
	v_add_u32_e32 v12, 0xb0, v146
	v_pk_mul_f32 v[6:7], v[2:3], v[0:1]
	v_cvt_pk_bf16_f32 v2, v4, v5
	v_mad_i64_i32 v[4:5], s[26:27], v12, s15, v[114:115]
	v_cvt_pk_bf16_f32 v0, v8, v9
	v_cvt_pk_bf16_f32 v1, v10, v11
	v_cvt_pk_bf16_f32 v3, v6, v7
	v_lshl_add_u64 v[4:5], v[4:5], 0, v[116:117]
	s_and_b64 vcc, exec, s[0:1]
	s_mov_b64 s[26:27], s[18:19]
	global_store_dwordx4 v[4:5], v[0:3], off
	s_cbranch_vccz .LBB0_1353
	s_waitcnt vmcnt(0)
	s_cmpk_gt_u32 s5, 0xff
	s_cbranch_scc1 .LBB0_1360
	s_barrier

.LBB0_1421:
	s_add_u32 s18, s16, 0x100
	s_addc_u32 s19, s17, 0
	s_add_i32 s47, 0, 0x10000
	v_add_u32_e32 v142, s47, v204
	ds_read_b128 v[130:133], v142
	ds_read_b128 v[134:137], v142 offset:1024
	ds_read_b128 v[138:141], v142 offset:2048
	ds_read_b128 v[142:145], v142 offset:3072
	s_cmp_eq_u32 s46, 40
	s_cselect_b32 s23, s11, s19
	s_cselect_b32 s22, s10, s18
	s_cselect_b32 s21, s13, s45
	s_cselect_b32 s20, s12, s44
	v_lshl_add_u64 v[188:189], s[16:17], 0, v[152:153]
	s_add_i32 m0, s31, 0xc000
	ds_read_b128 v[156:159], v206
	ds_read_b128 v[160:163], v206 offset:1024
	ds_read_b128 v[164:167], v206 offset:2048
	ds_read_b128 v[168:171], v206 offset:3072
	ds_read_b128 v[172:175], v206 offset:4096
	ds_read_b128 v[176:179], v206 offset:5120
	ds_read_b128 v[180:183], v206 offset:6144
	ds_read_b128 v[184:187], v206 offset:7168
	global_load_lds_dwordx4 v[188:189], off
	v_lshl_add_u64 v[188:189], s[16:17], 0, v[154:155]
	s_add_i32 m0, s31, 0xe000
	s_nop 0
	global_load_lds_dwordx4 v[188:189], off
	s_waitcnt lgkmcnt(8)
	s_barrier
	s_waitcnt lgkmcnt(0)
	s_setprio 1
	s_waitcnt lgkmcnt(0)
	v_mfma_f32_16x16x32_bf16 v[126:129], v[130:133], v[156:159], v[126:129]
	v_mfma_f32_16x16x32_bf16 v[122:125], v[138:141], v[156:159], v[122:125]
	v_mfma_f32_16x16x32_bf16 v[114:117], v[130:133], v[164:167], v[114:117]
	v_mfma_f32_16x16x32_bf16 v[106:109], v[138:141], v[164:167], v[106:109]
	v_mfma_f32_16x16x32_bf16 v[98:101], v[130:133], v[172:175], v[98:101]
	v_mfma_f32_16x16x32_bf16 v[90:93], v[138:141], v[172:175], v[90:93]
	v_mfma_f32_16x16x32_bf16 v[82:85], v[130:133], v[180:183], v[82:85]
	v_mfma_f32_16x16x32_bf16 v[74:77], v[138:141], v[180:183], v[74:77]
	v_mfma_f32_16x16x32_bf16 v[126:129], v[134:137], v[160:163], v[126:129]
	v_mfma_f32_16x16x32_bf16 v[122:125], v[142:145], v[160:163], v[122:125]
	v_mfma_f32_16x16x32_bf16 v[114:117], v[134:137], v[168:171], v[114:117]
	v_mfma_f32_16x16x32_bf16 v[106:109], v[142:145], v[168:171], v[106:109]
	v_mfma_f32_16x16x32_bf16 v[98:101], v[134:137], v[176:179], v[98:101]
	v_mfma_f32_16x16x32_bf16 v[90:93], v[142:145], v[176:179], v[90:93]
	v_mfma_f32_16x16x32_bf16 v[82:85], v[134:137], v[184:187], v[82:85]
	v_mfma_f32_16x16x32_bf16 v[74:77], v[142:145], v[184:187], v[74:77]
	s_setprio 0
	s_barrier
	s_add_i32 s48, 0, 0x14000
	v_add_u32_e32 v192, s48, v204
	s_add_i32 s16, s47, s25
	ds_read_b128 v[188:191], v192
	ds_read_b128 v[198:201], v192 offset:1024
	ds_read_b128 v[208:211], v192 offset:2048
	ds_read_b128 v[212:215], v192 offset:3072
	v_lshl_add_u64 v[192:193], s[20:21], 0, v[48:49]
	s_mov_b32 m0, s16
	v_lshl_add_u64 v[202:203], s[20:21], 0, v[146:147]
	global_load_lds_dwordx4 v[192:193], off
	s_add_i32 m0, s16, 0x2000
	s_nop 0
	global_load_lds_dwordx4 v[202:203], off
	s_barrier
	s_waitcnt lgkmcnt(0)
	s_setprio 1
	s_waitcnt lgkmcnt(0)
	v_mfma_f32_16x16x32_bf16 v[118:121], v[188:191], v[156:159], v[118:121]
	v_mfma_f32_16x16x32_bf16 v[110:113], v[208:211], v[156:159], v[110:113]
	v_mfma_f32_16x16x32_bf16 v[102:105], v[188:191], v[164:167], v[102:105]
	v_mfma_f32_16x16x32_bf16 v[94:97], v[208:211], v[164:167], v[94:97]
	v_mfma_f32_16x16x32_bf16 v[86:89], v[188:191], v[172:175], v[86:89]
	v_mfma_f32_16x16x32_bf16 v[78:81], v[208:211], v[172:175], v[78:81]
	v_mfma_f32_16x16x32_bf16 v[70:73], v[188:191], v[180:183], v[70:73]
	v_mfma_f32_16x16x32_bf16 v[66:69], v[208:211], v[180:183], v[66:69]
	v_mfma_f32_16x16x32_bf16 v[118:121], v[198:201], v[160:163], v[118:121]
	v_mfma_f32_16x16x32_bf16 v[110:113], v[212:215], v[160:163], v[110:113]
	v_mfma_f32_16x16x32_bf16 v[102:105], v[198:201], v[168:171], v[102:105]
	v_mfma_f32_16x16x32_bf16 v[94:97], v[212:215], v[168:171], v[94:97]
	v_mfma_f32_16x16x32_bf16 v[86:89], v[198:201], v[176:179], v[86:89]
	v_mfma_f32_16x16x32_bf16 v[78:81], v[212:215], v[176:179], v[78:81]
	v_mfma_f32_16x16x32_bf16 v[70:73], v[198:201], v[184:187], v[70:73]
	v_mfma_f32_16x16x32_bf16 v[66:69], v[212:215], v[184:187], v[66:69]
	s_setprio 0
	s_mov_b32 m0, s31
	v_lshl_add_u64 v[216:217], s[22:23], 0, v[48:49]
	s_barrier
	ds_read_b128 v[156:159], v206 offset:16384
	ds_read_b128 v[160:163], v206 offset:17408
	ds_read_b128 v[164:167], v206 offset:18432
	ds_read_b128 v[168:171], v206 offset:19456
	ds_read_b128 v[172:175], v206 offset:20480
	ds_read_b128 v[176:179], v206 offset:21504
	ds_read_b128 v[180:183], v206 offset:22528
	ds_read_b128 v[184:187], v206 offset:23552
	global_load_lds_dwordx4 v[216:217], off
	v_lshl_add_u64 v[218:219], s[22:23], 0, v[146:147]
	s_mov_b32 m0, s34
	s_nop 0
	global_load_lds_dwordx4 v[218:219], off
	s_barrier
	s_waitcnt lgkmcnt(0)
	s_setprio 1
	s_waitcnt lgkmcnt(0)
	v_mfma_f32_16x16x32_bf16 v[62:65], v[130:133], v[156:159], v[62:65]
	v_mfma_f32_16x16x32_bf16 v[58:61], v[138:141], v[156:159], v[58:61]
	v_mfma_f32_16x16x32_bf16 v[50:53], v[130:133], v[164:167], v[50:53]
	v_mfma_f32_16x16x32_bf16 v[40:43], v[138:141], v[164:167], v[40:43]
	v_mfma_f32_16x16x32_bf16 v[32:35], v[130:133], v[172:175], v[32:35]
	v_mfma_f32_16x16x32_bf16 v[24:27], v[138:141], v[172:175], v[24:27]
	v_mfma_f32_16x16x32_bf16 v[16:19], v[130:133], v[180:183], v[16:19]
	v_mfma_f32_16x16x32_bf16 v[8:11], v[138:141], v[180:183], v[8:11]
	v_mfma_f32_16x16x32_bf16 v[62:65], v[134:137], v[160:163], v[62:65]
	v_mfma_f32_16x16x32_bf16 v[58:61], v[142:145], v[160:163], v[58:61]
	v_mfma_f32_16x16x32_bf16 v[50:53], v[134:137], v[168:171], v[50:53]
	v_mfma_f32_16x16x32_bf16 v[40:43], v[142:145], v[168:171], v[40:43]
	v_mfma_f32_16x16x32_bf16 v[32:35], v[134:137], v[176:179], v[32:35]
	v_mfma_f32_16x16x32_bf16 v[24:27], v[142:145], v[176:179], v[24:27]
	v_mfma_f32_16x16x32_bf16 v[16:19], v[134:137], v[184:187], v[16:19]
	v_mfma_f32_16x16x32_bf16 v[8:11], v[142:145], v[184:187], v[8:11]
	s_setprio 0
	s_barrier
	s_add_u32 s16, s20, 0xb0000
	s_addc_u32 s17, s21, 0
	s_add_i32 s47, s48, s25
	v_lshl_add_u64 v[130:131], s[16:17], 0, v[48:49]
	s_mov_b32 m0, s47
	s_nop 0
	global_load_lds_dwordx4 v[130:131], off
	s_add_i32 m0, s47, 0x2000
	s_nop 0
	global_load_lds_dwordx4 v146, s[16:17]
	s_waitcnt vmcnt(6)
	s_barrier
	s_setprio 1
	v_mfma_f32_16x16x32_bf16 v[54:57], v[188:191], v[156:159], v[54:57]
	v_mfma_f32_16x16x32_bf16 v[44:47], v[208:211], v[156:159], v[44:47]
	v_mfma_f32_16x16x32_bf16 v[36:39], v[188:191], v[164:167], v[36:39]
	v_mfma_f32_16x16x32_bf16 v[28:31], v[208:211], v[164:167], v[28:31]
	v_mfma_f32_16x16x32_bf16 v[20:23], v[188:191], v[172:175], v[20:23]
	v_mfma_f32_16x16x32_bf16 v[12:15], v[208:211], v[172:175], v[12:15]
	v_mfma_f32_16x16x32_bf16 v[4:7], v[188:191], v[180:183], v[4:7]
	v_mfma_f32_16x16x32_bf16 v[0:3], v[208:211], v[180:183], v[0:3]
	v_mfma_f32_16x16x32_bf16 v[54:57], v[198:201], v[160:163], v[54:57]
	v_mfma_f32_16x16x32_bf16 v[44:47], v[212:215], v[160:163], v[44:47]
	v_mfma_f32_16x16x32_bf16 v[36:39], v[198:201], v[168:171], v[36:39]
	v_mfma_f32_16x16x32_bf16 v[28:31], v[212:215], v[168:171], v[28:31]
	v_mfma_f32_16x16x32_bf16 v[20:23], v[198:201], v[176:179], v[20:23]
	v_mfma_f32_16x16x32_bf16 v[12:15], v[212:215], v[176:179], v[12:15]
	v_mfma_f32_16x16x32_bf16 v[4:7], v[198:201], v[184:187], v[4:7]
	v_mfma_f32_16x16x32_bf16 v[0:3], v[212:215], v[184:187], v[0:3]
	s_setprio 0
	s_add_i32 s47, 0, 0x18000
	v_add_u32_e32 v142, s47, v204
	s_barrier
	ds_read_b128 v[130:133], v142
	ds_read_b128 v[134:137], v142 offset:1024
	ds_read_b128 v[138:141], v142 offset:2048
	ds_read_b128 v[142:145], v142 offset:3072
	s_add_u32 s16, s22, 0xb0000
	s_addc_u32 s17, s23, 0
	s_mov_b32 m0, s35
	v_lshl_add_u64 v[188:189], s[16:17], 0, v[48:49]
	ds_read_b128 v[156:159], v206 offset:32768
	ds_read_b128 v[160:163], v206 offset:33792
	ds_read_b128 v[164:167], v206 offset:34816
	ds_read_b128 v[168:171], v206 offset:35840
	ds_read_b128 v[172:175], v206 offset:36864
	ds_read_b128 v[176:179], v206 offset:37888
	ds_read_b128 v[180:183], v206 offset:38912
	ds_read_b128 v[184:187], v206 offset:39936
	global_load_lds_dwordx4 v[188:189], off
	s_mov_b32 m0, s36
	s_nop 0
	global_load_lds_dwordx4 v146, s[16:17]
	s_waitcnt lgkmcnt(8)
	s_barrier
	s_waitcnt lgkmcnt(0)
	s_setprio 1
	s_waitcnt lgkmcnt(0)
	v_mfma_f32_16x16x32_bf16 v[126:129], v[130:133], v[156:159], v[126:129]
	v_mfma_f32_16x16x32_bf16 v[122:125], v[138:141], v[156:159], v[122:125]
	v_mfma_f32_16x16x32_bf16 v[114:117], v[130:133], v[164:167], v[114:117]
	v_mfma_f32_16x16x32_bf16 v[106:109], v[138:141], v[164:167], v[106:109]
	v_mfma_f32_16x16x32_bf16 v[98:101], v[130:133], v[172:175], v[98:101]
	v_mfma_f32_16x16x32_bf16 v[90:93], v[138:141], v[172:175], v[90:93]
	v_mfma_f32_16x16x32_bf16 v[82:85], v[130:133], v[180:183], v[82:85]
	v_mfma_f32_16x16x32_bf16 v[74:77], v[138:141], v[180:183], v[74:77]
	v_mfma_f32_16x16x32_bf16 v[126:129], v[134:137], v[160:163], v[126:129]
	v_mfma_f32_16x16x32_bf16 v[122:125], v[142:145], v[160:163], v[122:125]
	v_mfma_f32_16x16x32_bf16 v[114:117], v[134:137], v[168:171], v[114:117]
	v_mfma_f32_16x16x32_bf16 v[106:109], v[142:145], v[168:171], v[106:109]
	v_mfma_f32_16x16x32_bf16 v[98:101], v[134:137], v[176:179], v[98:101]
	v_mfma_f32_16x16x32_bf16 v[90:93], v[142:145], v[176:179], v[90:93]
	v_mfma_f32_16x16x32_bf16 v[82:85], v[134:137], v[184:187], v[82:85]
	v_mfma_f32_16x16x32_bf16 v[74:77], v[142:145], v[184:187], v[74:77]
	s_setprio 0
	s_barrier
	s_add_i32 s22, 0, 0x1c000
	s_add_i32 s16, s47, s25
	v_add_u32_e32 v207, s22, v204
	v_lshl_add_u64 v[192:193], v[192:193], 0, s[66:67]
	s_mov_b32 m0, s16
	ds_read_b128 v[188:191], v207
	ds_read_b128 v[198:201], v207 offset:1024
	ds_read_b128 v[208:211], v207 offset:2048
	ds_read_b128 v[212:215], v207 offset:3072
	global_load_lds_dwordx4 v[192:193], off
	v_lshl_add_u64 v[192:193], v[202:203], 0, s[66:67]
	s_add_i32 m0, s16, 0x2000
	s_nop 0
	global_load_lds_dwordx4 v[192:193], off
	s_barrier
	s_waitcnt lgkmcnt(0)
	s_setprio 1
	s_waitcnt lgkmcnt(0)
	v_mfma_f32_16x16x32_bf16 v[118:121], v[188:191], v[156:159], v[118:121]
	v_mfma_f32_16x16x32_bf16 v[110:113], v[208:211], v[156:159], v[110:113]
	v_mfma_f32_16x16x32_bf16 v[102:105], v[188:191], v[164:167], v[102:105]
	v_mfma_f32_16x16x32_bf16 v[94:97], v[208:211], v[164:167], v[94:97]
	v_mfma_f32_16x16x32_bf16 v[86:89], v[188:191], v[172:175], v[86:89]
	v_mfma_f32_16x16x32_bf16 v[78:81], v[208:211], v[172:175], v[78:81]
	v_mfma_f32_16x16x32_bf16 v[70:73], v[188:191], v[180:183], v[70:73]
	v_mfma_f32_16x16x32_bf16 v[66:69], v[208:211], v[180:183], v[66:69]
	v_mfma_f32_16x16x32_bf16 v[118:121], v[198:201], v[160:163], v[118:121]
	v_mfma_f32_16x16x32_bf16 v[110:113], v[212:215], v[160:163], v[110:113]
	v_mfma_f32_16x16x32_bf16 v[102:105], v[198:201], v[168:171], v[102:105]
	v_mfma_f32_16x16x32_bf16 v[94:97], v[212:215], v[168:171], v[94:97]
	v_mfma_f32_16x16x32_bf16 v[86:89], v[198:201], v[176:179], v[86:89]
	v_mfma_f32_16x16x32_bf16 v[78:81], v[212:215], v[176:179], v[78:81]
	v_mfma_f32_16x16x32_bf16 v[70:73], v[198:201], v[184:187], v[70:73]
	v_mfma_f32_16x16x32_bf16 v[66:69], v[212:215], v[184:187], v[66:69]
	s_setprio 0
	s_mov_b32 m0, s39
	v_lshl_add_u64 v[192:193], v[216:217], 0, s[66:67]
	s_barrier
	ds_read_b128 v[156:159], v206 offset:49152
	ds_read_b128 v[160:163], v206 offset:50176
	ds_read_b128 v[164:167], v206 offset:51200
	ds_read_b128 v[168:171], v206 offset:52224
	ds_read_b128 v[172:175], v206 offset:53248
	ds_read_b128 v[176:179], v206 offset:54272
	ds_read_b128 v[180:183], v206 offset:55296
	ds_read_b128 v[184:187], v206 offset:56320
	global_load_lds_dwordx4 v[192:193], off
	v_lshl_add_u64 v[192:193], v[218:219], 0, s[66:67]
	s_mov_b32 m0, s40
	s_nop 0
	global_load_lds_dwordx4 v[192:193], off
	s_barrier
	s_waitcnt lgkmcnt(0)
	s_setprio 1
	s_waitcnt lgkmcnt(0)
	v_mfma_f32_16x16x32_bf16 v[62:65], v[130:133], v[156:159], v[62:65]
	v_mfma_f32_16x16x32_bf16 v[58:61], v[138:141], v[156:159], v[58:61]
	v_mfma_f32_16x16x32_bf16 v[50:53], v[130:133], v[164:167], v[50:53]
	v_mfma_f32_16x16x32_bf16 v[40:43], v[138:141], v[164:167], v[40:43]
	v_mfma_f32_16x16x32_bf16 v[32:35], v[130:133], v[172:175], v[32:35]
	v_mfma_f32_16x16x32_bf16 v[24:27], v[138:141], v[172:175], v[24:27]
	v_mfma_f32_16x16x32_bf16 v[16:19], v[130:133], v[180:183], v[16:19]
	v_mfma_f32_16x16x32_bf16 v[8:11], v[138:141], v[180:183], v[8:11]
	v_mfma_f32_16x16x32_bf16 v[62:65], v[134:137], v[160:163], v[62:65]
	v_mfma_f32_16x16x32_bf16 v[58:61], v[142:145], v[160:163], v[58:61]
	v_mfma_f32_16x16x32_bf16 v[50:53], v[134:137], v[168:171], v[50:53]
	v_mfma_f32_16x16x32_bf16 v[40:43], v[142:145], v[168:171], v[40:43]
	v_mfma_f32_16x16x32_bf16 v[32:35], v[134:137], v[176:179], v[32:35]
	v_mfma_f32_16x16x32_bf16 v[24:27], v[142:145], v[176:179], v[24:27]
	v_mfma_f32_16x16x32_bf16 v[16:19], v[134:137], v[184:187], v[16:19]
	v_mfma_f32_16x16x32_bf16 v[8:11], v[142:145], v[184:187], v[8:11]
	s_setprio 0
	s_barrier
	s_add_u32 s16, s20, 0xb0080
	s_addc_u32 s17, s21, 0
	s_add_i32 s20, s22, s25
	v_lshl_add_u64 v[130:131], s[16:17], 0, v[48:49]
	s_mov_b32 m0, s20
	s_nop 0
	global_load_lds_dwordx4 v[130:131], off
	s_add_i32 m0, s20, 0x2000
	s_nop 0
	global_load_lds_dwordx4 v146, s[16:17]
	s_waitcnt vmcnt(6)
	s_barrier
	s_setprio 1
	v_mfma_f32_16x16x32_bf16 v[54:57], v[188:191], v[156:159], v[54:57]
	v_mfma_f32_16x16x32_bf16 v[44:47], v[208:211], v[156:159], v[44:47]
	v_mfma_f32_16x16x32_bf16 v[36:39], v[188:191], v[164:167], v[36:39]
	v_mfma_f32_16x16x32_bf16 v[28:31], v[208:211], v[164:167], v[28:31]
	v_mfma_f32_16x16x32_bf16 v[20:23], v[188:191], v[172:175], v[20:23]
	v_mfma_f32_16x16x32_bf16 v[12:15], v[208:211], v[172:175], v[12:15]
	v_mfma_f32_16x16x32_bf16 v[4:7], v[188:191], v[180:183], v[4:7]
	v_mfma_f32_16x16x32_bf16 v[0:3], v[208:211], v[180:183], v[0:3]
	v_mfma_f32_16x16x32_bf16 v[54:57], v[198:201], v[160:163], v[54:57]
	v_mfma_f32_16x16x32_bf16 v[44:47], v[212:215], v[160:163], v[44:47]
	v_mfma_f32_16x16x32_bf16 v[36:39], v[198:201], v[168:171], v[36:39]
	v_mfma_f32_16x16x32_bf16 v[28:31], v[212:215], v[168:171], v[28:31]
	v_mfma_f32_16x16x32_bf16 v[20:23], v[198:201], v[176:179], v[20:23]
	v_mfma_f32_16x16x32_bf16 v[12:15], v[212:215], v[176:179], v[12:15]
	v_mfma_f32_16x16x32_bf16 v[4:7], v[198:201], v[184:187], v[4:7]
	v_mfma_f32_16x16x32_bf16 v[0:3], v[212:215], v[184:187], v[0:3]
	s_setprio 0
	s_add_i32 s46, s46, 2
	s_add_u32 s44, s44, 0x100
	s_addc_u32 s45, s45, 0
	s_cmp_gt_u32 s46, 41
	s_mov_b64 s[16:17], s[18:19]
	s_barrier
	s_cbranch_scc0 .LBB0_1421
	s_mul_hi_i32 s16, s14, 0x38e38e39
	s_lshr_b32 s17, s16, 31
	s_ashr_i32 s16, s16, 1
	s_add_i32 s16, s16, s17
	s_mul_i32 s17, s16, -9
	v_lshl_or_b32 v156, s15, 8, v205
	s_ashr_i32 s15, s14, 31
	s_add_i32 s18, s17, s14
	s_lshl_b64 s[14:15], s[14:15], 19
	s_ashr_i32 s17, s16, 31
	v_lshl_add_u64 v[158:159], v[150:151], 0, s[14:15]
	v_sub_co_u32_e64 v130, s[14:15], s18, 1
	s_lshl_b64 s[18:19], s[16:17], 23
	s_and_b64 s[14:15], s[14:15], exec
	v_ashrrev_i32_e32 v131, 31, v130
	s_cselect_b32 s14, 32, s16
	v_lshlrev_b64 v[130:131], 20, v[130:131]
	s_mul_hi_i32 s15, s14, 0x6000
	s_mulk_i32 s14, 0x6000
	v_ashrrev_i32_e32 v157, 31, v156
	v_lshl_add_u64 v[130:131], s[6:7], 0, v[130:131]
	s_add_u32 s14, s37, s14
	v_lshl_add_u64 v[130:131], v[130:131], 0, s[18:19]
	s_addc_u32 s15, s38, s15
	v_lshlrev_b64 v[208:209], 2, v[156:157]
	v_lshl_add_u64 v[162:163], v[130:131], 0, v[148:149]
	v_lshl_add_u64 v[130:131], s[14:15], 0, v[208:209]
	v_lshl_add_u64 v[156:157], v[156:157], 1, v[158:159]
	global_load_dwordx4 v[142:145], v[130:131], off
	global_load_dwordx4 v[138:141], v[130:131], off offset:64
	global_load_dwordx4 v[134:137], v[130:131], off offset:512
	s_nop 0
	global_load_dwordx4 v[130:133], v[130:131], off offset:576
	s_nop 0
	s_mov_b32 s14, 0x40000
	s_nop 0
	v_lshl_add_u64 v[162:163], v[162:163], 0, v[208:209]
	s_nop 0
	s_mov_b32 s15, s42
	s_nop 0
	s_mov_b32 s14, 0x48000
	s_nop 0
	s_mov_b32 s14, 0x50000
	s_nop 0
	s_mov_b32 s14, 0x58000
	s_nop 0
	s_mov_b32 s14, 0x20000
	s_nop 0
	s_nop 0
	s_mov_b64 s[18:19], s[12:13]
	s_mov_b64 s[16:17], s[10:11]
	v_and_b32_e32 v202, 16, v224
	v_lshrrev_b32_e32 v203, 1, v202
	v_add_u32_e32 v202, v202, v203
	v_mov_b32_e32 v203, 0
	v_mov_b32_e32 v223, 0
	v_lshl_add_u64 v[246:247], v[156:157], 0, v[202:203]
	v_mov_b32_e32 v222, 0x0
	v_lshl_add_u64 v[190:191], v[246:247], 0, v[222:223]
	global_load_dwordx4 v[198:201], v[190:191], off
	global_load_dwordx4 v[218:221], v[190:191], off offset:256
	v_mov_b32_e32 v222, 0x8000
	v_lshl_add_u64 v[190:191], v[246:247], 0, v[222:223]
	global_load_dwordx4 v[242:245], v[190:191], off
	global_load_dwordx4 v[164:167], v[190:191], off offset:256
	v_mov_b32_e32 v222, 0x10000
	v_lshl_add_u64 v[190:191], v[246:247], 0, v[222:223]
	global_load_dwordx4 v[168:171], v[190:191], off
	global_load_dwordx4 v[172:175], v[190:191], off offset:256
	v_mov_b32_e32 v222, 0x18000
	v_lshl_add_u64 v[190:191], v[246:247], 0, v[222:223]
	global_load_dwordx4 v[176:179], v[190:191], off
	global_load_dwordx4 v[180:183], v[190:191], off offset:256
	v_mov_b32_e32 v222, 0x40000
	v_lshl_add_u64 v[190:191], v[246:247], 0, v[222:223]
	global_load_dwordx4 v[184:187], v[190:191], off
	s_waitcnt vmcnt(8)
	v_permlane16_swap_b32 v198, v200
	v_permlane16_swap_b32 v199, v201
	s_nop 1
	v_lshlrev_b32_e32 v210, 16, v198
	v_and_b32_e32 v211, 0xffff0000, v198
	v_lshlrev_b32_e32 v212, 16, v199
	v_and_b32_e32 v213, 0xffff0000, v199
	v_pk_fma_f32 v[126:127], v[126:127], v[142:143], v[210:211]
	v_pk_fma_f32 v[128:129], v[128:129], v[144:145], v[212:213]
	v_lshlrev_b32_e32 v214, 16, v200
	v_and_b32_e32 v215, 0xffff0000, v200
	v_lshlrev_b32_e32 v216, 16, v201
	v_and_b32_e32 v217, 0xffff0000, v201
	v_pk_fma_f32 v[122:123], v[122:123], v[138:139], v[214:215]
	v_pk_fma_f32 v[124:125], v[124:125], v[140:141], v[216:217]
	v_mov_b32_e32 v222, 0x0
	v_lshl_add_u64 v[192:193], v[162:163], 0, v[222:223]
	global_store_dwordx4 v[192:193], v[126:129], off
	global_store_dwordx4 v[192:193], v[122:125], off offset:64
	global_load_dwordx4 v[198:201], v[190:191], off offset:256
	s_waitcnt vmcnt(10)
	v_permlane16_swap_b32 v218, v220
	v_permlane16_swap_b32 v219, v221
	s_nop 1
	v_lshlrev_b32_e32 v210, 16, v218
	v_and_b32_e32 v211, 0xffff0000, v218
	v_lshlrev_b32_e32 v212, 16, v219
	v_and_b32_e32 v213, 0xffff0000, v219
	v_pk_fma_f32 v[118:119], v[118:119], v[134:135], v[210:211]
	v_pk_fma_f32 v[120:121], v[120:121], v[136:137], v[212:213]
	v_lshlrev_b32_e32 v214, 16, v220
	v_and_b32_e32 v215, 0xffff0000, v220
	v_lshlrev_b32_e32 v216, 16, v221
	v_and_b32_e32 v217, 0xffff0000, v221
	v_pk_fma_f32 v[110:111], v[110:111], v[130:131], v[214:215]
	v_pk_fma_f32 v[112:113], v[112:113], v[132:133], v[216:217]
	v_mov_b32_e32 v222, 0x0
	v_lshl_add_u64 v[192:193], v[162:163], 0, v[222:223]
	global_store_dwordx4 v[192:193], v[118:121], off offset:512
	global_store_dwordx4 v[192:193], v[110:113], off offset:576
	v_mov_b32_e32 v222, 0x48000
	v_lshl_add_u64 v[190:191], v[246:247], 0, v[222:223]
	global_load_dwordx4 v[218:221], v[190:191], off
	s_waitcnt vmcnt(12)
	v_permlane16_swap_b32 v242, v244
	v_permlane16_swap_b32 v243, v245
	s_nop 1
	v_lshlrev_b32_e32 v210, 16, v242
	v_and_b32_e32 v211, 0xffff0000, v242
	v_lshlrev_b32_e32 v212, 16, v243
	v_and_b32_e32 v213, 0xffff0000, v243
	v_pk_fma_f32 v[114:115], v[114:115], v[142:143], v[210:211]
	v_pk_fma_f32 v[116:117], v[116:117], v[144:145], v[212:213]
	v_lshlrev_b32_e32 v214, 16, v244
	v_and_b32_e32 v215, 0xffff0000, v244
	v_lshlrev_b32_e32 v216, 16, v245
	v_and_b32_e32 v217, 0xffff0000, v245
	v_pk_fma_f32 v[106:107], v[106:107], v[138:139], v[214:215]
	v_pk_fma_f32 v[108:109], v[108:109], v[140:141], v[216:217]
	v_mov_b32_e32 v222, 0x10000
	v_lshl_add_u64 v[192:193], v[162:163], 0, v[222:223]
	global_store_dwordx4 v[192:193], v[114:117], off
	global_store_dwordx4 v[192:193], v[106:109], off offset:64
	global_load_dwordx4 v[242:245], v[190:191], off offset:256
	s_waitcnt vmcnt(14)
	v_permlane16_swap_b32 v164, v166
	v_permlane16_swap_b32 v165, v167
	s_nop 1
	v_lshlrev_b32_e32 v210, 16, v164
	v_and_b32_e32 v211, 0xffff0000, v164
	v_lshlrev_b32_e32 v212, 16, v165
	v_and_b32_e32 v213, 0xffff0000, v165
	v_pk_fma_f32 v[102:103], v[102:103], v[134:135], v[210:211]
	v_pk_fma_f32 v[104:105], v[104:105], v[136:137], v[212:213]
	v_lshlrev_b32_e32 v214, 16, v166
	v_and_b32_e32 v215, 0xffff0000, v166
	v_lshlrev_b32_e32 v216, 16, v167
	v_and_b32_e32 v217, 0xffff0000, v167
	v_pk_fma_f32 v[94:95], v[94:95], v[130:131], v[214:215]
	v_pk_fma_f32 v[96:97], v[96:97], v[132:133], v[216:217]
	v_mov_b32_e32 v222, 0x10000
	v_lshl_add_u64 v[192:193], v[162:163], 0, v[222:223]
	global_store_dwordx4 v[192:193], v[102:105], off offset:512
	global_store_dwordx4 v[192:193], v[94:97], off offset:576
	v_mov_b32_e32 v222, 0x50000
	v_lshl_add_u64 v[190:191], v[246:247], 0, v[222:223]
	global_load_dwordx4 v[164:167], v[190:191], off
	s_waitcnt vmcnt(16)
	v_permlane16_swap_b32 v168, v170
	v_permlane16_swap_b32 v169, v171
	s_nop 1
	v_lshlrev_b32_e32 v210, 16, v168
	v_and_b32_e32 v211, 0xffff0000, v168
	v_lshlrev_b32_e32 v212, 16, v169
	v_and_b32_e32 v213, 0xffff0000, v169
	v_pk_fma_f32 v[98:99], v[98:99], v[142:143], v[210:211]
	v_pk_fma_f32 v[100:101], v[100:101], v[144:145], v[212:213]
	v_lshlrev_b32_e32 v214, 16, v170
	v_and_b32_e32 v215, 0xffff0000, v170
	v_lshlrev_b32_e32 v216, 16, v171
	v_and_b32_e32 v217, 0xffff0000, v171
	v_pk_fma_f32 v[90:91], v[90:91], v[138:139], v[214:215]
	v_pk_fma_f32 v[92:93], v[92:93], v[140:141], v[216:217]
	v_mov_b32_e32 v222, 0x20000
	v_lshl_add_u64 v[192:193], v[162:163], 0, v[222:223]
	global_store_dwordx4 v[192:193], v[98:101], off
	global_store_dwordx4 v[192:193], v[90:93], off offset:64
	global_load_dwordx4 v[168:171], v[190:191], off offset:256
	s_waitcnt vmcnt(18)
	v_permlane16_swap_b32 v172, v174
	v_permlane16_swap_b32 v173, v175
	s_nop 1
	v_lshlrev_b32_e32 v210, 16, v172
	v_and_b32_e32 v211, 0xffff0000, v172
	v_lshlrev_b32_e32 v212, 16, v173
	v_and_b32_e32 v213, 0xffff0000, v173
	v_pk_fma_f32 v[86:87], v[86:87], v[134:135], v[210:211]
	v_pk_fma_f32 v[88:89], v[88:89], v[136:137], v[212:213]
	v_lshlrev_b32_e32 v214, 16, v174
	v_and_b32_e32 v215, 0xffff0000, v174
	v_lshlrev_b32_e32 v216, 16, v175
	v_and_b32_e32 v217, 0xffff0000, v175
	v_pk_fma_f32 v[78:79], v[78:79], v[130:131], v[214:215]
	v_pk_fma_f32 v[80:81], v[80:81], v[132:133], v[216:217]
	v_mov_b32_e32 v222, 0x20000
	v_lshl_add_u64 v[192:193], v[162:163], 0, v[222:223]
	global_store_dwordx4 v[192:193], v[86:89], off offset:512
	global_store_dwordx4 v[192:193], v[78:81], off offset:576
	v_mov_b32_e32 v222, 0x58000
	v_lshl_add_u64 v[190:191], v[246:247], 0, v[222:223]
	global_load_dwordx4 v[172:175], v[190:191], off
	s_waitcnt vmcnt(20)
	v_permlane16_swap_b32 v176, v178
	v_permlane16_swap_b32 v177, v179
	s_nop 1
	v_lshlrev_b32_e32 v210, 16, v176
	v_and_b32_e32 v211, 0xffff0000, v176
	v_lshlrev_b32_e32 v212, 16, v177
	v_and_b32_e32 v213, 0xffff0000, v177
	v_pk_fma_f32 v[82:83], v[82:83], v[142:143], v[210:211]
	v_pk_fma_f32 v[84:85], v[84:85], v[144:145], v[212:213]
	v_lshlrev_b32_e32 v214, 16, v178
	v_and_b32_e32 v215, 0xffff0000, v178
	v_lshlrev_b32_e32 v216, 16, v179
	v_and_b32_e32 v217, 0xffff0000, v179
	v_pk_fma_f32 v[74:75], v[74:75], v[138:139], v[214:215]
	v_pk_fma_f32 v[76:77], v[76:77], v[140:141], v[216:217]
	v_mov_b32_e32 v222, 0x30000
	v_lshl_add_u64 v[192:193], v[162:163], 0, v[222:223]
	global_store_dwordx4 v[192:193], v[82:85], off
	global_store_dwordx4 v[192:193], v[74:77], off offset:64
	global_load_dwordx4 v[176:179], v[190:191], off offset:256
	s_waitcnt vmcnt(22)
	v_permlane16_swap_b32 v180, v182
	v_permlane16_swap_b32 v181, v183
	s_nop 1
	v_lshlrev_b32_e32 v210, 16, v180
	v_and_b32_e32 v211, 0xffff0000, v180
	v_lshlrev_b32_e32 v212, 16, v181
	v_and_b32_e32 v213, 0xffff0000, v181
	v_pk_fma_f32 v[70:71], v[70:71], v[134:135], v[210:211]
	v_pk_fma_f32 v[72:73], v[72:73], v[136:137], v[212:213]
	v_lshlrev_b32_e32 v214, 16, v182
	v_and_b32_e32 v215, 0xffff0000, v182
	v_lshlrev_b32_e32 v216, 16, v183
	v_and_b32_e32 v217, 0xffff0000, v183
	v_pk_fma_f32 v[66:67], v[66:67], v[130:131], v[214:215]
	v_pk_fma_f32 v[68:69], v[68:69], v[132:133], v[216:217]
	v_mov_b32_e32 v222, 0x30000
	v_lshl_add_u64 v[192:193], v[162:163], 0, v[222:223]
	global_store_dwordx4 v[192:193], v[70:73], off offset:512
	global_store_dwordx4 v[192:193], v[66:69], off offset:576
	s_waitcnt vmcnt(23)
	v_permlane16_swap_b32 v184, v186
	v_permlane16_swap_b32 v185, v187
	s_nop 1
	v_lshlrev_b32_e32 v210, 16, v184
	v_and_b32_e32 v211, 0xffff0000, v184
	v_lshlrev_b32_e32 v212, 16, v185
	v_and_b32_e32 v213, 0xffff0000, v185
	v_pk_fma_f32 v[62:63], v[62:63], v[142:143], v[210:211]
	v_pk_fma_f32 v[64:65], v[64:65], v[144:145], v[212:213]
	v_lshlrev_b32_e32 v214, 16, v186
	v_and_b32_e32 v215, 0xffff0000, v186
	v_lshlrev_b32_e32 v216, 16, v187
	v_and_b32_e32 v217, 0xffff0000, v187
	v_pk_fma_f32 v[58:59], v[58:59], v[138:139], v[214:215]
	v_pk_fma_f32 v[60:61], v[60:61], v[140:141], v[216:217]
	v_mov_b32_e32 v222, 0x80000
	v_lshl_add_u64 v[192:193], v[162:163], 0, v[222:223]
	global_store_dwordx4 v[192:193], v[62:65], off
	global_store_dwordx4 v[192:193], v[58:61], off offset:64
	s_waitcnt vmcnt(22)
	v_permlane16_swap_b32 v198, v200
	v_permlane16_swap_b32 v199, v201
	s_nop 1
	v_lshlrev_b32_e32 v210, 16, v198
	v_and_b32_e32 v211, 0xffff0000, v198
	v_lshlrev_b32_e32 v212, 16, v199
	v_and_b32_e32 v213, 0xffff0000, v199
	v_pk_fma_f32 v[54:55], v[54:55], v[134:135], v[210:211]
	v_pk_fma_f32 v[56:57], v[56:57], v[136:137], v[212:213]
	v_lshlrev_b32_e32 v214, 16, v200
	v_and_b32_e32 v215, 0xffff0000, v200
	v_lshlrev_b32_e32 v216, 16, v201
	v_and_b32_e32 v217, 0xffff0000, v201
	v_pk_fma_f32 v[44:45], v[44:45], v[130:131], v[214:215]
	v_pk_fma_f32 v[46:47], v[46:47], v[132:133], v[216:217]
	v_mov_b32_e32 v222, 0x80000
	v_lshl_add_u64 v[192:193], v[162:163], 0, v[222:223]
	global_store_dwordx4 v[192:193], v[54:57], off offset:512
	global_store_dwordx4 v[192:193], v[44:47], off offset:576
	s_waitcnt vmcnt(21)
	v_permlane16_swap_b32 v218, v220
	v_permlane16_swap_b32 v219, v221
	s_nop 1
	v_lshlrev_b32_e32 v210, 16, v218
	v_and_b32_e32 v211, 0xffff0000, v218
	v_lshlrev_b32_e32 v212, 16, v219
	v_and_b32_e32 v213, 0xffff0000, v219
	v_pk_fma_f32 v[50:51], v[50:51], v[142:143], v[210:211]
	v_pk_fma_f32 v[52:53], v[52:53], v[144:145], v[212:213]
	v_lshlrev_b32_e32 v214, 16, v220
	v_and_b32_e32 v215, 0xffff0000, v220
	v_lshlrev_b32_e32 v216, 16, v221
	v_and_b32_e32 v217, 0xffff0000, v221
	v_pk_fma_f32 v[40:41], v[40:41], v[138:139], v[214:215]
	v_pk_fma_f32 v[42:43], v[42:43], v[140:141], v[216:217]
	v_mov_b32_e32 v222, 0x90000
	v_lshl_add_u64 v[192:193], v[162:163], 0, v[222:223]
	global_store_dwordx4 v[192:193], v[50:53], off
	global_store_dwordx4 v[192:193], v[40:43], off offset:64
	s_waitcnt vmcnt(20)
	v_permlane16_swap_b32 v242, v244
	v_permlane16_swap_b32 v243, v245
	s_nop 1
	v_lshlrev_b32_e32 v210, 16, v242
	v_and_b32_e32 v211, 0xffff0000, v242
	v_lshlrev_b32_e32 v212, 16, v243
	v_and_b32_e32 v213, 0xffff0000, v243
	v_pk_fma_f32 v[36:37], v[36:37], v[134:135], v[210:211]
	v_pk_fma_f32 v[38:39], v[38:39], v[136:137], v[212:213]
	v_lshlrev_b32_e32 v214, 16, v244
	v_and_b32_e32 v215, 0xffff0000, v244
	v_lshlrev_b32_e32 v216, 16, v245
	v_and_b32_e32 v217, 0xffff0000, v245
	v_pk_fma_f32 v[28:29], v[28:29], v[130:131], v[214:215]
	v_pk_fma_f32 v[30:31], v[30:31], v[132:133], v[216:217]
	v_mov_b32_e32 v222, 0x90000
	v_lshl_add_u64 v[192:193], v[162:163], 0, v[222:223]
	global_store_dwordx4 v[192:193], v[36:39], off offset:512
	global_store_dwordx4 v[192:193], v[28:31], off offset:576
	s_waitcnt vmcnt(19)
	v_permlane16_swap_b32 v164, v166
	v_permlane16_swap_b32 v165, v167
	s_nop 1
	v_lshlrev_b32_e32 v210, 16, v164
	v_and_b32_e32 v211, 0xffff0000, v164
	v_lshlrev_b32_e32 v212, 16, v165
	v_and_b32_e32 v213, 0xffff0000, v165
	v_pk_fma_f32 v[32:33], v[32:33], v[142:143], v[210:211]
	v_pk_fma_f32 v[34:35], v[34:35], v[144:145], v[212:213]
	v_lshlrev_b32_e32 v214, 16, v166
	v_and_b32_e32 v215, 0xffff0000, v166
	v_lshlrev_b32_e32 v216, 16, v167
	v_and_b32_e32 v217, 0xffff0000, v167
	v_pk_fma_f32 v[24:25], v[24:25], v[138:139], v[214:215]
	v_pk_fma_f32 v[26:27], v[26:27], v[140:141], v[216:217]
	v_mov_b32_e32 v222, 0xa0000
	v_lshl_add_u64 v[192:193], v[162:163], 0, v[222:223]
	global_store_dwordx4 v[192:193], v[32:35], off
	global_store_dwordx4 v[192:193], v[24:27], off offset:64
	s_waitcnt vmcnt(18)
	v_permlane16_swap_b32 v168, v170
	v_permlane16_swap_b32 v169, v171
	s_nop 1
	v_lshlrev_b32_e32 v210, 16, v168
	v_and_b32_e32 v211, 0xffff0000, v168
	v_lshlrev_b32_e32 v212, 16, v169
	v_and_b32_e32 v213, 0xffff0000, v169
	v_pk_fma_f32 v[20:21], v[20:21], v[134:135], v[210:211]
	v_pk_fma_f32 v[22:23], v[22:23], v[136:137], v[212:213]
	v_lshlrev_b32_e32 v214, 16, v170
	v_and_b32_e32 v215, 0xffff0000, v170
	v_lshlrev_b32_e32 v216, 16, v171
	v_and_b32_e32 v217, 0xffff0000, v171
	v_pk_fma_f32 v[12:13], v[12:13], v[130:131], v[214:215]
	v_pk_fma_f32 v[14:15], v[14:15], v[132:133], v[216:217]
	v_mov_b32_e32 v222, 0xa0000
	v_lshl_add_u64 v[192:193], v[162:163], 0, v[222:223]
	global_store_dwordx4 v[192:193], v[20:23], off offset:512
	global_store_dwordx4 v[192:193], v[12:15], off offset:576
	s_waitcnt vmcnt(17)
	v_permlane16_swap_b32 v172, v174
	v_permlane16_swap_b32 v173, v175
	s_nop 1
	v_lshlrev_b32_e32 v210, 16, v172
	v_and_b32_e32 v211, 0xffff0000, v172
	v_lshlrev_b32_e32 v212, 16, v173
	v_and_b32_e32 v213, 0xffff0000, v173
	v_pk_fma_f32 v[16:17], v[16:17], v[142:143], v[210:211]
	v_pk_fma_f32 v[18:19], v[18:19], v[144:145], v[212:213]
	v_lshlrev_b32_e32 v214, 16, v174
	v_and_b32_e32 v215, 0xffff0000, v174
	v_lshlrev_b32_e32 v216, 16, v175
	v_and_b32_e32 v217, 0xffff0000, v175
	v_pk_fma_f32 v[8:9], v[8:9], v[138:139], v[214:215]
	v_pk_fma_f32 v[10:11], v[10:11], v[140:141], v[216:217]
	v_mov_b32_e32 v222, 0xb0000
	v_lshl_add_u64 v[192:193], v[162:163], 0, v[222:223]
	global_store_dwordx4 v[192:193], v[16:19], off
	global_store_dwordx4 v[192:193], v[8:11], off offset:64
	s_waitcnt vmcnt(16)
	v_permlane16_swap_b32 v176, v178
	v_permlane16_swap_b32 v177, v179
	s_nop 1
	v_lshlrev_b32_e32 v210, 16, v176
	v_and_b32_e32 v211, 0xffff0000, v176
	v_lshlrev_b32_e32 v212, 16, v177
	v_and_b32_e32 v213, 0xffff0000, v177
	v_pk_fma_f32 v[4:5], v[4:5], v[134:135], v[210:211]
	v_pk_fma_f32 v[6:7], v[6:7], v[136:137], v[212:213]
	v_lshlrev_b32_e32 v214, 16, v178
	v_and_b32_e32 v215, 0xffff0000, v178
	v_lshlrev_b32_e32 v216, 16, v179
	v_and_b32_e32 v217, 0xffff0000, v179
	v_pk_fma_f32 v[0:1], v[0:1], v[130:131], v[214:215]
	v_pk_fma_f32 v[2:3], v[2:3], v[132:133], v[216:217]
	v_mov_b32_e32 v222, 0xb0000
	v_lshl_add_u64 v[192:193], v[162:163], 0, v[222:223]
	global_store_dwordx4 v[192:193], v[4:7], off offset:512
	global_store_dwordx4 v[192:193], v[0:3], off offset:576
	s_mov_b32 s14, 0x30000
	s_mov_b32 s14, 0x80000
	s_mov_b32 s14, 0x90000
	s_mov_b32 s14, 0xa0000
	s_mov_b32 s14, 0xb0000
	s_and_b64 vcc, exec, s[0:1]
	s_mov_b32 s14, s43
	s_cbranch_vccz .LBB0_1418
	s_waitcnt vmcnt(0)
	s_cmpk_gt_u32 s24, 0xff
	s_cbranch_scc1 .LBB0_1425
	s_barrier

.LBB0_1435:
	s_add_u32 s20, s18, 0x100
	s_addc_u32 s21, s19, 0
	s_add_i32 s47, 0, 0x10000
	v_add_u32_e32 v142, s47, v242
	ds_read_b128 v[130:133], v142
	ds_read_b128 v[134:137], v142 offset:1024
	ds_read_b128 v[138:141], v142 offset:2048
	ds_read_b128 v[142:145], v142 offset:3072
	s_cmp_eq_u32 s46, 40
	s_cselect_b32 s25, s13, s21
	s_cselect_b32 s24, s12, s20
	s_cselect_b32 s23, s15, s45
	s_cselect_b32 s22, s14, s44
	v_lshl_add_u64 v[186:187], s[18:19], 0, v[150:151]
	s_add_i32 m0, s31, 0xc000
	ds_read_b128 v[154:157], v244
	ds_read_b128 v[158:161], v244 offset:1024
	ds_read_b128 v[162:165], v244 offset:2048
	ds_read_b128 v[166:169], v244 offset:3072
	ds_read_b128 v[170:173], v244 offset:4096
	ds_read_b128 v[174:177], v244 offset:5120
	ds_read_b128 v[178:181], v244 offset:6144
	ds_read_b128 v[182:185], v244 offset:7168
	global_load_lds_dwordx4 v[186:187], off
	v_lshl_add_u64 v[186:187], s[18:19], 0, v[152:153]
	s_add_i32 m0, s31, 0xe000
	s_nop 0
	global_load_lds_dwordx4 v[186:187], off
	s_waitcnt lgkmcnt(8)
	s_barrier
	s_waitcnt lgkmcnt(0)
	s_setprio 1
	s_waitcnt lgkmcnt(0)
	v_mfma_f32_16x16x32_bf16 v[126:129], v[130:133], v[154:157], v[126:129]
	v_mfma_f32_16x16x32_bf16 v[122:125], v[138:141], v[154:157], v[122:125]
	v_mfma_f32_16x16x32_bf16 v[114:117], v[130:133], v[162:165], v[114:117]
	v_mfma_f32_16x16x32_bf16 v[106:109], v[138:141], v[162:165], v[106:109]
	v_mfma_f32_16x16x32_bf16 v[98:101], v[130:133], v[170:173], v[98:101]
	v_mfma_f32_16x16x32_bf16 v[90:93], v[138:141], v[170:173], v[90:93]
	v_mfma_f32_16x16x32_bf16 v[82:85], v[130:133], v[178:181], v[82:85]
	v_mfma_f32_16x16x32_bf16 v[74:77], v[138:141], v[178:181], v[74:77]
	v_mfma_f32_16x16x32_bf16 v[126:129], v[134:137], v[158:161], v[126:129]
	v_mfma_f32_16x16x32_bf16 v[122:125], v[142:145], v[158:161], v[122:125]
	v_mfma_f32_16x16x32_bf16 v[114:117], v[134:137], v[166:169], v[114:117]
	v_mfma_f32_16x16x32_bf16 v[106:109], v[142:145], v[166:169], v[106:109]
	v_mfma_f32_16x16x32_bf16 v[98:101], v[134:137], v[174:177], v[98:101]
	v_mfma_f32_16x16x32_bf16 v[90:93], v[142:145], v[174:177], v[90:93]
	v_mfma_f32_16x16x32_bf16 v[82:85], v[134:137], v[182:185], v[82:85]
	v_mfma_f32_16x16x32_bf16 v[74:77], v[142:145], v[182:185], v[74:77]
	s_setprio 0
	s_barrier
	s_add_i32 s48, 0, 0x14000
	s_add_i32 s18, s47, s30
	v_add_u32_e32 v202, s48, v242
	v_lshl_add_u64 v[206:207], s[22:23], 0, v[48:49]
	s_mov_b32 m0, s18
	ds_read_b128 v[186:189], v202
	ds_read_b128 v[190:193], v202 offset:1024
	ds_read_b128 v[198:201], v202 offset:2048
	ds_read_b128 v[202:205], v202 offset:3072
	global_load_lds_dwordx4 v[206:207], off
	v_lshl_add_u64 v[208:209], s[22:23], 0, v[146:147]
	s_add_i32 m0, s18, 0x2000
	s_nop 0
	global_load_lds_dwordx4 v[208:209], off
	s_barrier
	s_waitcnt lgkmcnt(0)
	s_setprio 1
	s_waitcnt lgkmcnt(0)
	v_mfma_f32_16x16x32_bf16 v[118:121], v[186:189], v[154:157], v[118:121]
	v_mfma_f32_16x16x32_bf16 v[110:113], v[198:201], v[154:157], v[110:113]
	v_mfma_f32_16x16x32_bf16 v[102:105], v[186:189], v[162:165], v[102:105]
	v_mfma_f32_16x16x32_bf16 v[94:97], v[198:201], v[162:165], v[94:97]
	v_mfma_f32_16x16x32_bf16 v[86:89], v[186:189], v[170:173], v[86:89]
	v_mfma_f32_16x16x32_bf16 v[78:81], v[198:201], v[170:173], v[78:81]
	v_mfma_f32_16x16x32_bf16 v[70:73], v[186:189], v[178:181], v[70:73]
	v_mfma_f32_16x16x32_bf16 v[66:69], v[198:201], v[178:181], v[66:69]
	v_mfma_f32_16x16x32_bf16 v[118:121], v[190:193], v[158:161], v[118:121]
	v_mfma_f32_16x16x32_bf16 v[110:113], v[202:205], v[158:161], v[110:113]
	v_mfma_f32_16x16x32_bf16 v[102:105], v[190:193], v[166:169], v[102:105]
	v_mfma_f32_16x16x32_bf16 v[94:97], v[202:205], v[166:169], v[94:97]
	v_mfma_f32_16x16x32_bf16 v[86:89], v[190:193], v[174:177], v[86:89]
	v_mfma_f32_16x16x32_bf16 v[78:81], v[202:205], v[174:177], v[78:81]
	v_mfma_f32_16x16x32_bf16 v[70:73], v[190:193], v[182:185], v[70:73]
	v_mfma_f32_16x16x32_bf16 v[66:69], v[202:205], v[182:185], v[66:69]
	s_setprio 0
	s_mov_b32 m0, s31
	v_lshl_add_u64 v[210:211], s[24:25], 0, v[48:49]
	s_barrier
	ds_read_b128 v[154:157], v244 offset:16384
	ds_read_b128 v[158:161], v244 offset:17408
	ds_read_b128 v[162:165], v244 offset:18432
	ds_read_b128 v[166:169], v244 offset:19456
	ds_read_b128 v[170:173], v244 offset:20480
	ds_read_b128 v[174:177], v244 offset:21504
	ds_read_b128 v[178:181], v244 offset:22528
	ds_read_b128 v[182:185], v244 offset:23552
	global_load_lds_dwordx4 v[210:211], off
	v_lshl_add_u64 v[212:213], s[24:25], 0, v[146:147]
	s_mov_b32 m0, s34
	s_nop 0
	global_load_lds_dwordx4 v[212:213], off
	s_barrier
	s_waitcnt lgkmcnt(0)
	s_setprio 1
	s_waitcnt lgkmcnt(0)
	v_mfma_f32_16x16x32_bf16 v[62:65], v[130:133], v[154:157], v[62:65]
	v_mfma_f32_16x16x32_bf16 v[58:61], v[138:141], v[154:157], v[58:61]
	v_mfma_f32_16x16x32_bf16 v[50:53], v[130:133], v[162:165], v[50:53]
	v_mfma_f32_16x16x32_bf16 v[40:43], v[138:141], v[162:165], v[40:43]
	v_mfma_f32_16x16x32_bf16 v[32:35], v[130:133], v[170:173], v[32:35]
	v_mfma_f32_16x16x32_bf16 v[24:27], v[138:141], v[170:173], v[24:27]
	v_mfma_f32_16x16x32_bf16 v[16:19], v[130:133], v[178:181], v[16:19]
	v_mfma_f32_16x16x32_bf16 v[8:11], v[138:141], v[178:181], v[8:11]
	v_mfma_f32_16x16x32_bf16 v[62:65], v[134:137], v[158:161], v[62:65]
	v_mfma_f32_16x16x32_bf16 v[58:61], v[142:145], v[158:161], v[58:61]
	v_mfma_f32_16x16x32_bf16 v[50:53], v[134:137], v[166:169], v[50:53]
	v_mfma_f32_16x16x32_bf16 v[40:43], v[142:145], v[166:169], v[40:43]
	v_mfma_f32_16x16x32_bf16 v[32:35], v[134:137], v[174:177], v[32:35]
	v_mfma_f32_16x16x32_bf16 v[24:27], v[142:145], v[174:177], v[24:27]
	v_mfma_f32_16x16x32_bf16 v[16:19], v[134:137], v[182:185], v[16:19]
	v_mfma_f32_16x16x32_bf16 v[8:11], v[142:145], v[182:185], v[8:11]
	s_setprio 0
	s_barrier
	s_add_u32 s18, s22, 0xb0000
	s_addc_u32 s19, s23, 0
	s_add_i32 s47, s48, s30
	v_lshl_add_u64 v[130:131], s[18:19], 0, v[48:49]
	s_mov_b32 m0, s47
	s_nop 0
	global_load_lds_dwordx4 v[130:131], off
	s_add_i32 m0, s47, 0x2000
	s_nop 0
	global_load_lds_dwordx4 v146, s[18:19]
	s_waitcnt vmcnt(6)
	s_barrier
	s_setprio 1
	v_mfma_f32_16x16x32_bf16 v[54:57], v[186:189], v[154:157], v[54:57]
	v_mfma_f32_16x16x32_bf16 v[44:47], v[198:201], v[154:157], v[44:47]
	v_mfma_f32_16x16x32_bf16 v[36:39], v[186:189], v[162:165], v[36:39]
	v_mfma_f32_16x16x32_bf16 v[28:31], v[198:201], v[162:165], v[28:31]
	v_mfma_f32_16x16x32_bf16 v[20:23], v[186:189], v[170:173], v[20:23]
	v_mfma_f32_16x16x32_bf16 v[12:15], v[198:201], v[170:173], v[12:15]
	v_mfma_f32_16x16x32_bf16 v[4:7], v[186:189], v[178:181], v[4:7]
	v_mfma_f32_16x16x32_bf16 v[0:3], v[198:201], v[178:181], v[0:3]
	v_mfma_f32_16x16x32_bf16 v[54:57], v[190:193], v[158:161], v[54:57]
	v_mfma_f32_16x16x32_bf16 v[44:47], v[202:205], v[158:161], v[44:47]
	v_mfma_f32_16x16x32_bf16 v[36:39], v[190:193], v[166:169], v[36:39]
	v_mfma_f32_16x16x32_bf16 v[28:31], v[202:205], v[166:169], v[28:31]
	v_mfma_f32_16x16x32_bf16 v[20:23], v[190:193], v[174:177], v[20:23]
	v_mfma_f32_16x16x32_bf16 v[12:15], v[202:205], v[174:177], v[12:15]
	v_mfma_f32_16x16x32_bf16 v[4:7], v[190:193], v[182:185], v[4:7]
	v_mfma_f32_16x16x32_bf16 v[0:3], v[202:205], v[182:185], v[0:3]
	s_setprio 0
	s_add_i32 s47, 0, 0x18000
	v_add_u32_e32 v142, s47, v242
	s_barrier
	ds_read_b128 v[130:133], v142
	ds_read_b128 v[134:137], v142 offset:1024
	ds_read_b128 v[138:141], v142 offset:2048
	ds_read_b128 v[142:145], v142 offset:3072
	s_add_u32 s18, s24, 0xb0000
	s_addc_u32 s19, s25, 0
	s_mov_b32 m0, s35
	v_lshl_add_u64 v[186:187], s[18:19], 0, v[48:49]
	ds_read_b128 v[154:157], v244 offset:32768
	ds_read_b128 v[158:161], v244 offset:33792
	ds_read_b128 v[162:165], v244 offset:34816
	ds_read_b128 v[166:169], v244 offset:35840
	ds_read_b128 v[170:173], v244 offset:36864
	ds_read_b128 v[174:177], v244 offset:37888
	ds_read_b128 v[178:181], v244 offset:38912
	ds_read_b128 v[182:185], v244 offset:39936
	global_load_lds_dwordx4 v[186:187], off
	s_mov_b32 m0, s36
	s_nop 0
	global_load_lds_dwordx4 v146, s[18:19]
	s_waitcnt lgkmcnt(8)
	s_barrier
	s_waitcnt lgkmcnt(0)
	s_setprio 1
	s_waitcnt lgkmcnt(0)
	v_mfma_f32_16x16x32_bf16 v[126:129], v[130:133], v[154:157], v[126:129]
	v_mfma_f32_16x16x32_bf16 v[122:125], v[138:141], v[154:157], v[122:125]
	v_mfma_f32_16x16x32_bf16 v[114:117], v[130:133], v[162:165], v[114:117]
	v_mfma_f32_16x16x32_bf16 v[106:109], v[138:141], v[162:165], v[106:109]
	v_mfma_f32_16x16x32_bf16 v[98:101], v[130:133], v[170:173], v[98:101]
	v_mfma_f32_16x16x32_bf16 v[90:93], v[138:141], v[170:173], v[90:93]
	v_mfma_f32_16x16x32_bf16 v[82:85], v[130:133], v[178:181], v[82:85]
	v_mfma_f32_16x16x32_bf16 v[74:77], v[138:141], v[178:181], v[74:77]
	v_mfma_f32_16x16x32_bf16 v[126:129], v[134:137], v[158:161], v[126:129]
	v_mfma_f32_16x16x32_bf16 v[122:125], v[142:145], v[158:161], v[122:125]
	v_mfma_f32_16x16x32_bf16 v[114:117], v[134:137], v[166:169], v[114:117]
	v_mfma_f32_16x16x32_bf16 v[106:109], v[142:145], v[166:169], v[106:109]
	v_mfma_f32_16x16x32_bf16 v[98:101], v[134:137], v[174:177], v[98:101]
	v_mfma_f32_16x16x32_bf16 v[90:93], v[142:145], v[174:177], v[90:93]
	v_mfma_f32_16x16x32_bf16 v[82:85], v[134:137], v[182:185], v[82:85]
	v_mfma_f32_16x16x32_bf16 v[74:77], v[142:145], v[182:185], v[74:77]
	s_setprio 0
	s_barrier
	s_add_i32 s24, 0, 0x1c000
	s_add_i32 s18, s47, s30
	v_add_u32_e32 v202, s24, v242
	v_lshl_add_u64 v[206:207], v[206:207], 0, s[66:67]
	s_mov_b32 m0, s18
	ds_read_b128 v[186:189], v202
	ds_read_b128 v[190:193], v202 offset:1024
	ds_read_b128 v[198:201], v202 offset:2048
	ds_read_b128 v[202:205], v202 offset:3072
	global_load_lds_dwordx4 v[206:207], off
	v_lshl_add_u64 v[206:207], v[208:209], 0, s[66:67]
	s_add_i32 m0, s18, 0x2000
	s_nop 0
	global_load_lds_dwordx4 v[206:207], off
	s_barrier
	s_waitcnt lgkmcnt(0)
	s_setprio 1
	s_waitcnt lgkmcnt(0)
	v_mfma_f32_16x16x32_bf16 v[118:121], v[186:189], v[154:157], v[118:121]
	v_mfma_f32_16x16x32_bf16 v[110:113], v[198:201], v[154:157], v[110:113]
	v_mfma_f32_16x16x32_bf16 v[102:105], v[186:189], v[162:165], v[102:105]
	v_mfma_f32_16x16x32_bf16 v[94:97], v[198:201], v[162:165], v[94:97]
	v_mfma_f32_16x16x32_bf16 v[86:89], v[186:189], v[170:173], v[86:89]
	v_mfma_f32_16x16x32_bf16 v[78:81], v[198:201], v[170:173], v[78:81]
	v_mfma_f32_16x16x32_bf16 v[70:73], v[186:189], v[178:181], v[70:73]
	v_mfma_f32_16x16x32_bf16 v[66:69], v[198:201], v[178:181], v[66:69]
	v_mfma_f32_16x16x32_bf16 v[118:121], v[190:193], v[158:161], v[118:121]
	v_mfma_f32_16x16x32_bf16 v[110:113], v[202:205], v[158:161], v[110:113]
	v_mfma_f32_16x16x32_bf16 v[102:105], v[190:193], v[166:169], v[102:105]
	v_mfma_f32_16x16x32_bf16 v[94:97], v[202:205], v[166:169], v[94:97]
	v_mfma_f32_16x16x32_bf16 v[86:89], v[190:193], v[174:177], v[86:89]
	v_mfma_f32_16x16x32_bf16 v[78:81], v[202:205], v[174:177], v[78:81]
	v_mfma_f32_16x16x32_bf16 v[70:73], v[190:193], v[182:185], v[70:73]
	v_mfma_f32_16x16x32_bf16 v[66:69], v[202:205], v[182:185], v[66:69]
	s_setprio 0
	s_mov_b32 m0, s39
	v_lshl_add_u64 v[206:207], v[210:211], 0, s[66:67]
	s_barrier
	ds_read_b128 v[154:157], v244 offset:49152
	ds_read_b128 v[158:161], v244 offset:50176
	ds_read_b128 v[162:165], v244 offset:51200
	ds_read_b128 v[166:169], v244 offset:52224
	ds_read_b128 v[170:173], v244 offset:53248
	ds_read_b128 v[174:177], v244 offset:54272
	ds_read_b128 v[178:181], v244 offset:55296
	ds_read_b128 v[182:185], v244 offset:56320
	global_load_lds_dwordx4 v[206:207], off
	v_lshl_add_u64 v[206:207], v[212:213], 0, s[66:67]
	s_mov_b32 m0, s40
	s_nop 0
	global_load_lds_dwordx4 v[206:207], off
	s_barrier
	s_waitcnt lgkmcnt(0)
	s_setprio 1
	s_waitcnt lgkmcnt(0)
	v_mfma_f32_16x16x32_bf16 v[62:65], v[130:133], v[154:157], v[62:65]
	v_mfma_f32_16x16x32_bf16 v[58:61], v[138:141], v[154:157], v[58:61]
	v_mfma_f32_16x16x32_bf16 v[50:53], v[130:133], v[162:165], v[50:53]
	v_mfma_f32_16x16x32_bf16 v[40:43], v[138:141], v[162:165], v[40:43]
	v_mfma_f32_16x16x32_bf16 v[32:35], v[130:133], v[170:173], v[32:35]
	v_mfma_f32_16x16x32_bf16 v[24:27], v[138:141], v[170:173], v[24:27]
	v_mfma_f32_16x16x32_bf16 v[16:19], v[130:133], v[178:181], v[16:19]
	v_mfma_f32_16x16x32_bf16 v[8:11], v[138:141], v[178:181], v[8:11]
	v_mfma_f32_16x16x32_bf16 v[62:65], v[134:137], v[158:161], v[62:65]
	v_mfma_f32_16x16x32_bf16 v[58:61], v[142:145], v[158:161], v[58:61]
	v_mfma_f32_16x16x32_bf16 v[50:53], v[134:137], v[166:169], v[50:53]
	v_mfma_f32_16x16x32_bf16 v[40:43], v[142:145], v[166:169], v[40:43]
	v_mfma_f32_16x16x32_bf16 v[32:35], v[134:137], v[174:177], v[32:35]
	v_mfma_f32_16x16x32_bf16 v[24:27], v[142:145], v[174:177], v[24:27]
	v_mfma_f32_16x16x32_bf16 v[16:19], v[134:137], v[182:185], v[16:19]
	v_mfma_f32_16x16x32_bf16 v[8:11], v[142:145], v[182:185], v[8:11]
	s_setprio 0
	s_barrier
	s_add_u32 s18, s22, 0xb0080
	s_addc_u32 s19, s23, 0
	s_add_i32 s22, s24, s30
	v_lshl_add_u64 v[130:131], s[18:19], 0, v[48:49]
	s_mov_b32 m0, s22
	s_nop 0
	global_load_lds_dwordx4 v[130:131], off
	s_add_i32 m0, s22, 0x2000
	s_nop 0
	global_load_lds_dwordx4 v146, s[18:19]
	s_waitcnt vmcnt(6)
	s_barrier
	s_setprio 1
	v_mfma_f32_16x16x32_bf16 v[54:57], v[186:189], v[154:157], v[54:57]
	v_mfma_f32_16x16x32_bf16 v[44:47], v[198:201], v[154:157], v[44:47]
	v_mfma_f32_16x16x32_bf16 v[36:39], v[186:189], v[162:165], v[36:39]
	v_mfma_f32_16x16x32_bf16 v[28:31], v[198:201], v[162:165], v[28:31]
	v_mfma_f32_16x16x32_bf16 v[20:23], v[186:189], v[170:173], v[20:23]
	v_mfma_f32_16x16x32_bf16 v[12:15], v[198:201], v[170:173], v[12:15]
	v_mfma_f32_16x16x32_bf16 v[4:7], v[186:189], v[178:181], v[4:7]
	v_mfma_f32_16x16x32_bf16 v[0:3], v[198:201], v[178:181], v[0:3]
	v_mfma_f32_16x16x32_bf16 v[54:57], v[190:193], v[158:161], v[54:57]
	v_mfma_f32_16x16x32_bf16 v[44:47], v[202:205], v[158:161], v[44:47]
	v_mfma_f32_16x16x32_bf16 v[36:39], v[190:193], v[166:169], v[36:39]
	v_mfma_f32_16x16x32_bf16 v[28:31], v[202:205], v[166:169], v[28:31]
	v_mfma_f32_16x16x32_bf16 v[20:23], v[190:193], v[174:177], v[20:23]
	v_mfma_f32_16x16x32_bf16 v[12:15], v[202:205], v[174:177], v[12:15]
	v_mfma_f32_16x16x32_bf16 v[4:7], v[190:193], v[182:185], v[4:7]
	v_mfma_f32_16x16x32_bf16 v[0:3], v[202:205], v[182:185], v[0:3]
	s_setprio 0
	s_add_i32 s46, s46, 2
	s_add_u32 s44, s44, 0x100
	s_addc_u32 s45, s45, 0
	s_cmp_gt_u32 s46, 41
	s_mov_b64 s[18:19], s[20:21]
	s_barrier
	s_cbranch_scc0 .LBB0_1435
	s_mul_hi_i32 s18, s16, 0x38e38e39
	s_lshr_b32 s19, s18, 31
	s_ashr_i32 s18, s18, 1
	s_add_i32 s18, s18, s19
	s_mul_i32 s19, s18, -9
	v_lshl_or_b32 v154, s17, 8, v243
	s_sub_i32 s17, 0, s16
	s_cmp_lg_u32 s19, s17
	s_cselect_b32 s17, s18, 32
	s_mul_hi_i32 s19, s17, 0x6000
	s_mulk_i32 s17, 0x6000
	s_add_u32 s18, s37, s17
	s_addc_u32 s19, s38, s19
	s_ashr_i32 s17, s16, 31
	s_lshl_b64 s[16:17], s[16:17], 18
	v_ashrrev_i32_e32 v155, 31, v154
	v_lshl_add_u64 v[156:157], s[16:17], 0, v[148:149]
	v_lshl_add_u64 v[130:131], v[154:155], 2, s[18:19]
	v_lshl_add_u64 v[154:155], v[156:157], 0, v[154:155]
	v_lshlrev_b64 v[184:185], 1, v[154:155]
	v_lshl_add_u64 v[154:155], s[10:11], 0, v[184:185]
	global_load_dwordx4 v[142:145], v[130:131], off
	global_load_dwordx4 v[138:141], v[130:131], off offset:64
	global_load_dwordx4 v[134:137], v[130:131], off offset:512
	s_nop 0
	global_load_dwordx4 v[130:133], v[130:131], off offset:576
	s_nop 0
	s_mov_b32 s16, 0x40000
	s_nop 0
	s_mov_b32 s17, 0x48000
	s_nop 0
	s_mov_b32 s18, 0x50000
	s_nop 0
	s_mov_b32 s19, 0x58000
	s_nop 0
	v_lshl_add_u64 v[184:185], s[6:7], 0, v[184:185]
	s_nop 0
	s_mov_b64 s[20:21], s[14:15]
	s_nop 0
	v_and_b32_e32 v210, 16, v224
	v_lshrrev_b32_e32 v211, 1, v210
	v_add_u32_e32 v210, v210, v211
	v_mov_b32_e32 v211, 0
	v_mov_b32_e32 v213, 0
	v_lshl_add_u64 v[214:215], v[154:155], 0, v[210:211]
	v_lshl_add_u64 v[216:217], v[184:185], 0, v[210:211]
	v_mov_b32_e32 v212, 0x0
	v_lshl_add_u64 v[218:219], v[214:215], 0, v[212:213]
	global_load_dwordx4 v[164:167], v[218:219], off
	global_load_dwordx4 v[168:171], v[218:219], off offset:256
	v_mov_b32_e32 v212, 0x8000
	v_lshl_add_u64 v[218:219], v[214:215], 0, v[212:213]
	global_load_dwordx4 v[172:175], v[218:219], off
	global_load_dwordx4 v[176:179], v[218:219], off offset:256
	v_mov_b32_e32 v212, 0x10000
	v_lshl_add_u64 v[218:219], v[214:215], 0, v[212:213]
	global_load_dwordx4 v[180:183], v[218:219], off
	global_load_dwordx4 v[198:201], v[218:219], off offset:256
	v_mov_b32_e32 v212, 0x18000
	v_lshl_add_u64 v[218:219], v[214:215], 0, v[212:213]
	global_load_dwordx4 v[202:205], v[218:219], off
	global_load_dwordx4 v[206:209], v[218:219], off offset:256
	s_waitcnt vmcnt(7)
	v_permlane16_swap_b32 v164, v166
	v_permlane16_swap_b32 v165, v167
	s_nop 1
	v_lshlrev_b32_e32 v186, 16, v164
	v_and_b32_e32 v187, 0xffff0000, v164
	v_lshlrev_b32_e32 v188, 16, v165
	v_and_b32_e32 v189, 0xffff0000, v165
	v_pk_fma_f32 v[126:127], v[126:127], v[142:143], v[186:187]
	v_pk_fma_f32 v[128:129], v[128:129], v[144:145], v[188:189]
	v_lshlrev_b32_e32 v190, 16, v166
	v_and_b32_e32 v191, 0xffff0000, v166
	v_lshlrev_b32_e32 v192, 16, v167
	v_and_b32_e32 v193, 0xffff0000, v167
	v_pk_fma_f32 v[122:123], v[122:123], v[138:139], v[190:191]
	v_pk_fma_f32 v[124:125], v[124:125], v[140:141], v[192:193]
	v_cvt_pk_bf16_f32 v126, v126, v127
	v_cvt_pk_bf16_f32 v127, v128, v129
	v_cvt_pk_bf16_f32 v128, v122, v123
	v_cvt_pk_bf16_f32 v129, v124, v125
	s_nop 1
	v_permlane16_swap_b32 v126, v128
	v_permlane16_swap_b32 v127, v129
	v_mov_b32_e32 v212, 0x0
	v_lshl_add_u64 v[220:221], v[216:217], 0, v[212:213]
	global_store_dwordx4 v[220:221], v[126:129], off
	v_mov_b32_e32 v212, 0x40000
	v_lshl_add_u64 v[218:219], v[214:215], 0, v[212:213]
	global_load_dwordx4 v[164:167], v[218:219], off
	s_waitcnt vmcnt(8)
	v_permlane16_swap_b32 v168, v170
	v_permlane16_swap_b32 v169, v171
	s_nop 1
	v_lshlrev_b32_e32 v186, 16, v168
	v_and_b32_e32 v187, 0xffff0000, v168
	v_lshlrev_b32_e32 v188, 16, v169
	v_and_b32_e32 v189, 0xffff0000, v169
	v_pk_fma_f32 v[118:119], v[118:119], v[134:135], v[186:187]
	v_pk_fma_f32 v[120:121], v[120:121], v[136:137], v[188:189]
	v_lshlrev_b32_e32 v190, 16, v170
	v_and_b32_e32 v191, 0xffff0000, v170
	v_lshlrev_b32_e32 v192, 16, v171
	v_and_b32_e32 v193, 0xffff0000, v171
	v_pk_fma_f32 v[110:111], v[110:111], v[130:131], v[190:191]
	v_pk_fma_f32 v[112:113], v[112:113], v[132:133], v[192:193]
	v_cvt_pk_bf16_f32 v118, v118, v119
	v_cvt_pk_bf16_f32 v119, v120, v121
	v_cvt_pk_bf16_f32 v120, v110, v111
	v_cvt_pk_bf16_f32 v121, v112, v113
	s_nop 1
	v_permlane16_swap_b32 v118, v120
	v_permlane16_swap_b32 v119, v121
	v_mov_b32_e32 v212, 0x0
	v_lshl_add_u64 v[220:221], v[216:217], 0, v[212:213]
	global_store_dwordx4 v[220:221], v[118:121], off offset:256
	global_load_dwordx4 v[168:171], v[218:219], off offset:256
	s_waitcnt vmcnt(9)
	v_permlane16_swap_b32 v172, v174
	v_permlane16_swap_b32 v173, v175
	s_nop 1
	v_lshlrev_b32_e32 v186, 16, v172
	v_and_b32_e32 v187, 0xffff0000, v172
	v_lshlrev_b32_e32 v188, 16, v173
	v_and_b32_e32 v189, 0xffff0000, v173
	v_pk_fma_f32 v[114:115], v[114:115], v[142:143], v[186:187]
	v_pk_fma_f32 v[116:117], v[116:117], v[144:145], v[188:189]
	v_lshlrev_b32_e32 v190, 16, v174
	v_and_b32_e32 v191, 0xffff0000, v174
	v_lshlrev_b32_e32 v192, 16, v175
	v_and_b32_e32 v193, 0xffff0000, v175
	v_pk_fma_f32 v[106:107], v[106:107], v[138:139], v[190:191]
	v_pk_fma_f32 v[108:109], v[108:109], v[140:141], v[192:193]
	v_cvt_pk_bf16_f32 v114, v114, v115
	v_cvt_pk_bf16_f32 v115, v116, v117
	v_cvt_pk_bf16_f32 v116, v106, v107
	v_cvt_pk_bf16_f32 v117, v108, v109
	s_nop 1
	v_permlane16_swap_b32 v114, v116
	v_permlane16_swap_b32 v115, v117
	v_mov_b32_e32 v212, 0x8000
	v_lshl_add_u64 v[220:221], v[216:217], 0, v[212:213]
	global_store_dwordx4 v[220:221], v[114:117], off
	v_mov_b32_e32 v212, 0x48000
	v_lshl_add_u64 v[218:219], v[214:215], 0, v[212:213]
	global_load_dwordx4 v[172:175], v[218:219], off
	s_waitcnt vmcnt(10)
	v_permlane16_swap_b32 v176, v178
	v_permlane16_swap_b32 v177, v179
	s_nop 1
	v_lshlrev_b32_e32 v186, 16, v176
	v_and_b32_e32 v187, 0xffff0000, v176
	v_lshlrev_b32_e32 v188, 16, v177
	v_and_b32_e32 v189, 0xffff0000, v177
	v_pk_fma_f32 v[102:103], v[102:103], v[134:135], v[186:187]
	v_pk_fma_f32 v[104:105], v[104:105], v[136:137], v[188:189]
	v_lshlrev_b32_e32 v190, 16, v178
	v_and_b32_e32 v191, 0xffff0000, v178
	v_lshlrev_b32_e32 v192, 16, v179
	v_and_b32_e32 v193, 0xffff0000, v179
	v_pk_fma_f32 v[94:95], v[94:95], v[130:131], v[190:191]
	v_pk_fma_f32 v[96:97], v[96:97], v[132:133], v[192:193]
	v_cvt_pk_bf16_f32 v102, v102, v103
	v_cvt_pk_bf16_f32 v103, v104, v105
	v_cvt_pk_bf16_f32 v104, v94, v95
	v_cvt_pk_bf16_f32 v105, v96, v97
	s_nop 1
	v_permlane16_swap_b32 v102, v104
	v_permlane16_swap_b32 v103, v105
	v_mov_b32_e32 v212, 0x8000
	v_lshl_add_u64 v[220:221], v[216:217], 0, v[212:213]
	global_store_dwordx4 v[220:221], v[102:105], off offset:256
	global_load_dwordx4 v[176:179], v[218:219], off offset:256
	s_waitcnt vmcnt(11)
	v_permlane16_swap_b32 v180, v182
	v_permlane16_swap_b32 v181, v183
	s_nop 1
	v_lshlrev_b32_e32 v186, 16, v180
	v_and_b32_e32 v187, 0xffff0000, v180
	v_lshlrev_b32_e32 v188, 16, v181
	v_and_b32_e32 v189, 0xffff0000, v181
	v_pk_fma_f32 v[98:99], v[98:99], v[142:143], v[186:187]
	v_pk_fma_f32 v[100:101], v[100:101], v[144:145], v[188:189]
	v_lshlrev_b32_e32 v190, 16, v182
	v_and_b32_e32 v191, 0xffff0000, v182
	v_lshlrev_b32_e32 v192, 16, v183
	v_and_b32_e32 v193, 0xffff0000, v183
	v_pk_fma_f32 v[90:91], v[90:91], v[138:139], v[190:191]
	v_pk_fma_f32 v[92:93], v[92:93], v[140:141], v[192:193]
	v_cvt_pk_bf16_f32 v98, v98, v99
	v_cvt_pk_bf16_f32 v99, v100, v101
	v_cvt_pk_bf16_f32 v100, v90, v91
	v_cvt_pk_bf16_f32 v101, v92, v93
	s_nop 1
	v_permlane16_swap_b32 v98, v100
	v_permlane16_swap_b32 v99, v101
	v_mov_b32_e32 v212, 0x10000
	v_lshl_add_u64 v[220:221], v[216:217], 0, v[212:213]
	global_store_dwordx4 v[220:221], v[98:101], off
	v_mov_b32_e32 v212, 0x50000
	v_lshl_add_u64 v[218:219], v[214:215], 0, v[212:213]
	global_load_dwordx4 v[180:183], v[218:219], off
	s_waitcnt vmcnt(12)
	v_permlane16_swap_b32 v198, v200
	v_permlane16_swap_b32 v199, v201
	s_nop 1
	v_lshlrev_b32_e32 v186, 16, v198
	v_and_b32_e32 v187, 0xffff0000, v198
	v_lshlrev_b32_e32 v188, 16, v199
	v_and_b32_e32 v189, 0xffff0000, v199
	v_pk_fma_f32 v[86:87], v[86:87], v[134:135], v[186:187]
	v_pk_fma_f32 v[88:89], v[88:89], v[136:137], v[188:189]
	v_lshlrev_b32_e32 v190, 16, v200
	v_and_b32_e32 v191, 0xffff0000, v200
	v_lshlrev_b32_e32 v192, 16, v201
	v_and_b32_e32 v193, 0xffff0000, v201
	v_pk_fma_f32 v[78:79], v[78:79], v[130:131], v[190:191]
	v_pk_fma_f32 v[80:81], v[80:81], v[132:133], v[192:193]
	v_cvt_pk_bf16_f32 v86, v86, v87
	v_cvt_pk_bf16_f32 v87, v88, v89
	v_cvt_pk_bf16_f32 v88, v78, v79
	v_cvt_pk_bf16_f32 v89, v80, v81
	s_nop 1
	v_permlane16_swap_b32 v86, v88
	v_permlane16_swap_b32 v87, v89
	v_mov_b32_e32 v212, 0x10000
	v_lshl_add_u64 v[220:221], v[216:217], 0, v[212:213]
	global_store_dwordx4 v[220:221], v[86:89], off offset:256
	global_load_dwordx4 v[198:201], v[218:219], off offset:256
	s_waitcnt vmcnt(13)
	v_permlane16_swap_b32 v202, v204
	v_permlane16_swap_b32 v203, v205
	s_nop 1
	v_lshlrev_b32_e32 v186, 16, v202
	v_and_b32_e32 v187, 0xffff0000, v202
	v_lshlrev_b32_e32 v188, 16, v203
	v_and_b32_e32 v189, 0xffff0000, v203
	v_pk_fma_f32 v[82:83], v[82:83], v[142:143], v[186:187]
	v_pk_fma_f32 v[84:85], v[84:85], v[144:145], v[188:189]
	v_lshlrev_b32_e32 v190, 16, v204
	v_and_b32_e32 v191, 0xffff0000, v204
	v_lshlrev_b32_e32 v192, 16, v205
	v_and_b32_e32 v193, 0xffff0000, v205
	v_pk_fma_f32 v[74:75], v[74:75], v[138:139], v[190:191]
	v_pk_fma_f32 v[76:77], v[76:77], v[140:141], v[192:193]
	v_cvt_pk_bf16_f32 v82, v82, v83
	v_cvt_pk_bf16_f32 v83, v84, v85
	v_cvt_pk_bf16_f32 v84, v74, v75
	v_cvt_pk_bf16_f32 v85, v76, v77
	s_nop 1
	v_permlane16_swap_b32 v82, v84
	v_permlane16_swap_b32 v83, v85
	v_mov_b32_e32 v212, 0x18000
	v_lshl_add_u64 v[220:221], v[216:217], 0, v[212:213]
	global_store_dwordx4 v[220:221], v[82:85], off
	v_mov_b32_e32 v212, 0x58000
	v_lshl_add_u64 v[218:219], v[214:215], 0, v[212:213]
	global_load_dwordx4 v[202:205], v[218:219], off
	s_waitcnt vmcnt(14)
	v_permlane16_swap_b32 v206, v208
	v_permlane16_swap_b32 v207, v209
	s_nop 1
	v_lshlrev_b32_e32 v186, 16, v206
	v_and_b32_e32 v187, 0xffff0000, v206
	v_lshlrev_b32_e32 v188, 16, v207
	v_and_b32_e32 v189, 0xffff0000, v207
	v_pk_fma_f32 v[70:71], v[70:71], v[134:135], v[186:187]
	v_pk_fma_f32 v[72:73], v[72:73], v[136:137], v[188:189]
	v_lshlrev_b32_e32 v190, 16, v208
	v_and_b32_e32 v191, 0xffff0000, v208
	v_lshlrev_b32_e32 v192, 16, v209
	v_and_b32_e32 v193, 0xffff0000, v209
	v_pk_fma_f32 v[66:67], v[66:67], v[130:131], v[190:191]
	v_pk_fma_f32 v[68:69], v[68:69], v[132:133], v[192:193]
	v_cvt_pk_bf16_f32 v70, v70, v71
	v_cvt_pk_bf16_f32 v71, v72, v73
	v_cvt_pk_bf16_f32 v72, v66, v67
	v_cvt_pk_bf16_f32 v73, v68, v69
	s_nop 1
	v_permlane16_swap_b32 v70, v72
	v_permlane16_swap_b32 v71, v73
	v_mov_b32_e32 v212, 0x18000
	v_lshl_add_u64 v[220:221], v[216:217], 0, v[212:213]
	global_store_dwordx4 v[220:221], v[70:73], off offset:256
	global_load_dwordx4 v[206:209], v[218:219], off offset:256
	s_waitcnt vmcnt(14)
	v_permlane16_swap_b32 v164, v166
	v_permlane16_swap_b32 v165, v167
	s_nop 1
	v_lshlrev_b32_e32 v186, 16, v164
	v_and_b32_e32 v187, 0xffff0000, v164
	v_lshlrev_b32_e32 v188, 16, v165
	v_and_b32_e32 v189, 0xffff0000, v165
	v_pk_fma_f32 v[62:63], v[62:63], v[142:143], v[186:187]
	v_pk_fma_f32 v[64:65], v[64:65], v[144:145], v[188:189]
	v_lshlrev_b32_e32 v190, 16, v166
	v_and_b32_e32 v191, 0xffff0000, v166
	v_lshlrev_b32_e32 v192, 16, v167
	v_and_b32_e32 v193, 0xffff0000, v167
	v_pk_fma_f32 v[58:59], v[58:59], v[138:139], v[190:191]
	v_pk_fma_f32 v[60:61], v[60:61], v[140:141], v[192:193]
	v_cvt_pk_bf16_f32 v62, v62, v63
	v_cvt_pk_bf16_f32 v63, v64, v65
	v_cvt_pk_bf16_f32 v64, v58, v59
	v_cvt_pk_bf16_f32 v65, v60, v61
	s_nop 1
	v_permlane16_swap_b32 v62, v64
	v_permlane16_swap_b32 v63, v65
	v_mov_b32_e32 v212, 0x40000
	v_lshl_add_u64 v[220:221], v[216:217], 0, v[212:213]
	global_store_dwordx4 v[220:221], v[62:65], off
	s_waitcnt vmcnt(13)
	v_permlane16_swap_b32 v168, v170
	v_permlane16_swap_b32 v169, v171
	s_nop 1
	v_lshlrev_b32_e32 v186, 16, v168
	v_and_b32_e32 v187, 0xffff0000, v168
	v_lshlrev_b32_e32 v188, 16, v169
	v_and_b32_e32 v189, 0xffff0000, v169
	v_pk_fma_f32 v[54:55], v[54:55], v[134:135], v[186:187]
	v_pk_fma_f32 v[56:57], v[56:57], v[136:137], v[188:189]
	v_lshlrev_b32_e32 v190, 16, v170
	v_and_b32_e32 v191, 0xffff0000, v170
	v_lshlrev_b32_e32 v192, 16, v171
	v_and_b32_e32 v193, 0xffff0000, v171
	v_pk_fma_f32 v[44:45], v[44:45], v[130:131], v[190:191]
	v_pk_fma_f32 v[46:47], v[46:47], v[132:133], v[192:193]
	v_cvt_pk_bf16_f32 v54, v54, v55
	v_cvt_pk_bf16_f32 v55, v56, v57
	v_cvt_pk_bf16_f32 v56, v44, v45
	v_cvt_pk_bf16_f32 v57, v46, v47
	s_nop 1
	v_permlane16_swap_b32 v54, v56
	v_permlane16_swap_b32 v55, v57
	v_mov_b32_e32 v212, 0x40000
	v_lshl_add_u64 v[220:221], v[216:217], 0, v[212:213]
	global_store_dwordx4 v[220:221], v[54:57], off offset:256
	s_waitcnt vmcnt(12)
	v_permlane16_swap_b32 v172, v174
	v_permlane16_swap_b32 v173, v175
	s_nop 1
	v_lshlrev_b32_e32 v186, 16, v172
	v_and_b32_e32 v187, 0xffff0000, v172
	v_lshlrev_b32_e32 v188, 16, v173
	v_and_b32_e32 v189, 0xffff0000, v173
	v_pk_fma_f32 v[50:51], v[50:51], v[142:143], v[186:187]
	v_pk_fma_f32 v[52:53], v[52:53], v[144:145], v[188:189]
	v_lshlrev_b32_e32 v190, 16, v174
	v_and_b32_e32 v191, 0xffff0000, v174
	v_lshlrev_b32_e32 v192, 16, v175
	v_and_b32_e32 v193, 0xffff0000, v175
	v_pk_fma_f32 v[40:41], v[40:41], v[138:139], v[190:191]
	v_pk_fma_f32 v[42:43], v[42:43], v[140:141], v[192:193]
	v_cvt_pk_bf16_f32 v50, v50, v51
	v_cvt_pk_bf16_f32 v51, v52, v53
	v_cvt_pk_bf16_f32 v52, v40, v41
	v_cvt_pk_bf16_f32 v53, v42, v43
	s_nop 1
	v_permlane16_swap_b32 v50, v52
	v_permlane16_swap_b32 v51, v53
	v_mov_b32_e32 v212, 0x48000
	v_lshl_add_u64 v[220:221], v[216:217], 0, v[212:213]
	global_store_dwordx4 v[220:221], v[50:53], off
	s_waitcnt vmcnt(11)
	v_permlane16_swap_b32 v176, v178
	v_permlane16_swap_b32 v177, v179
	s_nop 1
	v_lshlrev_b32_e32 v186, 16, v176
	v_and_b32_e32 v187, 0xffff0000, v176
	v_lshlrev_b32_e32 v188, 16, v177
	v_and_b32_e32 v189, 0xffff0000, v177
	v_pk_fma_f32 v[36:37], v[36:37], v[134:135], v[186:187]
	v_pk_fma_f32 v[38:39], v[38:39], v[136:137], v[188:189]
	v_lshlrev_b32_e32 v190, 16, v178
	v_and_b32_e32 v191, 0xffff0000, v178
	v_lshlrev_b32_e32 v192, 16, v179
	v_and_b32_e32 v193, 0xffff0000, v179
	v_pk_fma_f32 v[28:29], v[28:29], v[130:131], v[190:191]
	v_pk_fma_f32 v[30:31], v[30:31], v[132:133], v[192:193]
	v_cvt_pk_bf16_f32 v36, v36, v37
	v_cvt_pk_bf16_f32 v37, v38, v39
	v_cvt_pk_bf16_f32 v38, v28, v29
	v_cvt_pk_bf16_f32 v39, v30, v31
	s_nop 1
	v_permlane16_swap_b32 v36, v38
	v_permlane16_swap_b32 v37, v39
	v_mov_b32_e32 v212, 0x48000
	v_lshl_add_u64 v[220:221], v[216:217], 0, v[212:213]
	global_store_dwordx4 v[220:221], v[36:39], off offset:256
	s_waitcnt vmcnt(10)
	v_permlane16_swap_b32 v180, v182
	v_permlane16_swap_b32 v181, v183
	s_nop 1
	v_lshlrev_b32_e32 v186, 16, v180
	v_and_b32_e32 v187, 0xffff0000, v180
	v_lshlrev_b32_e32 v188, 16, v181
	v_and_b32_e32 v189, 0xffff0000, v181
	v_pk_fma_f32 v[32:33], v[32:33], v[142:143], v[186:187]
	v_pk_fma_f32 v[34:35], v[34:35], v[144:145], v[188:189]
	v_lshlrev_b32_e32 v190, 16, v182
	v_and_b32_e32 v191, 0xffff0000, v182
	v_lshlrev_b32_e32 v192, 16, v183
	v_and_b32_e32 v193, 0xffff0000, v183
	v_pk_fma_f32 v[24:25], v[24:25], v[138:139], v[190:191]
	v_pk_fma_f32 v[26:27], v[26:27], v[140:141], v[192:193]
	v_cvt_pk_bf16_f32 v32, v32, v33
	v_cvt_pk_bf16_f32 v33, v34, v35
	v_cvt_pk_bf16_f32 v34, v24, v25
	v_cvt_pk_bf16_f32 v35, v26, v27
	s_nop 1
	v_permlane16_swap_b32 v32, v34
	v_permlane16_swap_b32 v33, v35
	v_mov_b32_e32 v212, 0x50000
	v_lshl_add_u64 v[220:221], v[216:217], 0, v[212:213]
	global_store_dwordx4 v[220:221], v[32:35], off
	s_waitcnt vmcnt(9)
	v_permlane16_swap_b32 v198, v200
	v_permlane16_swap_b32 v199, v201
	s_nop 1
	v_lshlrev_b32_e32 v186, 16, v198
	v_and_b32_e32 v187, 0xffff0000, v198
	v_lshlrev_b32_e32 v188, 16, v199
	v_and_b32_e32 v189, 0xffff0000, v199
	v_pk_fma_f32 v[20:21], v[20:21], v[134:135], v[186:187]
	v_pk_fma_f32 v[22:23], v[22:23], v[136:137], v[188:189]
	v_lshlrev_b32_e32 v190, 16, v200
	v_and_b32_e32 v191, 0xffff0000, v200
	v_lshlrev_b32_e32 v192, 16, v201
	v_and_b32_e32 v193, 0xffff0000, v201
	v_pk_fma_f32 v[12:13], v[12:13], v[130:131], v[190:191]
	v_pk_fma_f32 v[14:15], v[14:15], v[132:133], v[192:193]
	v_cvt_pk_bf16_f32 v20, v20, v21
	v_cvt_pk_bf16_f32 v21, v22, v23
	v_cvt_pk_bf16_f32 v22, v12, v13
	v_cvt_pk_bf16_f32 v23, v14, v15
	s_nop 1
	v_permlane16_swap_b32 v20, v22
	v_permlane16_swap_b32 v21, v23
	v_mov_b32_e32 v212, 0x50000
	v_lshl_add_u64 v[220:221], v[216:217], 0, v[212:213]
	global_store_dwordx4 v[220:221], v[20:23], off offset:256
	s_waitcnt vmcnt(8)
	v_permlane16_swap_b32 v202, v204
	v_permlane16_swap_b32 v203, v205
	s_nop 1
	v_lshlrev_b32_e32 v186, 16, v202
	v_and_b32_e32 v187, 0xffff0000, v202
	v_lshlrev_b32_e32 v188, 16, v203
	v_and_b32_e32 v189, 0xffff0000, v203
	v_pk_fma_f32 v[16:17], v[16:17], v[142:143], v[186:187]
	v_pk_fma_f32 v[18:19], v[18:19], v[144:145], v[188:189]
	v_lshlrev_b32_e32 v190, 16, v204
	v_and_b32_e32 v191, 0xffff0000, v204
	v_lshlrev_b32_e32 v192, 16, v205
	v_and_b32_e32 v193, 0xffff0000, v205
	v_pk_fma_f32 v[8:9], v[8:9], v[138:139], v[190:191]
	v_pk_fma_f32 v[10:11], v[10:11], v[140:141], v[192:193]
	v_cvt_pk_bf16_f32 v16, v16, v17
	v_cvt_pk_bf16_f32 v17, v18, v19
	v_cvt_pk_bf16_f32 v18, v8, v9
	v_cvt_pk_bf16_f32 v19, v10, v11
	s_nop 1
	v_permlane16_swap_b32 v16, v18
	v_permlane16_swap_b32 v17, v19
	v_mov_b32_e32 v212, 0x58000
	v_lshl_add_u64 v[220:221], v[216:217], 0, v[212:213]
	global_store_dwordx4 v[220:221], v[16:19], off
	s_waitcnt vmcnt(7)
	v_permlane16_swap_b32 v206, v208
	v_permlane16_swap_b32 v207, v209
	s_nop 1
	v_lshlrev_b32_e32 v186, 16, v206
	v_and_b32_e32 v187, 0xffff0000, v206
	v_lshlrev_b32_e32 v188, 16, v207
	v_and_b32_e32 v189, 0xffff0000, v207
	v_pk_fma_f32 v[4:5], v[4:5], v[134:135], v[186:187]
	v_pk_fma_f32 v[6:7], v[6:7], v[136:137], v[188:189]
	v_lshlrev_b32_e32 v190, 16, v208
	v_and_b32_e32 v191, 0xffff0000, v208
	v_lshlrev_b32_e32 v192, 16, v209
	v_and_b32_e32 v193, 0xffff0000, v209
	v_pk_fma_f32 v[0:1], v[0:1], v[130:131], v[190:191]
	v_pk_fma_f32 v[2:3], v[2:3], v[132:133], v[192:193]
	v_cvt_pk_bf16_f32 v4, v4, v5
	v_cvt_pk_bf16_f32 v5, v6, v7
	v_cvt_pk_bf16_f32 v6, v0, v1
	v_cvt_pk_bf16_f32 v7, v2, v3
	s_nop 1
	v_permlane16_swap_b32 v4, v6
	v_permlane16_swap_b32 v5, v7
	v_mov_b32_e32 v212, 0x58000
	v_lshl_add_u64 v[220:221], v[216:217], 0, v[212:213]
	global_store_dwordx4 v[220:221], v[4:7], off offset:256
	s_mov_b32 s16, s43
	s_mov_b32 s17, s42
	s_and_b64 vcc, exec, s[0:1]
	s_mov_b64 s[18:19], s[12:13]
	s_cbranch_vccz .LBB0_1432
	s_waitcnt vmcnt(0)
	s_cmpk_gt_u32 s29, 0xff
	s_cbranch_scc1 .LBB0_1439
	s_barrier
